# v37 plus epilogue de-serialisation: the 8 per-row-group rss loads of the SwiGLU (P1,P8) and in-projection (P3) epilogues hoisted, counted vmcnt(7) waits
# speedup vs baseline: 1.0085x; 1.0028x over previous
; __device__ __forceinline__ unsigned cvt_pk_bf16(float lo, float hi) { unsigned r; asm volatile("v_cvt_pk_bf16_f32 %0, %1, %2" : "=v"(r) : "v"(lo), "v"(hi)); return r; }
; __device__ __forceinline__ float silu_f(float x) { return x * sigmoid_f(x); }
;     __device__ __forceinline__ void operator()(const f32x4 (&acc)[2][2][4][2], const Unit& u, int wr, int wc, int fr, int fq) const {
;         const int row0 = u.pm * BM + wr * 64 + fr, col0 = u.pn * 128 + wc * 32 + 8 * fq;
; #pragma unroll
;         for (int ai = 0; ai < 2; ++ai)
; #pragma unroll
;             for (int m = 0; m < 4; ++m) {
;                 const int row = row0 + ai * HALF + m * 16;
;                 const float r = __builtin_amdgcn_rsqf(rss[row] * (1.f / 1024.f) + NEPS);
;                 float o[8];
; #pragma unroll
;                 for (int n = 0; n < 2; ++n)
; #pragma unroll
;                     for (int e = 0; e < 4; ++e) o[4 * n + e] = silu_f(acc[ai][0][m][n][e] * r) * (acc[ai][1][m][n][e] * r);
;                 u32x4 w; w.x = cvt_pk_bf16(o[0], o[1]); w.y = cvt_pk_bf16(o[2], o[3]); w.z = cvt_pk_bf16(o[4], o[5]); w.w = cvt_pk_bf16(o[6], o[7]);
;                 *(u32x4*)(O + (size_t)row * 2816 + col0) = w;
.LBB0_134:
	v_lshl_add_u32 v140, s48, 8, v144
	v_ashrrev_i32_e32 v141, 31, v140
	v_lshl_add_u64 v[142:143], v[140:141], 2, s[4:5]
	global_load_dword v200, v[142:143], off
	global_load_dword v201, v[142:143], off offset:64
	global_load_dword v202, v[142:143], off offset:128
	global_load_dword v203, v[142:143], off offset:192
	global_load_dword v204, v[142:143], off offset:512
	global_load_dword v205, v[142:143], off offset:576
	global_load_dword v206, v[142:143], off offset:640
	global_load_dword v207, v[142:143], off offset:704
	v_lshl_or_b32 v152, s49, 7, v146
	v_ashrrev_i32_e32 v153, 31, v152
	v_mov_b32_e32 v156, v120
	v_mov_b32_e32 v157, v116
	v_mov_b32_e32 v116, v121
	v_lshlrev_b64 v[120:121], 1, v[152:153]
	v_mov_b32_e32 v154, v126
	v_mov_b32_e32 v155, v122
	v_mov_b32_e32 v122, v127
	v_mov_b32_e32 v126, v128
	v_mov_b32_e32 v127, v124
	v_mov_b32_e32 v124, v129
	v_mov_b32_e32 v128, v118
	v_mov_b32_e32 v129, v114
	v_mov_b32_e32 v114, v119
	v_or_b32_e32 v160, 16, v140
	v_ashrrev_i32_e32 v161, 31, v160
	v_lshl_add_u64 v[164:165], v[160:161], 2, s[4:5]
	v_mov_b64_e32 v[118:119], s[60:61]
	v_mad_i64_i32 v[158:159], s[24:25], v140, s47, v[118:119]
	v_lshl_add_u64 v[158:159], v[158:159], 0, v[120:121]
	s_andn2_b64 vcc, exec, s[6:7]
	s_mov_b64 s[6:7], -1
	s_waitcnt vmcnt(0)
	v_mov_b32_e32 v141, v200
	v_fmamk_f32 v141, v141, 0x3a800000, v150
	v_rsq_f32_e32 v152, v141
	s_nop 0
	v_pk_mul_f32 v[116:117], v[116:117], v[152:153] op_sel_hi:[1,0]
	v_pk_mul_f32 v[154:155], v[154:155], v[152:153] op_sel_hi:[1,0]
	v_pk_mul_f32 v[122:123], v[122:123], v[152:153] op_sel_hi:[1,0]
	v_pk_mul_f32 v[126:127], v[126:127], v[152:153] op_sel_hi:[1,0]
	v_pk_mul_f32 v[124:125], v[124:125], v[152:153] op_sel_hi:[1,0]
	v_pk_mul_f32 v[128:129], v[128:129], v[152:153] op_sel_hi:[1,0]
	v_pk_mul_f32 v[114:115], v[114:115], v[152:153] op_sel_hi:[1,0]
	v_pk_mul_f32 v[156:157], v[156:157], v[152:153] op_sel_hi:[1,0]
	v_mul_f32_e32 v167, 0xbfb8aa3b, v117
	v_mul_f32_e32 v141, 0xbfb8aa3b, v155
	v_mul_f32_e32 v151, 0xbfb8aa3b, v123
	v_mul_f32_e32 v152, 0xbfb8aa3b, v127
	v_mul_f32_e32 v153, 0xbfb8aa3b, v125
	v_mul_f32_e32 v161, 0xbfb8aa3b, v129
	v_mul_f32_e32 v163, 0xbfb8aa3b, v115
	v_mul_f32_e32 v166, 0xbfb8aa3b, v157
	v_exp_f32_e32 v167, v167
	v_exp_f32_e32 v141, v141
	v_exp_f32_e32 v151, v151
	v_exp_f32_e32 v152, v152
	v_exp_f32_e32 v153, v153
	v_exp_f32_e32 v161, v161
	v_exp_f32_e32 v163, v163
	v_exp_f32_e32 v166, v166
	v_add_f32_e32 v167, 1.0, v167
	v_add_f32_e32 v141, 1.0, v141
	v_add_f32_e32 v151, 1.0, v151
	v_add_f32_e32 v152, 1.0, v152
	v_add_f32_e32 v153, 1.0, v153
	v_add_f32_e32 v161, 1.0, v161
	v_add_f32_e32 v163, 1.0, v163
	v_add_f32_e32 v166, 1.0, v166
	v_rcp_f32_e32 v167, v167
	v_rcp_f32_e32 v141, v141
	v_rcp_f32_e32 v151, v151
	v_rcp_f32_e32 v152, v152
	v_rcp_f32_e32 v153, v153
	v_rcp_f32_e32 v161, v161
	v_rcp_f32_e32 v163, v163
	v_rcp_f32_e32 v166, v166
	v_mul_f32_e32 v117, v117, v167
	v_mul_f32_e32 v141, v155, v141
	v_mul_f32_e32 v123, v123, v151
	v_mul_f32_e32 v127, v127, v152
	v_mul_f32_e32 v125, v125, v153
	v_mul_f32_e32 v129, v129, v161
	v_mul_f32_e32 v115, v115, v163
	v_mul_f32_e32 v151, v157, v166
	v_mul_f32_e32 v117, v116, v117
	v_mul_f32_e32 v141, v154, v141
	v_mul_f32_e32 v122, v122, v123
	v_mul_f32_e32 v123, v126, v127
	v_mul_f32_e32 v124, v124, v125
	v_mul_f32_e32 v125, v128, v129
	v_mul_f32_e32 v126, v114, v115
	v_mul_f32_e32 v127, v156, v151
	v_cvt_pk_bf16_f32 v114, v141, v122
	v_cvt_pk_bf16_f32 v115, v123, v124
	v_cvt_pk_bf16_f32 v116, v125, v126
	v_cvt_pk_bf16_f32 v117, v127, v117
	global_store_dwordx4 v[158:159], v[114:117], off
	s_nop 0
	s_nop 0
	v_mov_b32_e32 v115, v106
	v_mov_b32_e32 v106, v111
	v_mov_b32_e32 v111, v108
	v_mov_b32_e32 v108, v113
	v_mov_b32_e32 v113, v98
	v_mov_b32_e32 v98, v103
	v_mov_b32_e32 v103, v100
	v_mov_b32_e32 v100, v105
	v_mov_b32_e32 v114, v110
	v_mov_b32_e32 v110, v112
	v_mov_b32_e32 v112, v102
	v_mov_b32_e32 v102, v104
	v_or_b32_e32 v104, 32, v140
	v_mad_i64_i32 v[116:117], s[24:25], v160, s47, v[118:119]
	v_lshl_add_u64 v[116:117], v[116:117], 0, v[120:121]
	s_waitcnt vmcnt(7)
	v_mov_b32_e32 v122, v201
	v_fmamk_f32 v105, v122, 0x3a800000, v150
	v_rsq_f32_e32 v122, v105
	v_ashrrev_i32_e32 v105, 31, v104
	v_lshl_add_u64 v[124:125], v[104:105], 2, s[4:5]
	v_pk_mul_f32 v[100:101], v[100:101], v[122:123] op_sel_hi:[1,0]
	v_pk_mul_f32 v[114:115], v[114:115], v[122:123] op_sel_hi:[1,0]
	v_pk_mul_f32 v[106:107], v[106:107], v[122:123] op_sel_hi:[1,0]
	v_pk_mul_f32 v[110:111], v[110:111], v[122:123] op_sel_hi:[1,0]
	v_pk_mul_f32 v[108:109], v[108:109], v[122:123] op_sel_hi:[1,0]
	v_pk_mul_f32 v[112:113], v[112:113], v[122:123] op_sel_hi:[1,0]
	v_pk_mul_f32 v[98:99], v[98:99], v[122:123] op_sel_hi:[1,0]
	v_pk_mul_f32 v[102:103], v[102:103], v[122:123] op_sel_hi:[1,0]
	v_mul_f32_e32 v141, 0xbfb8aa3b, v101
	v_mul_f32_e32 v105, 0xbfb8aa3b, v115
	v_mul_f32_e32 v122, 0xbfb8aa3b, v107
	v_mul_f32_e32 v123, 0xbfb8aa3b, v111
	v_mul_f32_e32 v126, 0xbfb8aa3b, v109
	v_mul_f32_e32 v127, 0xbfb8aa3b, v113
	v_mul_f32_e32 v128, 0xbfb8aa3b, v99
	v_mul_f32_e32 v129, 0xbfb8aa3b, v103
	v_exp_f32_e32 v141, v141
	v_exp_f32_e32 v105, v105
	v_exp_f32_e32 v122, v122
	v_exp_f32_e32 v123, v123
	v_exp_f32_e32 v126, v126
	v_exp_f32_e32 v127, v127
	v_exp_f32_e32 v128, v128
	v_exp_f32_e32 v129, v129
	v_add_f32_e32 v141, 1.0, v141
	v_add_f32_e32 v105, 1.0, v105
	v_add_f32_e32 v122, 1.0, v122
	v_add_f32_e32 v123, 1.0, v123
	v_add_f32_e32 v126, 1.0, v126
	v_add_f32_e32 v127, 1.0, v127
	v_add_f32_e32 v128, 1.0, v128
	v_add_f32_e32 v129, 1.0, v129
	v_rcp_f32_e32 v141, v141
	v_rcp_f32_e32 v105, v105
	v_rcp_f32_e32 v122, v122
	v_rcp_f32_e32 v123, v123
	v_rcp_f32_e32 v126, v126
	v_rcp_f32_e32 v127, v127
	v_rcp_f32_e32 v128, v128
	v_rcp_f32_e32 v129, v129
	v_mul_f32_e32 v101, v101, v141
	v_mul_f32_e32 v105, v115, v105
	v_mul_f32_e32 v107, v107, v122
	v_mul_f32_e32 v111, v111, v123
	v_mul_f32_e32 v109, v109, v126
	v_mul_f32_e32 v113, v113, v127
	v_mul_f32_e32 v99, v99, v128
	v_mul_f32_e32 v103, v103, v129
	v_mul_f32_e32 v101, v100, v101
	v_mul_f32_e32 v105, v114, v105
	v_mul_f32_e32 v106, v106, v107
	v_mul_f32_e32 v107, v110, v111
	v_mul_f32_e32 v108, v108, v109
	v_mul_f32_e32 v109, v112, v113
	v_mul_f32_e32 v110, v98, v99
	v_mul_f32_e32 v102, v102, v103
	v_cvt_pk_bf16_f32 v98, v105, v106
	v_cvt_pk_bf16_f32 v99, v107, v108
	v_cvt_pk_bf16_f32 v100, v109, v110
	v_cvt_pk_bf16_f32 v101, v102, v101
	global_store_dwordx4 v[116:117], v[98:101], off
	s_nop 0
	s_nop 0
	v_mov_b32_e32 v99, v90
	v_mov_b32_e32 v90, v95
	v_mov_b32_e32 v95, v92
	v_mov_b32_e32 v92, v97
	v_mov_b32_e32 v97, v82
	v_mov_b32_e32 v82, v87
	v_mov_b32_e32 v87, v84
	v_mov_b32_e32 v84, v89
	v_mov_b32_e32 v98, v94
	v_mov_b32_e32 v94, v96
	v_mov_b32_e32 v96, v86
	v_mov_b32_e32 v86, v88
	v_or_b32_e32 v88, 48, v140
	v_mad_i64_i32 v[100:101], s[24:25], v104, s47, v[118:119]
	v_lshl_add_u64 v[100:101], v[100:101], 0, v[120:121]
	s_waitcnt vmcnt(7)
; __device__ __forceinline__ unsigned cvt_pk_bf16(float lo, float hi) { unsigned r; asm volatile("v_cvt_pk_bf16_f32 %0, %1, %2" : "=v"(r) : "v"(lo), "v"(hi)); return r; }
; __device__ __forceinline__ float silu_f(float x) { return x * sigmoid_f(x); }
;     __device__ __forceinline__ void operator()(const f32x4 (&acc)[2][2][4][2], const Unit& u, int wr, int wc, int fr, int fq) const {
;         const int row0 = u.pm * BM + wr * 64 + fr, col0 = u.pn * 128 + wc * 32 + 8 * fq;
; #pragma unroll
;         for (int ai = 0; ai < 2; ++ai)
; #pragma unroll
;             for (int m = 0; m < 4; ++m) {
;                 const int row = row0 + ai * HALF + m * 16;
;                 const float r = __builtin_amdgcn_rsqf(rss[row] * (1.f / 1024.f) + NEPS);
;                 float o[8];
; #pragma unroll
;                 for (int n = 0; n < 2; ++n)
; #pragma unroll
;                     for (int e = 0; e < 4; ++e) o[4 * n + e] = silu_f(acc[ai][0][m][n][e] * r) * (acc[ai][1][m][n][e] * r);
;                 u32x4 w; w.x = cvt_pk_bf16(o[0], o[1]); w.y = cvt_pk_bf16(o[2], o[3]); w.z = cvt_pk_bf16(o[4], o[5]); w.w = cvt_pk_bf16(o[6], o[7]);
;                 *(u32x4*)(O + (size_t)row * 2816 + col0) = w;
	v_mov_b32_e32 v102, v202
	v_fmamk_f32 v89, v102, 0x3a800000, v150
	v_rsq_f32_e32 v102, v89
	v_ashrrev_i32_e32 v89, 31, v88
	v_lshl_add_u64 v[104:105], v[88:89], 2, s[4:5]
	v_pk_mul_f32 v[84:85], v[84:85], v[102:103] op_sel_hi:[1,0]
	v_pk_mul_f32 v[98:99], v[98:99], v[102:103] op_sel_hi:[1,0]
	v_pk_mul_f32 v[90:91], v[90:91], v[102:103] op_sel_hi:[1,0]
	v_pk_mul_f32 v[94:95], v[94:95], v[102:103] op_sel_hi:[1,0]
	v_pk_mul_f32 v[92:93], v[92:93], v[102:103] op_sel_hi:[1,0]
	v_pk_mul_f32 v[96:97], v[96:97], v[102:103] op_sel_hi:[1,0]
	v_pk_mul_f32 v[82:83], v[82:83], v[102:103] op_sel_hi:[1,0]
	v_pk_mul_f32 v[86:87], v[86:87], v[102:103] op_sel_hi:[1,0]
	v_mul_f32_e32 v110, 0xbfb8aa3b, v85
	v_mul_f32_e32 v89, 0xbfb8aa3b, v99
	v_mul_f32_e32 v102, 0xbfb8aa3b, v91
	v_mul_f32_e32 v103, 0xbfb8aa3b, v95
	v_mul_f32_e32 v106, 0xbfb8aa3b, v93
	v_mul_f32_e32 v107, 0xbfb8aa3b, v97
	v_mul_f32_e32 v108, 0xbfb8aa3b, v83
	v_mul_f32_e32 v109, 0xbfb8aa3b, v87
	v_exp_f32_e32 v110, v110
	v_exp_f32_e32 v89, v89
	v_exp_f32_e32 v102, v102
	v_exp_f32_e32 v103, v103
	v_exp_f32_e32 v106, v106
	v_exp_f32_e32 v107, v107
	v_exp_f32_e32 v108, v108
	v_exp_f32_e32 v109, v109
	v_add_f32_e32 v110, 1.0, v110
	v_add_f32_e32 v89, 1.0, v89
	v_add_f32_e32 v102, 1.0, v102
	v_add_f32_e32 v103, 1.0, v103
	v_add_f32_e32 v106, 1.0, v106
	v_add_f32_e32 v107, 1.0, v107
	v_add_f32_e32 v108, 1.0, v108
	v_add_f32_e32 v109, 1.0, v109
	v_rcp_f32_e32 v110, v110
	v_rcp_f32_e32 v89, v89
	v_rcp_f32_e32 v102, v102
	v_rcp_f32_e32 v103, v103
	v_rcp_f32_e32 v106, v106
	v_rcp_f32_e32 v107, v107
	v_rcp_f32_e32 v108, v108
	v_rcp_f32_e32 v109, v109
	v_mul_f32_e32 v85, v85, v110
	v_mul_f32_e32 v89, v99, v89
	v_mul_f32_e32 v91, v91, v102
	v_mul_f32_e32 v95, v95, v103
	v_mul_f32_e32 v93, v93, v106
	v_mul_f32_e32 v97, v97, v107
	v_mul_f32_e32 v83, v83, v108
	v_mul_f32_e32 v87, v87, v109
	v_mul_f32_e32 v85, v84, v85
	v_mul_f32_e32 v89, v98, v89
	v_mul_f32_e32 v90, v90, v91
	v_mul_f32_e32 v91, v94, v95
	v_mul_f32_e32 v92, v92, v93
	v_mul_f32_e32 v93, v96, v97
	v_mul_f32_e32 v94, v82, v83
	v_mul_f32_e32 v86, v86, v87
	v_cvt_pk_bf16_f32 v82, v89, v90
	v_cvt_pk_bf16_f32 v83, v91, v92
	v_cvt_pk_bf16_f32 v84, v93, v94
	v_cvt_pk_bf16_f32 v85, v86, v85
	global_store_dwordx4 v[100:101], v[82:85], off
	s_nop 0
	s_nop 0
	v_mov_b32_e32 v82, v78
	v_mov_b32_e32 v78, v80
	v_mov_b32_e32 v80, v66
	v_mov_b32_e32 v66, v68
	v_mov_b32_e32 v83, v74
	v_mov_b32_e32 v74, v79
	v_mov_b32_e32 v79, v76
	v_mov_b32_e32 v76, v81
	v_mov_b32_e32 v81, v70
	v_mov_b32_e32 v70, v67
	v_mov_b32_e32 v67, v72
	v_mov_b32_e32 v72, v69
	s_waitcnt vmcnt(7)
	v_mov_b32_e32 v84, v203
	v_fmamk_f32 v68, v84, 0x3a800000, v150
	v_rsq_f32_e32 v68, v68
	v_mad_i64_i32 v[84:85], s[24:25], v88, s47, v[118:119]
	v_lshl_add_u64 v[84:85], v[84:85], 0, v[120:121]
	v_pk_mul_f32 v[82:83], v[82:83], v[68:69] op_sel_hi:[1,0]
	v_pk_mul_f32 v[74:75], v[74:75], v[68:69] op_sel_hi:[1,0]
	v_pk_mul_f32 v[78:79], v[78:79], v[68:69] op_sel_hi:[1,0]
	v_pk_mul_f32 v[76:77], v[76:77], v[68:69] op_sel_hi:[1,0]
	v_pk_mul_f32 v[80:81], v[80:81], v[68:69] op_sel_hi:[1,0]
	v_pk_mul_f32 v[70:71], v[70:71], v[68:69] op_sel_hi:[1,0]
	v_pk_mul_f32 v[66:67], v[66:67], v[68:69] op_sel_hi:[1,0]
	v_pk_mul_f32 v[68:69], v[72:73], v[68:69] op_sel_hi:[1,0]
	v_mul_f32_e32 v72, 0xbfb8aa3b, v83
	v_mul_f32_e32 v91, 0xbfb8aa3b, v69
	v_mul_f32_e32 v73, 0xbfb8aa3b, v75
	v_mul_f32_e32 v86, 0xbfb8aa3b, v79
	v_mul_f32_e32 v87, 0xbfb8aa3b, v77
	v_mul_f32_e32 v88, 0xbfb8aa3b, v81
	v_mul_f32_e32 v89, 0xbfb8aa3b, v71
	v_mul_f32_e32 v90, 0xbfb8aa3b, v67
	v_exp_f32_e32 v91, v91
	v_exp_f32_e32 v72, v72
	v_exp_f32_e32 v73, v73
	v_exp_f32_e32 v86, v86
	v_exp_f32_e32 v87, v87
	v_exp_f32_e32 v88, v88
	v_exp_f32_e32 v89, v89
	v_exp_f32_e32 v90, v90
	v_add_f32_e32 v91, 1.0, v91
	v_add_f32_e32 v72, 1.0, v72
	v_add_f32_e32 v73, 1.0, v73
	v_add_f32_e32 v86, 1.0, v86
	v_add_f32_e32 v87, 1.0, v87
	v_add_f32_e32 v88, 1.0, v88
	v_add_f32_e32 v89, 1.0, v89
	v_add_f32_e32 v90, 1.0, v90
	v_rcp_f32_e32 v91, v91
	v_rcp_f32_e32 v72, v72
	v_rcp_f32_e32 v73, v73
	v_rcp_f32_e32 v86, v86
	v_rcp_f32_e32 v87, v87
	v_rcp_f32_e32 v88, v88
	v_rcp_f32_e32 v89, v89
	v_rcp_f32_e32 v90, v90
	v_mul_f32_e32 v69, v69, v91
	v_mul_f32_e32 v72, v83, v72
	v_mul_f32_e32 v73, v75, v73
	v_mul_f32_e32 v75, v79, v86
	v_mul_f32_e32 v77, v77, v87
	v_mul_f32_e32 v79, v81, v88
	v_mul_f32_e32 v71, v71, v89
	v_mul_f32_e32 v67, v67, v90
	v_mul_f32_e32 v69, v68, v69
	v_mul_f32_e32 v72, v82, v72
	v_mul_f32_e32 v73, v74, v73
	v_mul_f32_e32 v74, v78, v75
	v_mul_f32_e32 v75, v76, v77
	v_mul_f32_e32 v76, v80, v79
	v_mul_f32_e32 v70, v70, v71
	v_mul_f32_e32 v71, v66, v67
	v_cvt_pk_bf16_f32 v66, v72, v73
	v_cvt_pk_bf16_f32 v67, v74, v75
	v_cvt_pk_bf16_f32 v68, v76, v70
	v_cvt_pk_bf16_f32 v69, v71, v69
	global_store_dwordx4 v[84:85], v[66:69], off
	s_nop 0
	s_nop 0
	v_mov_b32_e32 v66, v62
	v_mov_b32_e32 v62, v64
	v_mov_b32_e32 v64, v50
	v_mov_b32_e32 v50, v52
	v_mov_b32_e32 v67, v58
	v_mov_b32_e32 v58, v63
	v_mov_b32_e32 v63, v60
	v_mov_b32_e32 v60, v65
	v_mov_b32_e32 v65, v54
	v_mov_b32_e32 v54, v51
	v_mov_b32_e32 v51, v56
	v_mov_b32_e32 v56, v53
	v_add_u32_e32 v53, 0x80, v140
	s_waitcnt vmcnt(7)
; __device__ __forceinline__ unsigned cvt_pk_bf16(float lo, float hi) { unsigned r; asm volatile("v_cvt_pk_bf16_f32 %0, %1, %2" : "=v"(r) : "v"(lo), "v"(hi)); return r; }
; __device__ __forceinline__ float silu_f(float x) { return x * sigmoid_f(x); }
;     __device__ __forceinline__ void operator()(const f32x4 (&acc)[2][2][4][2], const Unit& u, int wr, int wc, int fr, int fq) const {
;         const int row0 = u.pm * BM + wr * 64 + fr, col0 = u.pn * 128 + wc * 32 + 8 * fq;
; #pragma unroll
;         for (int ai = 0; ai < 2; ++ai)
; #pragma unroll
;             for (int m = 0; m < 4; ++m) {
;                 const int row = row0 + ai * HALF + m * 16;
;                 const float r = __builtin_amdgcn_rsqf(rss[row] * (1.f / 1024.f) + NEPS);
;                 float o[8];
; #pragma unroll
;                 for (int n = 0; n < 2; ++n)
; #pragma unroll
;                     for (int e = 0; e < 4; ++e) o[4 * n + e] = silu_f(acc[ai][0][m][n][e] * r) * (acc[ai][1][m][n][e] * r);
;                 u32x4 w; w.x = cvt_pk_bf16(o[0], o[1]); w.y = cvt_pk_bf16(o[2], o[3]); w.z = cvt_pk_bf16(o[4], o[5]); w.w = cvt_pk_bf16(o[6], o[7]);
;                 *(u32x4*)(O + (size_t)row * 2816 + col0) = w;
	v_mov_b32_e32 v68, v204
	v_fmamk_f32 v52, v68, 0x3a800000, v150
	v_rsq_f32_e32 v52, v52
	v_mad_i64_i32 v[68:69], s[24:25], v53, s47, v[118:119]
	v_lshl_add_u64 v[68:69], v[68:69], 0, v[120:121]
	v_pk_mul_f32 v[66:67], v[66:67], v[52:53] op_sel_hi:[1,0]
	v_pk_mul_f32 v[58:59], v[58:59], v[52:53] op_sel_hi:[1,0]
	v_pk_mul_f32 v[62:63], v[62:63], v[52:53] op_sel_hi:[1,0]
	v_pk_mul_f32 v[60:61], v[60:61], v[52:53] op_sel_hi:[1,0]
	v_pk_mul_f32 v[64:65], v[64:65], v[52:53] op_sel_hi:[1,0]
	v_pk_mul_f32 v[54:55], v[54:55], v[52:53] op_sel_hi:[1,0]
	v_pk_mul_f32 v[50:51], v[50:51], v[52:53] op_sel_hi:[1,0]
	v_pk_mul_f32 v[52:53], v[56:57], v[52:53] op_sel_hi:[1,0]
	v_mul_f32_e32 v56, 0xbfb8aa3b, v67
	v_mul_f32_e32 v75, 0xbfb8aa3b, v53
	v_mul_f32_e32 v57, 0xbfb8aa3b, v59
	v_mul_f32_e32 v70, 0xbfb8aa3b, v63
	v_mul_f32_e32 v71, 0xbfb8aa3b, v61
	v_mul_f32_e32 v72, 0xbfb8aa3b, v65
	v_mul_f32_e32 v73, 0xbfb8aa3b, v55
	v_mul_f32_e32 v74, 0xbfb8aa3b, v51
	v_exp_f32_e32 v75, v75
	v_exp_f32_e32 v56, v56
	v_exp_f32_e32 v57, v57
	v_exp_f32_e32 v70, v70
	v_exp_f32_e32 v71, v71
	v_exp_f32_e32 v72, v72
	v_exp_f32_e32 v73, v73
	v_exp_f32_e32 v74, v74
	v_add_f32_e32 v75, 1.0, v75
	v_add_f32_e32 v56, 1.0, v56
	v_add_f32_e32 v57, 1.0, v57
	v_add_f32_e32 v70, 1.0, v70
	v_add_f32_e32 v71, 1.0, v71
	v_add_f32_e32 v72, 1.0, v72
	v_add_f32_e32 v73, 1.0, v73
	v_add_f32_e32 v74, 1.0, v74
	v_rcp_f32_e32 v75, v75
	v_rcp_f32_e32 v56, v56
	v_rcp_f32_e32 v57, v57
	v_rcp_f32_e32 v70, v70
	v_rcp_f32_e32 v71, v71
	v_rcp_f32_e32 v72, v72
	v_rcp_f32_e32 v73, v73
	v_rcp_f32_e32 v74, v74
	v_mul_f32_e32 v53, v53, v75
	v_mul_f32_e32 v56, v67, v56
	v_mul_f32_e32 v57, v59, v57
	v_mul_f32_e32 v59, v63, v70
	v_mul_f32_e32 v61, v61, v71
	v_mul_f32_e32 v63, v65, v72
	v_mul_f32_e32 v55, v55, v73
	v_mul_f32_e32 v51, v51, v74
	v_mul_f32_e32 v53, v52, v53
	v_mul_f32_e32 v56, v66, v56
	v_mul_f32_e32 v57, v58, v57
	v_mul_f32_e32 v58, v62, v59
	v_mul_f32_e32 v59, v60, v61
	v_mul_f32_e32 v60, v64, v63
	v_mul_f32_e32 v54, v54, v55
	v_mul_f32_e32 v55, v50, v51
	v_cvt_pk_bf16_f32 v50, v56, v57
	v_cvt_pk_bf16_f32 v51, v58, v59
	v_cvt_pk_bf16_f32 v52, v60, v54
	v_cvt_pk_bf16_f32 v53, v55, v53
	global_store_dwordx4 v[68:69], v[50:53], off
	s_nop 0
	s_nop 0
	v_mov_b32_e32 v50, v46
	v_mov_b32_e32 v46, v48
	v_mov_b32_e32 v48, v34
	v_mov_b32_e32 v34, v36
	v_mov_b32_e32 v51, v42
	v_mov_b32_e32 v42, v47
	v_mov_b32_e32 v47, v44
	v_mov_b32_e32 v44, v49
	v_mov_b32_e32 v49, v38
	v_mov_b32_e32 v38, v35
	v_mov_b32_e32 v35, v40
	v_mov_b32_e32 v40, v37
	v_add_u32_e32 v37, 0x90, v140
	s_waitcnt vmcnt(7)
	v_mov_b32_e32 v52, v205
	v_fmamk_f32 v36, v52, 0x3a800000, v150
	v_rsq_f32_e32 v36, v36
	v_mad_i64_i32 v[52:53], s[24:25], v37, s47, v[118:119]
	v_lshl_add_u64 v[52:53], v[52:53], 0, v[120:121]
	v_pk_mul_f32 v[50:51], v[50:51], v[36:37] op_sel_hi:[1,0]
	v_pk_mul_f32 v[42:43], v[42:43], v[36:37] op_sel_hi:[1,0]
	v_pk_mul_f32 v[46:47], v[46:47], v[36:37] op_sel_hi:[1,0]
	v_pk_mul_f32 v[44:45], v[44:45], v[36:37] op_sel_hi:[1,0]
	v_pk_mul_f32 v[48:49], v[48:49], v[36:37] op_sel_hi:[1,0]
	v_pk_mul_f32 v[38:39], v[38:39], v[36:37] op_sel_hi:[1,0]
	v_pk_mul_f32 v[34:35], v[34:35], v[36:37] op_sel_hi:[1,0]
	v_pk_mul_f32 v[36:37], v[40:41], v[36:37] op_sel_hi:[1,0]
	v_mul_f32_e32 v40, 0xbfb8aa3b, v51
	v_mul_f32_e32 v59, 0xbfb8aa3b, v37
	v_mul_f32_e32 v41, 0xbfb8aa3b, v43
	v_mul_f32_e32 v54, 0xbfb8aa3b, v47
	v_mul_f32_e32 v55, 0xbfb8aa3b, v45
	v_mul_f32_e32 v56, 0xbfb8aa3b, v49
	v_mul_f32_e32 v57, 0xbfb8aa3b, v39
	v_mul_f32_e32 v58, 0xbfb8aa3b, v35
	v_exp_f32_e32 v59, v59
	v_exp_f32_e32 v40, v40
	v_exp_f32_e32 v41, v41
	v_exp_f32_e32 v54, v54
	v_exp_f32_e32 v55, v55
	v_exp_f32_e32 v56, v56
	v_exp_f32_e32 v57, v57
	v_exp_f32_e32 v58, v58
	v_add_f32_e32 v59, 1.0, v59
	v_add_f32_e32 v40, 1.0, v40
	v_add_f32_e32 v41, 1.0, v41
	v_add_f32_e32 v54, 1.0, v54
	v_add_f32_e32 v55, 1.0, v55
	v_add_f32_e32 v56, 1.0, v56
	v_add_f32_e32 v57, 1.0, v57
	v_add_f32_e32 v58, 1.0, v58
	v_rcp_f32_e32 v59, v59
	v_rcp_f32_e32 v40, v40
	v_rcp_f32_e32 v41, v41
	v_rcp_f32_e32 v54, v54
	v_rcp_f32_e32 v55, v55
	v_rcp_f32_e32 v56, v56
	v_rcp_f32_e32 v57, v57
	v_rcp_f32_e32 v58, v58
	v_mul_f32_e32 v37, v37, v59
	v_mul_f32_e32 v40, v51, v40
	v_mul_f32_e32 v41, v43, v41
	v_mul_f32_e32 v43, v47, v54
	v_mul_f32_e32 v45, v45, v55
	v_mul_f32_e32 v47, v49, v56
	v_mul_f32_e32 v39, v39, v57
	v_mul_f32_e32 v35, v35, v58
	v_mul_f32_e32 v37, v36, v37
	v_mul_f32_e32 v40, v50, v40
	v_mul_f32_e32 v41, v42, v41
	v_mul_f32_e32 v42, v46, v43
	v_mul_f32_e32 v43, v44, v45
	v_mul_f32_e32 v44, v48, v47
	v_mul_f32_e32 v38, v38, v39
	v_mul_f32_e32 v39, v34, v35
	v_cvt_pk_bf16_f32 v34, v40, v41
	v_cvt_pk_bf16_f32 v35, v42, v43
	v_cvt_pk_bf16_f32 v36, v44, v38
	v_cvt_pk_bf16_f32 v37, v39, v37
	global_store_dwordx4 v[52:53], v[34:37], off
	s_nop 0
	s_nop 0
	v_mov_b32_e32 v34, v30
	v_mov_b32_e32 v30, v32
	v_mov_b32_e32 v32, v18
	v_mov_b32_e32 v18, v20
	v_mov_b32_e32 v35, v26
	v_mov_b32_e32 v26, v31
	v_mov_b32_e32 v31, v28
	v_mov_b32_e32 v28, v33
	v_mov_b32_e32 v33, v22
	v_mov_b32_e32 v22, v19
	v_mov_b32_e32 v19, v24
	v_mov_b32_e32 v24, v21
	v_add_u32_e32 v21, 0xa0, v140
	s_waitcnt vmcnt(7)
; __device__ __forceinline__ unsigned cvt_pk_bf16(float lo, float hi) { unsigned r; asm volatile("v_cvt_pk_bf16_f32 %0, %1, %2" : "=v"(r) : "v"(lo), "v"(hi)); return r; }
; __device__ __forceinline__ float silu_f(float x) { return x * sigmoid_f(x); }
;     __device__ __forceinline__ void operator()(const f32x4 (&acc)[2][2][4][2], const Unit& u, int wr, int wc, int fr, int fq) const {
;         const int row0 = u.pm * BM + wr * 64 + fr, col0 = u.pn * 128 + wc * 32 + 8 * fq;
; #pragma unroll
;         for (int ai = 0; ai < 2; ++ai)
; #pragma unroll
;             for (int m = 0; m < 4; ++m) {
;                 const int row = row0 + ai * HALF + m * 16;
;                 const float r = __builtin_amdgcn_rsqf(rss[row] * (1.f / 1024.f) + NEPS);
;                 float o[8];
; #pragma unroll
;                 for (int n = 0; n < 2; ++n)
; #pragma unroll
;                     for (int e = 0; e < 4; ++e) o[4 * n + e] = silu_f(acc[ai][0][m][n][e] * r) * (acc[ai][1][m][n][e] * r);
;                 u32x4 w; w.x = cvt_pk_bf16(o[0], o[1]); w.y = cvt_pk_bf16(o[2], o[3]); w.z = cvt_pk_bf16(o[4], o[5]); w.w = cvt_pk_bf16(o[6], o[7]);
;                 *(u32x4*)(O + (size_t)row * 2816 + col0) = w;
	v_mov_b32_e32 v36, v206
	v_fmamk_f32 v20, v36, 0x3a800000, v150
	v_rsq_f32_e32 v20, v20
	v_mad_i64_i32 v[36:37], s[24:25], v21, s47, v[118:119]
	v_lshl_add_u64 v[36:37], v[36:37], 0, v[120:121]
	v_pk_mul_f32 v[34:35], v[34:35], v[20:21] op_sel_hi:[1,0]
	v_pk_mul_f32 v[26:27], v[26:27], v[20:21] op_sel_hi:[1,0]
	v_pk_mul_f32 v[30:31], v[30:31], v[20:21] op_sel_hi:[1,0]
	v_pk_mul_f32 v[28:29], v[28:29], v[20:21] op_sel_hi:[1,0]
	v_pk_mul_f32 v[32:33], v[32:33], v[20:21] op_sel_hi:[1,0]
	v_pk_mul_f32 v[22:23], v[22:23], v[20:21] op_sel_hi:[1,0]
	v_pk_mul_f32 v[18:19], v[18:19], v[20:21] op_sel_hi:[1,0]
	v_pk_mul_f32 v[20:21], v[24:25], v[20:21] op_sel_hi:[1,0]
	v_mul_f32_e32 v24, 0xbfb8aa3b, v35
	v_mul_f32_e32 v43, 0xbfb8aa3b, v21
	v_mul_f32_e32 v25, 0xbfb8aa3b, v27
	v_mul_f32_e32 v38, 0xbfb8aa3b, v31
	v_mul_f32_e32 v39, 0xbfb8aa3b, v29
	v_mul_f32_e32 v40, 0xbfb8aa3b, v33
	v_mul_f32_e32 v41, 0xbfb8aa3b, v23
	v_mul_f32_e32 v42, 0xbfb8aa3b, v19
	v_exp_f32_e32 v43, v43
	v_exp_f32_e32 v24, v24
	v_exp_f32_e32 v25, v25
	v_exp_f32_e32 v38, v38
	v_exp_f32_e32 v39, v39
	v_exp_f32_e32 v40, v40
	v_exp_f32_e32 v41, v41
	v_exp_f32_e32 v42, v42
	v_add_f32_e32 v43, 1.0, v43
	v_add_f32_e32 v24, 1.0, v24
	v_add_f32_e32 v25, 1.0, v25
	v_add_f32_e32 v38, 1.0, v38
	v_add_f32_e32 v39, 1.0, v39
	v_add_f32_e32 v40, 1.0, v40
	v_add_f32_e32 v41, 1.0, v41
	v_add_f32_e32 v42, 1.0, v42
	v_rcp_f32_e32 v43, v43
	v_rcp_f32_e32 v24, v24
	v_rcp_f32_e32 v25, v25
	v_rcp_f32_e32 v38, v38
	v_rcp_f32_e32 v39, v39
	v_rcp_f32_e32 v40, v40
	v_rcp_f32_e32 v41, v41
	v_rcp_f32_e32 v42, v42
	v_mul_f32_e32 v21, v21, v43
	v_mul_f32_e32 v24, v35, v24
	v_mul_f32_e32 v25, v27, v25
	v_mul_f32_e32 v27, v31, v38
	v_mul_f32_e32 v29, v29, v39
	v_mul_f32_e32 v31, v33, v40
	v_mul_f32_e32 v23, v23, v41
	v_mul_f32_e32 v19, v19, v42
	v_mul_f32_e32 v21, v20, v21
	v_mul_f32_e32 v24, v34, v24
	v_mul_f32_e32 v25, v26, v25
	v_mul_f32_e32 v26, v30, v27
	v_mul_f32_e32 v27, v28, v29
	v_mul_f32_e32 v28, v32, v31
	v_mul_f32_e32 v22, v22, v23
	v_mul_f32_e32 v23, v18, v19
	v_cvt_pk_bf16_f32 v18, v24, v25
	v_cvt_pk_bf16_f32 v19, v26, v27
	v_cvt_pk_bf16_f32 v20, v28, v22
	v_cvt_pk_bf16_f32 v21, v23, v21
	global_store_dwordx4 v[36:37], v[18:21], off
	s_nop 0
	s_nop 0
	v_mov_b32_e32 v18, v14
	v_mov_b32_e32 v14, v16
	v_mov_b32_e32 v16, v2
	v_mov_b32_e32 v2, v4
	v_mov_b32_e32 v19, v10
	v_mov_b32_e32 v10, v15
	v_mov_b32_e32 v15, v12
	v_mov_b32_e32 v12, v17
	v_mov_b32_e32 v17, v6
	v_mov_b32_e32 v6, v3
	v_mov_b32_e32 v3, v8
	v_mov_b32_e32 v8, v5
	v_add_u32_e32 v5, 0xb0, v140
	s_waitcnt vmcnt(7)
	v_mov_b32_e32 v20, v207
	v_fmamk_f32 v4, v20, 0x3a800000, v150
	v_rsq_f32_e32 v4, v4
	v_mad_i64_i32 v[20:21], s[24:25], v5, s47, v[118:119]
	v_lshl_add_u64 v[20:21], v[20:21], 0, v[120:121]
	v_pk_mul_f32 v[18:19], v[18:19], v[4:5] op_sel_hi:[1,0]
	v_pk_mul_f32 v[10:11], v[10:11], v[4:5] op_sel_hi:[1,0]
	v_pk_mul_f32 v[14:15], v[14:15], v[4:5] op_sel_hi:[1,0]
	v_pk_mul_f32 v[12:13], v[12:13], v[4:5] op_sel_hi:[1,0]
	v_pk_mul_f32 v[16:17], v[16:17], v[4:5] op_sel_hi:[1,0]
	v_pk_mul_f32 v[6:7], v[6:7], v[4:5] op_sel_hi:[1,0]
	v_pk_mul_f32 v[2:3], v[2:3], v[4:5] op_sel_hi:[1,0]
	v_pk_mul_f32 v[4:5], v[8:9], v[4:5] op_sel_hi:[1,0]
	v_mul_f32_e32 v8, 0xbfb8aa3b, v19
	v_mul_f32_e32 v27, 0xbfb8aa3b, v5
	v_mul_f32_e32 v9, 0xbfb8aa3b, v11
	v_mul_f32_e32 v22, 0xbfb8aa3b, v15
	v_mul_f32_e32 v23, 0xbfb8aa3b, v13
	v_mul_f32_e32 v24, 0xbfb8aa3b, v17
	v_mul_f32_e32 v25, 0xbfb8aa3b, v7
	v_mul_f32_e32 v26, 0xbfb8aa3b, v3
	v_exp_f32_e32 v27, v27
	v_exp_f32_e32 v8, v8
	v_exp_f32_e32 v9, v9
	v_exp_f32_e32 v22, v22
	v_exp_f32_e32 v23, v23
	v_exp_f32_e32 v24, v24
	v_exp_f32_e32 v25, v25
	v_exp_f32_e32 v26, v26
	v_add_f32_e32 v27, 1.0, v27
	v_add_f32_e32 v8, 1.0, v8
	v_add_f32_e32 v9, 1.0, v9
	v_add_f32_e32 v22, 1.0, v22
	v_add_f32_e32 v23, 1.0, v23
	v_add_f32_e32 v24, 1.0, v24
	v_add_f32_e32 v25, 1.0, v25
	v_add_f32_e32 v26, 1.0, v26
	v_rcp_f32_e32 v27, v27
	v_rcp_f32_e32 v8, v8
	v_rcp_f32_e32 v9, v9
	v_rcp_f32_e32 v22, v22
	v_rcp_f32_e32 v23, v23
	v_rcp_f32_e32 v24, v24
	v_rcp_f32_e32 v25, v25
	v_rcp_f32_e32 v26, v26
	v_mul_f32_e32 v5, v5, v27
	v_mul_f32_e32 v8, v19, v8
	v_mul_f32_e32 v9, v11, v9
	v_mul_f32_e32 v11, v15, v22
	v_mul_f32_e32 v13, v13, v23
	v_mul_f32_e32 v15, v17, v24
	v_mul_f32_e32 v7, v7, v25
	v_mul_f32_e32 v3, v3, v26
	v_mul_f32_e32 v5, v4, v5
	v_mul_f32_e32 v8, v18, v8
	v_mul_f32_e32 v9, v10, v9
	v_mul_f32_e32 v10, v14, v11
	v_mul_f32_e32 v11, v12, v13
	v_mul_f32_e32 v12, v16, v15
	v_mul_f32_e32 v6, v6, v7
	v_mul_f32_e32 v7, v2, v3
	v_cvt_pk_bf16_f32 v2, v8, v9
	v_cvt_pk_bf16_f32 v3, v10, v11
	v_cvt_pk_bf16_f32 v4, v12, v6
	v_cvt_pk_bf16_f32 v5, v7, v5
	global_store_dwordx4 v[20:21], v[2:5], off
	s_cbranch_vccnz .LBB0_127
	s_andn2_b64 vcc, exec, s[10:11]
	s_cbranch_vccnz .LBB0_126
	s_barrier
	s_branch .LBB0_126

; __device__ __forceinline__ unsigned cvt_pk_bf16(float lo, float hi) { unsigned r; asm volatile("v_cvt_pk_bf16_f32 %0, %1, %2" : "=v"(r) : "v"(lo), "v"(hi)); return r; }
; __device__ __forceinline__ float sigmoid_f(float x) { return __builtin_amdgcn_rcpf(1.f + __builtin_amdgcn_exp2f(-1.4426950408889634f * x)); }
;     __device__ __forceinline__ void operator()(const f32x4 (&acc)[2][2][4][2], const Unit& u, int wr, int wc, int fr, int fq) const {
;     ...
;             const int col0 = (pn - 13) * 256 + wc * 32 + 8 * fq;
;             f32x4 bv[2][2];
; #pragma unroll
;             for (int bj = 0; bj < 2; ++bj)
; #pragma unroll
;                 for (int n = 0; n < 2; ++n) bv[bj][n] = *(const f32x4*)(b_gate + col0 + bj * HALF + 4 * n);
; #pragma unroll
;             for (int ai = 0; ai < 2; ++ai)
; #pragma unroll
;                 for (int m = 0; m < 4; ++m) {
;                     const int row = row0 + ai * HALF + m * 16; const float r = __builtin_amdgcn_rsqf(rss[row] * (1.f / 1024.f) + NEPS);
; #pragma unroll
;                     for (int bj = 0; bj < 2; ++bj) {
;                         float o[8];
; #pragma unroll
;                         for (int n = 0; n < 2; ++n)
; #pragma unroll
;                             for (int e = 0; e < 4; ++e) o[4 * n + e] = sigmoid_f(acc[ai][bj][m][n][e] * r + bv[bj][n][e]);
;                         u32x4 w; w.x = cvt_pk_bf16(o[0], o[1]); w.y = cvt_pk_bf16(o[2], o[3]); w.z = cvt_pk_bf16(o[4], o[5]); w.w = cvt_pk_bf16(o[6], o[7]);
;                         *(u32x4*)(G + (size_t)row * 2048 + col0 + bj * HALF) = w;
;                     }
.LBB0_390:
	s_lshl_b32 s29, s2, 8
	s_add_i32 s29, s29, s78
	s_cmp_gt_i32 s2, 63
	s_cselect_b64 s[56:57], -1, 0
	s_cmp_lt_i32 s2, 64
	v_or_b32_e32 v182, s29, v163
	s_cselect_b64 s[54:55], -1, 0
	s_cmp_gt_i32 s38, 3
	s_mov_b64 s[2:3], -1
	s_cbranch_scc0 .LBB0_556
	s_cmp_gt_u32 s38, 12
	s_cbranch_scc0 .LBB0_393
	v_ashrrev_i32_e32 v183, 31, v182
	v_lshl_add_u64 v[146:147], v[182:183], 2, s[40:41]
	global_load_dword v236, v[146:147], off
	global_load_dword v237, v[146:147], off offset:64
	global_load_dword v238, v[146:147], off offset:128
	global_load_dword v239, v[146:147], off offset:192
	global_load_dword v240, v[146:147], off offset:512
	global_load_dword v241, v[146:147], off offset:576
	global_load_dword v242, v[146:147], off offset:640
	global_load_dword v243, v[146:147], off offset:704
	v_readlane_b32 s2, v250, 14
	v_lshl_add_u32 v168, s38, 8, v204
	v_readlane_b32 s3, v250, 15
	v_lshlrev_b64 v[148:149], 12, v[182:183]
	v_lshl_add_u64 v[148:149], s[94:95], 0, v[148:149]
	v_lshl_add_u64 v[130:131], v[168:169], 2, s[2:3]
	global_load_dwordx4 v[142:145], v[130:131], off
	global_load_dwordx4 v[138:141], v[130:131], off offset:16
	global_load_dwordx4 v[134:137], v[130:131], off offset:512
	s_nop 0
	global_load_dwordx4 v[130:133], v[130:131], off offset:528
	s_mov_b32 s0, 0x80000
	s_mov_b64 s[2:3], 0x80000
	s_waitcnt vmcnt(0)
	v_mov_b32_e32 v150, v236
	v_fmamk_f32 v150, v150, 0x3a800000, v212
	v_rsq_f32_e32 v152, v150
	v_lshlrev_b64 v[150:151], 1, v[168:169]
	v_lshl_add_u64 v[148:149], v[148:149], 0, v[150:151]
	v_fma_f32 v153, v126, v152, v142
	v_fma_f32 v154, v127, v152, v143
	v_fma_f32 v155, v128, v152, v144
	v_fma_f32 v156, v129, v152, v145
	v_fma_f32 v157, v122, v152, v138
	v_fma_f32 v158, v123, v152, v139
	v_fma_f32 v159, v124, v152, v140
	v_fma_f32 v160, v125, v152, v141
	v_fma_f32 v161, v118, v152, v134
	v_fma_f32 v168, v119, v152, v135
	v_fma_f32 v183, v120, v152, v136
	v_fma_f32 v184, v121, v152, v137
	v_fma_f32 v185, v114, v152, v130
	v_fma_f32 v186, v115, v152, v131
	v_fma_f32 v187, v116, v152, v132
	v_fma_f32 v152, v117, v152, v133
	v_mul_f32_e32 v153, 0xbfb8aa3b, v153
	v_mul_f32_e32 v154, 0xbfb8aa3b, v154
	v_mul_f32_e32 v155, 0xbfb8aa3b, v155
	v_mul_f32_e32 v152, 0xbfb8aa3b, v152
	v_mul_f32_e32 v156, 0xbfb8aa3b, v156
	v_mul_f32_e32 v157, 0xbfb8aa3b, v157
	v_mul_f32_e32 v158, 0xbfb8aa3b, v158
	v_mul_f32_e32 v159, 0xbfb8aa3b, v159
	v_mul_f32_e32 v160, 0xbfb8aa3b, v160
	v_mul_f32_e32 v161, 0xbfb8aa3b, v161
	v_mul_f32_e32 v168, 0xbfb8aa3b, v168
	v_exp_f32_e32 v153, v153
	v_exp_f32_e32 v154, v154
	v_exp_f32_e32 v155, v155
	v_exp_f32_e32 v152, v152
	v_mul_f32_e32 v183, 0xbfb8aa3b, v183
	v_mul_f32_e32 v184, 0xbfb8aa3b, v184
	v_mul_f32_e32 v185, 0xbfb8aa3b, v185
	v_mul_f32_e32 v186, 0xbfb8aa3b, v186
	v_mul_f32_e32 v187, 0xbfb8aa3b, v187
	v_exp_f32_e32 v156, v156
	v_exp_f32_e32 v157, v157
	v_exp_f32_e32 v158, v158
	v_exp_f32_e32 v159, v159
	v_exp_f32_e32 v160, v160
	v_exp_f32_e32 v161, v161
	v_exp_f32_e32 v168, v168
	v_exp_f32_e32 v183, v183
	v_exp_f32_e32 v184, v184
	v_exp_f32_e32 v185, v185
	v_exp_f32_e32 v186, v186
	v_exp_f32_e32 v187, v187
	v_add_f32_e32 v153, 1.0, v153
	v_add_f32_e32 v154, 1.0, v154
	v_add_f32_e32 v155, 1.0, v155
	v_add_f32_e32 v152, 1.0, v152
	v_add_f32_e32 v156, 1.0, v156
	v_add_f32_e32 v157, 1.0, v157
	v_add_f32_e32 v158, 1.0, v158
	v_add_f32_e32 v159, 1.0, v159
	v_add_f32_e32 v160, 1.0, v160
	v_add_f32_e32 v161, 1.0, v161
	v_add_f32_e32 v168, 1.0, v168
	v_rcp_f32_e32 v153, v153
	v_rcp_f32_e32 v154, v154
	v_rcp_f32_e32 v155, v155
	v_rcp_f32_e32 v188, v152
	v_cvt_pk_bf16_f32 v152, v153, v154
	v_add_f32_e32 v183, 1.0, v183
	v_add_f32_e32 v184, 1.0, v184
	v_add_f32_e32 v185, 1.0, v185
	v_add_f32_e32 v186, 1.0, v186
	v_add_f32_e32 v187, 1.0, v187
	v_rcp_f32_e32 v156, v156
	v_rcp_f32_e32 v157, v157
	v_rcp_f32_e32 v158, v158
	v_rcp_f32_e32 v159, v159
	v_rcp_f32_e32 v160, v160
	v_rcp_f32_e32 v161, v161
	v_rcp_f32_e32 v168, v168
	v_cvt_pk_bf16_f32 v153, v155, v156
	v_cvt_pk_bf16_f32 v154, v157, v158
	v_cvt_pk_bf16_f32 v155, v159, v160
	global_store_dwordx4 v[148:149], v[152:155], off
	v_rcp_f32_e32 v183, v183
	v_rcp_f32_e32 v184, v184
	v_cvt_pk_bf16_f32 v152, v161, v168
	v_rcp_f32_e32 v185, v185
	v_rcp_f32_e32 v186, v186
	v_rcp_f32_e32 v187, v187
	v_cvt_pk_bf16_f32 v153, v183, v184
	v_cvt_pk_bf16_f32 v154, v185, v186
	v_cvt_pk_bf16_f32 v155, v187, v188
	global_store_dwordx4 v[148:149], v[152:155], off offset:256
	s_nop 1
	v_or_b32_e32 v152, 16, v182
	v_ashrrev_i32_e32 v153, 31, v152
	v_lshl_add_u64 v[154:155], v[152:153], 2, s[40:41]
	s_nop 0
	v_lshlrev_b64 v[152:153], 12, v[152:153]
	v_lshl_add_u64 v[152:153], s[94:95], 0, v[152:153]
	v_lshl_add_u64 v[156:157], v[152:153], 0, v[150:151]
	s_waitcnt vmcnt(7)
; __device__ __forceinline__ unsigned cvt_pk_bf16(float lo, float hi) { unsigned r; asm volatile("v_cvt_pk_bf16_f32 %0, %1, %2" : "=v"(r) : "v"(lo), "v"(hi)); return r; }
; __device__ __forceinline__ float sigmoid_f(float x) { return __builtin_amdgcn_rcpf(1.f + __builtin_amdgcn_exp2f(-1.4426950408889634f * x)); }
;     __device__ __forceinline__ void operator()(const f32x4 (&acc)[2][2][4][2], const Unit& u, int wr, int wc, int fr, int fq) const {
;     ...
;             for (int ai = 0; ai < 2; ++ai)
; #pragma unroll
;                 for (int m = 0; m < 4; ++m) {
;                     const int row = row0 + ai * HALF + m * 16; const float r = __builtin_amdgcn_rsqf(rss[row] * (1.f / 1024.f) + NEPS);
; #pragma unroll
;                     for (int bj = 0; bj < 2; ++bj) {
;                         float o[8];
; #pragma unroll
;                         for (int n = 0; n < 2; ++n)
; #pragma unroll
;                             for (int e = 0; e < 4; ++e) o[4 * n + e] = sigmoid_f(acc[ai][bj][m][n][e] * r + bv[bj][n][e]);
;                         u32x4 w; w.x = cvt_pk_bf16(o[0], o[1]); w.y = cvt_pk_bf16(o[2], o[3]); w.z = cvt_pk_bf16(o[4], o[5]); w.w = cvt_pk_bf16(o[6], o[7]);
;                         *(u32x4*)(G + (size_t)row * 2048 + col0 + bj * HALF) = w;
;                     }
	v_mov_b32_e32 v154, v237
	v_fmamk_f32 v154, v154, 0x3a800000, v212
	v_rsq_f32_e32 v154, v154
	s_nop 0
	v_fma_f32 v152, v110, v154, v142
	v_fma_f32 v153, v111, v154, v143
	v_fma_f32 v155, v112, v154, v144
	v_mul_f32_e32 v152, 0xbfb8aa3b, v152
	v_fma_f32 v158, v113, v154, v145
	v_fma_f32 v159, v106, v154, v138
	v_fma_f32 v160, v107, v154, v139
	v_fma_f32 v161, v108, v154, v140
	v_fma_f32 v168, v109, v154, v141
	v_fma_f32 v183, v102, v154, v134
	v_fma_f32 v184, v103, v154, v135
	v_fma_f32 v185, v104, v154, v136
	v_fma_f32 v186, v105, v154, v137
	v_fma_f32 v187, v98, v154, v130
	v_fma_f32 v188, v99, v154, v131
	v_fma_f32 v189, v100, v154, v132
	v_fma_f32 v154, v101, v154, v133
	v_mul_f32_e32 v153, 0xbfb8aa3b, v153
	v_mul_f32_e32 v155, 0xbfb8aa3b, v155
	v_exp_f32_e32 v152, v152
	v_mul_f32_e32 v158, 0xbfb8aa3b, v158
	v_mul_f32_e32 v159, 0xbfb8aa3b, v159
	v_mul_f32_e32 v160, 0xbfb8aa3b, v160
	v_mul_f32_e32 v161, 0xbfb8aa3b, v161
	v_mul_f32_e32 v168, 0xbfb8aa3b, v168
	v_mul_f32_e32 v183, 0xbfb8aa3b, v183
	v_mul_f32_e32 v184, 0xbfb8aa3b, v184
	v_mul_f32_e32 v154, 0xbfb8aa3b, v154
	v_exp_f32_e32 v153, v153
	v_exp_f32_e32 v155, v155
	v_mul_f32_e32 v185, 0xbfb8aa3b, v185
	v_mul_f32_e32 v186, 0xbfb8aa3b, v186
	v_mul_f32_e32 v187, 0xbfb8aa3b, v187
	v_mul_f32_e32 v188, 0xbfb8aa3b, v188
	v_mul_f32_e32 v189, 0xbfb8aa3b, v189
	v_exp_f32_e32 v158, v158
	v_exp_f32_e32 v159, v159
	v_exp_f32_e32 v160, v160
	v_exp_f32_e32 v161, v161
	v_exp_f32_e32 v168, v168
	v_exp_f32_e32 v183, v183
	v_exp_f32_e32 v184, v184
	v_exp_f32_e32 v154, v154
	v_exp_f32_e32 v185, v185
	v_exp_f32_e32 v186, v186
	v_exp_f32_e32 v187, v187
	v_exp_f32_e32 v188, v188
	v_exp_f32_e32 v189, v189
	v_add_f32_e32 v152, 1.0, v152
	v_add_f32_e32 v153, 1.0, v153
	v_add_f32_e32 v155, 1.0, v155
	v_rcp_f32_e32 v152, v152
	v_add_f32_e32 v158, 1.0, v158
	v_add_f32_e32 v159, 1.0, v159
	v_add_f32_e32 v160, 1.0, v160
	v_add_f32_e32 v161, 1.0, v161
	v_add_f32_e32 v168, 1.0, v168
	v_add_f32_e32 v183, 1.0, v183
	v_add_f32_e32 v184, 1.0, v184
	v_add_f32_e32 v154, 1.0, v154
	v_rcp_f32_e32 v153, v153
	v_rcp_f32_e32 v155, v155
	v_cvt_pk_bf16_f32 v152, v152, v153
	v_add_f32_e32 v185, 1.0, v185
	v_add_f32_e32 v186, 1.0, v186
	v_add_f32_e32 v187, 1.0, v187
	v_add_f32_e32 v188, 1.0, v188
	v_add_f32_e32 v189, 1.0, v189
	v_rcp_f32_e32 v158, v158
	v_rcp_f32_e32 v159, v159
	v_rcp_f32_e32 v160, v160
	v_rcp_f32_e32 v161, v161
	v_rcp_f32_e32 v168, v168
	v_rcp_f32_e32 v183, v183
	v_rcp_f32_e32 v184, v184
	v_rcp_f32_e32 v190, v154
	v_cvt_pk_bf16_f32 v153, v155, v158
	v_cvt_pk_bf16_f32 v154, v159, v160
	v_cvt_pk_bf16_f32 v155, v161, v168
	global_store_dwordx4 v[156:157], v[152:155], off
	v_rcp_f32_e32 v185, v185
	v_rcp_f32_e32 v186, v186
	v_cvt_pk_bf16_f32 v152, v183, v184
	v_rcp_f32_e32 v187, v187
	v_rcp_f32_e32 v188, v188
	v_rcp_f32_e32 v189, v189
	v_cvt_pk_bf16_f32 v153, v185, v186
	v_cvt_pk_bf16_f32 v154, v187, v188
	v_cvt_pk_bf16_f32 v155, v189, v190
	global_store_dwordx4 v[156:157], v[152:155], off offset:256
	s_nop 1
	v_or_b32_e32 v152, 32, v182
	v_ashrrev_i32_e32 v153, 31, v152
	v_lshl_add_u64 v[154:155], v[152:153], 2, s[40:41]
	s_nop 0
	v_lshlrev_b64 v[152:153], 12, v[152:153]
	v_lshl_add_u64 v[152:153], s[94:95], 0, v[152:153]
	v_lshl_add_u64 v[156:157], v[152:153], 0, v[150:151]
	s_waitcnt vmcnt(7)
	v_mov_b32_e32 v154, v238
	v_fmamk_f32 v154, v154, 0x3a800000, v212
	v_rsq_f32_e32 v154, v154
	s_nop 0
	v_fma_f32 v152, v94, v154, v142
	v_fma_f32 v153, v95, v154, v143
	v_fma_f32 v155, v96, v154, v144
	v_mul_f32_e32 v152, 0xbfb8aa3b, v152
	v_fma_f32 v158, v97, v154, v145
	v_fma_f32 v159, v90, v154, v138
	v_fma_f32 v160, v91, v154, v139
	v_fma_f32 v161, v92, v154, v140
	v_fma_f32 v168, v93, v154, v141
	v_fma_f32 v183, v86, v154, v134
	v_fma_f32 v184, v87, v154, v135
	v_fma_f32 v185, v88, v154, v136
	v_fma_f32 v186, v89, v154, v137
	v_fma_f32 v187, v82, v154, v130
	v_fma_f32 v188, v83, v154, v131
	v_fma_f32 v189, v84, v154, v132
	v_fma_f32 v154, v85, v154, v133
	v_mul_f32_e32 v153, 0xbfb8aa3b, v153
	v_mul_f32_e32 v155, 0xbfb8aa3b, v155
	v_exp_f32_e32 v152, v152
	v_mul_f32_e32 v158, 0xbfb8aa3b, v158
	v_mul_f32_e32 v159, 0xbfb8aa3b, v159
	v_mul_f32_e32 v160, 0xbfb8aa3b, v160
	v_mul_f32_e32 v161, 0xbfb8aa3b, v161
	v_mul_f32_e32 v168, 0xbfb8aa3b, v168
	v_mul_f32_e32 v183, 0xbfb8aa3b, v183
	v_mul_f32_e32 v184, 0xbfb8aa3b, v184
	v_mul_f32_e32 v154, 0xbfb8aa3b, v154
	v_exp_f32_e32 v153, v153
	v_exp_f32_e32 v155, v155
	v_mul_f32_e32 v185, 0xbfb8aa3b, v185
	v_mul_f32_e32 v186, 0xbfb8aa3b, v186
	v_mul_f32_e32 v187, 0xbfb8aa3b, v187
	v_mul_f32_e32 v188, 0xbfb8aa3b, v188
	v_mul_f32_e32 v189, 0xbfb8aa3b, v189
	v_exp_f32_e32 v158, v158
	v_exp_f32_e32 v159, v159
	v_exp_f32_e32 v160, v160
	v_exp_f32_e32 v161, v161
	v_exp_f32_e32 v168, v168
	v_exp_f32_e32 v183, v183
	v_exp_f32_e32 v184, v184
	v_exp_f32_e32 v154, v154
	v_exp_f32_e32 v185, v185
	v_exp_f32_e32 v186, v186
	v_exp_f32_e32 v187, v187
	v_exp_f32_e32 v188, v188
	v_exp_f32_e32 v189, v189
	v_add_f32_e32 v152, 1.0, v152
	v_add_f32_e32 v153, 1.0, v153
	v_add_f32_e32 v155, 1.0, v155
	v_rcp_f32_e32 v152, v152
	v_add_f32_e32 v158, 1.0, v158
	v_add_f32_e32 v159, 1.0, v159
	v_add_f32_e32 v160, 1.0, v160
	v_add_f32_e32 v161, 1.0, v161
	v_add_f32_e32 v168, 1.0, v168
	v_add_f32_e32 v183, 1.0, v183
	v_add_f32_e32 v184, 1.0, v184
	v_add_f32_e32 v154, 1.0, v154
	v_rcp_f32_e32 v153, v153
	v_rcp_f32_e32 v155, v155
	v_cvt_pk_bf16_f32 v152, v152, v153
	v_add_f32_e32 v185, 1.0, v185
	v_add_f32_e32 v186, 1.0, v186
	v_add_f32_e32 v187, 1.0, v187
	v_add_f32_e32 v188, 1.0, v188
	v_add_f32_e32 v189, 1.0, v189
	v_rcp_f32_e32 v158, v158
	v_rcp_f32_e32 v159, v159
	v_rcp_f32_e32 v160, v160
	v_rcp_f32_e32 v161, v161
	v_rcp_f32_e32 v168, v168
	v_rcp_f32_e32 v183, v183
	v_rcp_f32_e32 v184, v184
	v_rcp_f32_e32 v190, v154
	v_cvt_pk_bf16_f32 v153, v155, v158
	v_cvt_pk_bf16_f32 v154, v159, v160
	v_cvt_pk_bf16_f32 v155, v161, v168
	global_store_dwordx4 v[156:157], v[152:155], off
	v_rcp_f32_e32 v185, v185
	v_rcp_f32_e32 v186, v186
	v_cvt_pk_bf16_f32 v152, v183, v184
	v_rcp_f32_e32 v187, v187
	v_rcp_f32_e32 v188, v188
	v_rcp_f32_e32 v189, v189
	v_cvt_pk_bf16_f32 v153, v185, v186
	v_cvt_pk_bf16_f32 v154, v187, v188
	v_cvt_pk_bf16_f32 v155, v189, v190
	global_store_dwordx4 v[156:157], v[152:155], off offset:256
	s_nop 1
	v_or_b32_e32 v152, 48, v182
	v_ashrrev_i32_e32 v153, 31, v152
	v_lshl_add_u64 v[154:155], v[152:153], 2, s[40:41]
	s_nop 0
	v_lshlrev_b64 v[152:153], 12, v[152:153]
	v_lshl_add_u64 v[152:153], s[94:95], 0, v[152:153]
	s_waitcnt vmcnt(7)
; __device__ __forceinline__ unsigned cvt_pk_bf16(float lo, float hi) { unsigned r; asm volatile("v_cvt_pk_bf16_f32 %0, %1, %2" : "=v"(r) : "v"(lo), "v"(hi)); return r; }
; __device__ __forceinline__ float sigmoid_f(float x) { return __builtin_amdgcn_rcpf(1.f + __builtin_amdgcn_exp2f(-1.4426950408889634f * x)); }
;     __device__ __forceinline__ void operator()(const f32x4 (&acc)[2][2][4][2], const Unit& u, int wr, int wc, int fr, int fq) const {
;     ...
;             for (int ai = 0; ai < 2; ++ai)
; #pragma unroll
;                 for (int m = 0; m < 4; ++m) {
;                     const int row = row0 + ai * HALF + m * 16; const float r = __builtin_amdgcn_rsqf(rss[row] * (1.f / 1024.f) + NEPS);
; #pragma unroll
;                     for (int bj = 0; bj < 2; ++bj) {
;                         float o[8];
; #pragma unroll
;                         for (int n = 0; n < 2; ++n)
; #pragma unroll
;                             for (int e = 0; e < 4; ++e) o[4 * n + e] = sigmoid_f(acc[ai][bj][m][n][e] * r + bv[bj][n][e]);
;                         u32x4 w; w.x = cvt_pk_bf16(o[0], o[1]); w.y = cvt_pk_bf16(o[2], o[3]); w.z = cvt_pk_bf16(o[4], o[5]); w.w = cvt_pk_bf16(o[6], o[7]);
;                         *(u32x4*)(G + (size_t)row * 2048 + col0 + bj * HALF) = w;
;                     }
	v_mov_b32_e32 v154, v239
	v_fmamk_f32 v154, v154, 0x3a800000, v212
	v_rsq_f32_e32 v156, v154
	v_lshl_add_u64 v[154:155], v[152:153], 0, v[150:151]
	v_fma_f32 v150, v78, v156, v142
	v_fma_f32 v151, v79, v156, v143
	v_fma_f32 v152, v80, v156, v144
	v_fma_f32 v153, v81, v156, v145
	v_fma_f32 v157, v74, v156, v138
	v_fma_f32 v158, v75, v156, v139
	v_fma_f32 v159, v76, v156, v140
	v_fma_f32 v160, v77, v156, v141
	v_mul_f32_e32 v150, 0xbfb8aa3b, v150
	v_mul_f32_e32 v151, 0xbfb8aa3b, v151
	v_mul_f32_e32 v152, 0xbfb8aa3b, v152
	v_mul_f32_e32 v153, 0xbfb8aa3b, v153
	v_fma_f32 v161, v70, v156, v134
	v_fma_f32 v168, v71, v156, v135
	v_fma_f32 v183, v72, v156, v136
	v_fma_f32 v184, v73, v156, v137
	v_fma_f32 v185, v66, v156, v130
	v_fma_f32 v186, v67, v156, v131
	v_fma_f32 v187, v68, v156, v132
	v_fma_f32 v156, v69, v156, v133
	v_mul_f32_e32 v157, 0xbfb8aa3b, v157
	v_mul_f32_e32 v158, 0xbfb8aa3b, v158
	v_mul_f32_e32 v159, 0xbfb8aa3b, v159
	v_mul_f32_e32 v160, 0xbfb8aa3b, v160
	v_exp_f32_e32 v150, v150
	v_exp_f32_e32 v151, v151
	v_exp_f32_e32 v152, v152
	v_exp_f32_e32 v153, v153
	v_mul_f32_e32 v161, 0xbfb8aa3b, v161
	v_mul_f32_e32 v168, 0xbfb8aa3b, v168
	v_mul_f32_e32 v183, 0xbfb8aa3b, v183
	v_mul_f32_e32 v184, 0xbfb8aa3b, v184
	v_mul_f32_e32 v185, 0xbfb8aa3b, v185
	v_mul_f32_e32 v186, 0xbfb8aa3b, v186
	v_mul_f32_e32 v187, 0xbfb8aa3b, v187
	v_mul_f32_e32 v156, 0xbfb8aa3b, v156
	v_exp_f32_e32 v157, v157
	v_exp_f32_e32 v158, v158
	v_exp_f32_e32 v159, v159
	v_exp_f32_e32 v160, v160
	v_exp_f32_e32 v161, v161
	v_exp_f32_e32 v168, v168
	v_exp_f32_e32 v183, v183
	v_exp_f32_e32 v184, v184
	v_exp_f32_e32 v185, v185
	v_exp_f32_e32 v186, v186
	v_exp_f32_e32 v187, v187
	v_exp_f32_e32 v156, v156
	v_add_f32_e32 v150, 1.0, v150
	v_add_f32_e32 v151, 1.0, v151
	v_add_f32_e32 v152, 1.0, v152
	v_add_f32_e32 v153, 1.0, v153
	v_add_f32_e32 v157, 1.0, v157
	v_add_f32_e32 v158, 1.0, v158
	v_add_f32_e32 v159, 1.0, v159
	v_add_f32_e32 v160, 1.0, v160
	v_rcp_f32_e32 v150, v150
	v_rcp_f32_e32 v151, v151
	v_rcp_f32_e32 v152, v152
	v_rcp_f32_e32 v153, v153
	v_add_f32_e32 v161, 1.0, v161
	v_add_f32_e32 v168, 1.0, v168
	v_add_f32_e32 v183, 1.0, v183
	v_add_f32_e32 v184, 1.0, v184
	v_add_f32_e32 v185, 1.0, v185
	v_add_f32_e32 v186, 1.0, v186
	v_add_f32_e32 v187, 1.0, v187
	v_add_f32_e32 v156, 1.0, v156
	v_rcp_f32_e32 v157, v157
	v_rcp_f32_e32 v158, v158
	v_rcp_f32_e32 v159, v159
	v_rcp_f32_e32 v160, v160
	v_cvt_pk_bf16_f32 v150, v150, v151
	v_cvt_pk_bf16_f32 v151, v152, v153
	v_cvt_pk_bf16_f32 v152, v157, v158
	v_cvt_pk_bf16_f32 v153, v159, v160
	v_rcp_f32_e32 v161, v161
	v_rcp_f32_e32 v168, v168
	v_rcp_f32_e32 v183, v183
	v_rcp_f32_e32 v184, v184
	v_rcp_f32_e32 v185, v185
	v_rcp_f32_e32 v186, v186
	v_rcp_f32_e32 v187, v187
	v_rcp_f32_e32 v156, v156
	global_store_dwordx4 v[154:155], v[150:153], off
	s_nop 1
	v_cvt_pk_bf16_f32 v150, v161, v168
	v_cvt_pk_bf16_f32 v151, v183, v184
	v_cvt_pk_bf16_f32 v152, v185, v186
	v_cvt_pk_bf16_f32 v153, v187, v156
	global_store_dwordx4 v[154:155], v[150:153], off offset:256
	s_nop 0
	v_add_co_u32_e32 v156, vcc, s0, v148
	v_lshl_add_u64 v[154:155], v[148:149], 0, s[2:3]
	s_nop 0
	v_addc_co_u32_e32 v157, vcc, 0, v149, vcc
	s_mov_b32 s0, 0x90000
	s_mov_b64 s[2:3], 0x90000
	s_waitcnt vmcnt(7)
	v_mov_b32_e32 v150, v240
	v_fmamk_f32 v150, v150, 0x3a800000, v212
	v_rsq_f32_e32 v150, v150
	s_nop 0
	v_fma_f32 v151, v62, v150, v142
	v_fma_f32 v152, v63, v150, v143
	v_fma_f32 v153, v64, v150, v144
	v_fma_f32 v158, v65, v150, v145
	v_fma_f32 v159, v58, v150, v138
	v_fma_f32 v160, v59, v150, v139
	v_fma_f32 v161, v60, v150, v140
	v_fma_f32 v168, v61, v150, v141
	v_fma_f32 v183, v54, v150, v134
	v_fma_f32 v184, v55, v150, v135
	v_fma_f32 v185, v56, v150, v136
	v_fma_f32 v186, v57, v150, v137
	v_fma_f32 v187, v50, v150, v130
	v_fma_f32 v188, v51, v150, v131
	v_fma_f32 v189, v52, v150, v132
	v_fma_f32 v150, v53, v150, v133
	v_mul_f32_e32 v151, 0xbfb8aa3b, v151
	v_mul_f32_e32 v152, 0xbfb8aa3b, v152
	v_mul_f32_e32 v153, 0xbfb8aa3b, v153
	v_mul_f32_e32 v158, 0xbfb8aa3b, v158
	v_mul_f32_e32 v159, 0xbfb8aa3b, v159
	v_mul_f32_e32 v160, 0xbfb8aa3b, v160
	v_mul_f32_e32 v161, 0xbfb8aa3b, v161
	v_mul_f32_e32 v168, 0xbfb8aa3b, v168
	v_mul_f32_e32 v150, 0xbfb8aa3b, v150
	v_exp_f32_e32 v151, v151
	v_exp_f32_e32 v152, v152
	v_exp_f32_e32 v153, v153
	v_mul_f32_e32 v183, 0xbfb8aa3b, v183
	v_mul_f32_e32 v184, 0xbfb8aa3b, v184
	v_mul_f32_e32 v185, 0xbfb8aa3b, v185
	v_mul_f32_e32 v186, 0xbfb8aa3b, v186
	v_mul_f32_e32 v187, 0xbfb8aa3b, v187
	v_mul_f32_e32 v188, 0xbfb8aa3b, v188
	v_mul_f32_e32 v189, 0xbfb8aa3b, v189
	v_exp_f32_e32 v158, v158
	v_exp_f32_e32 v159, v159
	v_exp_f32_e32 v160, v160
	v_exp_f32_e32 v161, v161
	v_exp_f32_e32 v168, v168
	v_exp_f32_e32 v150, v150
	v_exp_f32_e32 v183, v183
	v_exp_f32_e32 v184, v184
	v_exp_f32_e32 v185, v185
	v_exp_f32_e32 v186, v186
	v_exp_f32_e32 v187, v187
	v_exp_f32_e32 v188, v188
	v_exp_f32_e32 v189, v189
	v_add_f32_e32 v151, 1.0, v151
	v_add_f32_e32 v152, 1.0, v152
	v_add_f32_e32 v153, 1.0, v153
	v_add_f32_e32 v158, 1.0, v158
	v_add_f32_e32 v159, 1.0, v159
	v_add_f32_e32 v160, 1.0, v160
	v_add_f32_e32 v161, 1.0, v161
	v_add_f32_e32 v168, 1.0, v168
	v_add_f32_e32 v150, 1.0, v150
	v_rcp_f32_e32 v151, v151
	v_rcp_f32_e32 v152, v152
	v_rcp_f32_e32 v153, v153
	v_add_f32_e32 v183, 1.0, v183
	v_add_f32_e32 v184, 1.0, v184
	v_add_f32_e32 v185, 1.0, v185
	v_add_f32_e32 v186, 1.0, v186
	v_add_f32_e32 v187, 1.0, v187
	v_add_f32_e32 v188, 1.0, v188
	v_add_f32_e32 v189, 1.0, v189
	v_rcp_f32_e32 v158, v158
	v_rcp_f32_e32 v159, v159
	v_rcp_f32_e32 v160, v160
	v_rcp_f32_e32 v161, v161
	v_rcp_f32_e32 v168, v168
	v_rcp_f32_e32 v190, v150
	v_cvt_pk_bf16_f32 v150, v151, v152
	v_cvt_pk_bf16_f32 v151, v153, v158
	v_cvt_pk_bf16_f32 v152, v159, v160
	v_cvt_pk_bf16_f32 v153, v161, v168
	v_rcp_f32_e32 v183, v183
	v_rcp_f32_e32 v184, v184
	v_rcp_f32_e32 v185, v185
	v_rcp_f32_e32 v186, v186
	v_rcp_f32_e32 v187, v187
	v_rcp_f32_e32 v188, v188
	v_rcp_f32_e32 v189, v189
	global_store_dwordx4 v[156:157], v[150:153], off
	v_add_co_u32_e32 v156, vcc, s0, v148
	s_nop 0
	v_cvt_pk_bf16_f32 v150, v183, v184
	v_cvt_pk_bf16_f32 v151, v185, v186
	v_cvt_pk_bf16_f32 v152, v187, v188
	v_cvt_pk_bf16_f32 v153, v189, v190
	global_store_dwordx4 v[154:155], v[150:153], off offset:256
	s_nop 0
	v_lshl_add_u64 v[154:155], v[148:149], 0, s[2:3]
	v_addc_co_u32_e32 v157, vcc, 0, v149, vcc
	s_mov_b32 s0, 0xa0000
	s_mov_b64 s[2:3], 0xa0000
	s_waitcnt vmcnt(7)
; __device__ __forceinline__ unsigned cvt_pk_bf16(float lo, float hi) { unsigned r; asm volatile("v_cvt_pk_bf16_f32 %0, %1, %2" : "=v"(r) : "v"(lo), "v"(hi)); return r; }
; __device__ __forceinline__ float sigmoid_f(float x) { return __builtin_amdgcn_rcpf(1.f + __builtin_amdgcn_exp2f(-1.4426950408889634f * x)); }
;     __device__ __forceinline__ void operator()(const f32x4 (&acc)[2][2][4][2], const Unit& u, int wr, int wc, int fr, int fq) const {
;     ...
;             for (int ai = 0; ai < 2; ++ai)
; #pragma unroll
;                 for (int m = 0; m < 4; ++m) {
;                     const int row = row0 + ai * HALF + m * 16; const float r = __builtin_amdgcn_rsqf(rss[row] * (1.f / 1024.f) + NEPS);
; #pragma unroll
;                     for (int bj = 0; bj < 2; ++bj) {
;                         float o[8];
; #pragma unroll
;                         for (int n = 0; n < 2; ++n)
; #pragma unroll
;                             for (int e = 0; e < 4; ++e) o[4 * n + e] = sigmoid_f(acc[ai][bj][m][n][e] * r + bv[bj][n][e]);
;                         u32x4 w; w.x = cvt_pk_bf16(o[0], o[1]); w.y = cvt_pk_bf16(o[2], o[3]); w.z = cvt_pk_bf16(o[4], o[5]); w.w = cvt_pk_bf16(o[6], o[7]);
;                         *(u32x4*)(G + (size_t)row * 2048 + col0 + bj * HALF) = w;
;                     }
	v_mov_b32_e32 v150, v241
	v_fmamk_f32 v150, v150, 0x3a800000, v212
	v_rsq_f32_e32 v150, v150
	s_nop 0
	v_fma_f32 v151, v46, v150, v142
	v_fma_f32 v152, v47, v150, v143
	v_fma_f32 v153, v48, v150, v144
	v_fma_f32 v158, v49, v150, v145
	v_fma_f32 v159, v42, v150, v138
	v_fma_f32 v160, v43, v150, v139
	v_fma_f32 v161, v44, v150, v140
	v_fma_f32 v168, v45, v150, v141
	v_fma_f32 v183, v38, v150, v134
	v_fma_f32 v184, v39, v150, v135
	v_fma_f32 v185, v40, v150, v136
	v_fma_f32 v186, v41, v150, v137
	v_fma_f32 v187, v34, v150, v130
	v_fma_f32 v188, v35, v150, v131
	v_fma_f32 v189, v36, v150, v132
	v_fma_f32 v150, v37, v150, v133
	v_mul_f32_e32 v151, 0xbfb8aa3b, v151
	v_mul_f32_e32 v152, 0xbfb8aa3b, v152
	v_mul_f32_e32 v153, 0xbfb8aa3b, v153
	v_mul_f32_e32 v158, 0xbfb8aa3b, v158
	v_mul_f32_e32 v159, 0xbfb8aa3b, v159
	v_mul_f32_e32 v160, 0xbfb8aa3b, v160
	v_mul_f32_e32 v161, 0xbfb8aa3b, v161
	v_mul_f32_e32 v168, 0xbfb8aa3b, v168
	v_mul_f32_e32 v150, 0xbfb8aa3b, v150
	v_exp_f32_e32 v151, v151
	v_exp_f32_e32 v152, v152
	v_exp_f32_e32 v153, v153
	v_mul_f32_e32 v183, 0xbfb8aa3b, v183
	v_mul_f32_e32 v184, 0xbfb8aa3b, v184
	v_mul_f32_e32 v185, 0xbfb8aa3b, v185
	v_mul_f32_e32 v186, 0xbfb8aa3b, v186
	v_mul_f32_e32 v187, 0xbfb8aa3b, v187
	v_mul_f32_e32 v188, 0xbfb8aa3b, v188
	v_mul_f32_e32 v189, 0xbfb8aa3b, v189
	v_exp_f32_e32 v158, v158
	v_exp_f32_e32 v159, v159
	v_exp_f32_e32 v160, v160
	v_exp_f32_e32 v161, v161
	v_exp_f32_e32 v168, v168
	v_exp_f32_e32 v150, v150
	v_exp_f32_e32 v183, v183
	v_exp_f32_e32 v184, v184
	v_exp_f32_e32 v185, v185
	v_exp_f32_e32 v186, v186
	v_exp_f32_e32 v187, v187
	v_exp_f32_e32 v188, v188
	v_exp_f32_e32 v189, v189
	v_add_f32_e32 v151, 1.0, v151
	v_add_f32_e32 v152, 1.0, v152
	v_add_f32_e32 v153, 1.0, v153
	v_add_f32_e32 v158, 1.0, v158
	v_add_f32_e32 v159, 1.0, v159
	v_add_f32_e32 v160, 1.0, v160
	v_add_f32_e32 v161, 1.0, v161
	v_add_f32_e32 v168, 1.0, v168
	v_add_f32_e32 v150, 1.0, v150
	v_rcp_f32_e32 v151, v151
	v_rcp_f32_e32 v152, v152
	v_rcp_f32_e32 v153, v153
	v_add_f32_e32 v183, 1.0, v183
	v_add_f32_e32 v184, 1.0, v184
	v_add_f32_e32 v185, 1.0, v185
	v_add_f32_e32 v186, 1.0, v186
	v_add_f32_e32 v187, 1.0, v187
	v_add_f32_e32 v188, 1.0, v188
	v_add_f32_e32 v189, 1.0, v189
	v_rcp_f32_e32 v158, v158
	v_rcp_f32_e32 v159, v159
	v_rcp_f32_e32 v160, v160
	v_rcp_f32_e32 v161, v161
	v_rcp_f32_e32 v168, v168
	v_rcp_f32_e32 v190, v150
	v_cvt_pk_bf16_f32 v150, v151, v152
	v_cvt_pk_bf16_f32 v151, v153, v158
	v_cvt_pk_bf16_f32 v152, v159, v160
	v_cvt_pk_bf16_f32 v153, v161, v168
	v_rcp_f32_e32 v183, v183
	v_rcp_f32_e32 v184, v184
	v_rcp_f32_e32 v185, v185
	v_rcp_f32_e32 v186, v186
	v_rcp_f32_e32 v187, v187
	v_rcp_f32_e32 v188, v188
	v_rcp_f32_e32 v189, v189
	global_store_dwordx4 v[156:157], v[150:153], off
	v_add_co_u32_e32 v156, vcc, s0, v148
	s_nop 0
	v_cvt_pk_bf16_f32 v150, v183, v184
	v_cvt_pk_bf16_f32 v151, v185, v186
	v_cvt_pk_bf16_f32 v152, v187, v188
	v_cvt_pk_bf16_f32 v153, v189, v190
	global_store_dwordx4 v[154:155], v[150:153], off offset:256
	s_nop 0
	v_lshl_add_u64 v[154:155], v[148:149], 0, s[2:3]
	v_addc_co_u32_e32 v157, vcc, 0, v149, vcc
	s_mov_b64 s[2:3], 0xb0000
	s_mov_b32 s0, 0xb0000
	s_waitcnt vmcnt(7)
; __device__ __forceinline__ unsigned cvt_pk_bf16(float lo, float hi) { unsigned r; asm volatile("v_cvt_pk_bf16_f32 %0, %1, %2" : "=v"(r) : "v"(lo), "v"(hi)); return r; }
; __device__ __forceinline__ float sigmoid_f(float x) { return __builtin_amdgcn_rcpf(1.f + __builtin_amdgcn_exp2f(-1.4426950408889634f * x)); }
;     __device__ __forceinline__ void operator()(const f32x4 (&acc)[2][2][4][2], const Unit& u, int wr, int wc, int fr, int fq) const {
;     ...
;             for (int ai = 0; ai < 2; ++ai)
; #pragma unroll
;                 for (int m = 0; m < 4; ++m) {
;                     const int row = row0 + ai * HALF + m * 16; const float r = __builtin_amdgcn_rsqf(rss[row] * (1.f / 1024.f) + NEPS);
; #pragma unroll
;                     for (int bj = 0; bj < 2; ++bj) {
;                         float o[8];
; #pragma unroll
;                         for (int n = 0; n < 2; ++n)
; #pragma unroll
;                             for (int e = 0; e < 4; ++e) o[4 * n + e] = sigmoid_f(acc[ai][bj][m][n][e] * r + bv[bj][n][e]);
;                         u32x4 w; w.x = cvt_pk_bf16(o[0], o[1]); w.y = cvt_pk_bf16(o[2], o[3]); w.z = cvt_pk_bf16(o[4], o[5]); w.w = cvt_pk_bf16(o[6], o[7]);
;                         *(u32x4*)(G + (size_t)row * 2048 + col0 + bj * HALF) = w;
;                     }
	v_mov_b32_e32 v150, v242
	v_fmamk_f32 v150, v150, 0x3a800000, v212
	v_rsq_f32_e32 v150, v150
	s_nop 0
	v_fma_f32 v151, v30, v150, v142
	v_fma_f32 v152, v31, v150, v143
	v_fma_f32 v153, v32, v150, v144
	v_fma_f32 v158, v33, v150, v145
	v_fma_f32 v159, v26, v150, v138
	v_fma_f32 v160, v27, v150, v139
	v_fma_f32 v161, v28, v150, v140
	v_fma_f32 v168, v29, v150, v141
	v_fma_f32 v183, v22, v150, v134
	v_fma_f32 v184, v23, v150, v135
	v_fma_f32 v185, v24, v150, v136
	v_fma_f32 v186, v25, v150, v137
	v_fma_f32 v187, v18, v150, v130
	v_fma_f32 v188, v19, v150, v131
	v_fma_f32 v189, v20, v150, v132
	v_fma_f32 v150, v21, v150, v133
	v_mul_f32_e32 v151, 0xbfb8aa3b, v151
	v_mul_f32_e32 v152, 0xbfb8aa3b, v152
	v_mul_f32_e32 v153, 0xbfb8aa3b, v153
	v_mul_f32_e32 v158, 0xbfb8aa3b, v158
	v_mul_f32_e32 v159, 0xbfb8aa3b, v159
	v_mul_f32_e32 v160, 0xbfb8aa3b, v160
	v_mul_f32_e32 v161, 0xbfb8aa3b, v161
	v_mul_f32_e32 v168, 0xbfb8aa3b, v168
	v_mul_f32_e32 v150, 0xbfb8aa3b, v150
	v_exp_f32_e32 v151, v151
	v_exp_f32_e32 v152, v152
	v_exp_f32_e32 v153, v153
	v_mul_f32_e32 v183, 0xbfb8aa3b, v183
	v_mul_f32_e32 v184, 0xbfb8aa3b, v184
	v_mul_f32_e32 v185, 0xbfb8aa3b, v185
	v_mul_f32_e32 v186, 0xbfb8aa3b, v186
	v_mul_f32_e32 v187, 0xbfb8aa3b, v187
	v_mul_f32_e32 v188, 0xbfb8aa3b, v188
	v_mul_f32_e32 v189, 0xbfb8aa3b, v189
	v_exp_f32_e32 v158, v158
	v_exp_f32_e32 v159, v159
	v_exp_f32_e32 v160, v160
	v_exp_f32_e32 v161, v161
	v_exp_f32_e32 v168, v168
	v_exp_f32_e32 v150, v150
	v_exp_f32_e32 v183, v183
	v_exp_f32_e32 v184, v184
	v_exp_f32_e32 v185, v185
	v_exp_f32_e32 v186, v186
	v_exp_f32_e32 v187, v187
	v_exp_f32_e32 v188, v188
	v_exp_f32_e32 v189, v189
	v_add_f32_e32 v151, 1.0, v151
	v_add_f32_e32 v152, 1.0, v152
	v_add_f32_e32 v153, 1.0, v153
	v_add_f32_e32 v158, 1.0, v158
	v_add_f32_e32 v159, 1.0, v159
	v_add_f32_e32 v160, 1.0, v160
	v_add_f32_e32 v161, 1.0, v161
	v_add_f32_e32 v168, 1.0, v168
	v_add_f32_e32 v150, 1.0, v150
	v_rcp_f32_e32 v151, v151
	v_rcp_f32_e32 v152, v152
	v_rcp_f32_e32 v153, v153
	v_add_f32_e32 v183, 1.0, v183
	v_add_f32_e32 v184, 1.0, v184
	v_add_f32_e32 v185, 1.0, v185
	v_add_f32_e32 v186, 1.0, v186
	v_add_f32_e32 v187, 1.0, v187
	v_add_f32_e32 v188, 1.0, v188
	v_add_f32_e32 v189, 1.0, v189
	v_rcp_f32_e32 v158, v158
	v_rcp_f32_e32 v159, v159
	v_rcp_f32_e32 v160, v160
	v_rcp_f32_e32 v161, v161
	v_rcp_f32_e32 v168, v168
	v_rcp_f32_e32 v190, v150
	v_cvt_pk_bf16_f32 v150, v151, v152
	v_cvt_pk_bf16_f32 v151, v153, v158
	v_cvt_pk_bf16_f32 v152, v159, v160
	v_cvt_pk_bf16_f32 v153, v161, v168
	v_rcp_f32_e32 v183, v183
	v_rcp_f32_e32 v184, v184
	v_rcp_f32_e32 v185, v185
	v_rcp_f32_e32 v186, v186
	v_rcp_f32_e32 v187, v187
	v_rcp_f32_e32 v188, v188
	v_rcp_f32_e32 v189, v189
	global_store_dwordx4 v[156:157], v[150:153], off
	s_nop 1
	v_cvt_pk_bf16_f32 v150, v183, v184
	v_cvt_pk_bf16_f32 v151, v185, v186
	v_cvt_pk_bf16_f32 v152, v187, v188
	v_cvt_pk_bf16_f32 v153, v189, v190
	global_store_dwordx4 v[154:155], v[150:153], off offset:256
	s_nop 0
	v_lshl_add_u64 v[146:147], v[148:149], 0, s[2:3]
	v_add_co_u32_e32 v148, vcc, s0, v148
	s_mov_b64 s[2:3], 0
	s_nop 0
	v_addc_co_u32_e32 v149, vcc, 0, v149, vcc
	s_waitcnt vmcnt(7)
	v_mov_b32_e32 v150, v243
	v_fmamk_f32 v150, v150, 0x3a800000, v212
	v_rsq_f32_e32 v150, v150
	s_nop 0
	v_fma_f32 v142, v14, v150, v142
	v_fma_f32 v143, v15, v150, v143
	v_fma_f32 v144, v16, v150, v144
	v_fmac_f32_e32 v145, v17, v150
	v_fma_f32 v138, v10, v150, v138
	v_fma_f32 v139, v11, v150, v139
	v_fma_f32 v140, v12, v150, v140
	v_fmac_f32_e32 v141, v13, v150
	v_fma_f32 v130, v2, v150, v130
	v_fma_f32 v131, v3, v150, v131
	v_fma_f32 v132, v4, v150, v132
	v_fmac_f32_e32 v133, v5, v150
	v_fma_f32 v134, v6, v150, v134
	v_fma_f32 v135, v7, v150, v135
	v_fma_f32 v136, v8, v150, v136
	v_fmac_f32_e32 v137, v9, v150
	v_mul_f32_e32 v142, 0xbfb8aa3b, v142
	v_mul_f32_e32 v143, 0xbfb8aa3b, v143
	v_mul_f32_e32 v144, 0xbfb8aa3b, v144
	v_mul_f32_e32 v145, 0xbfb8aa3b, v145
	v_mul_f32_e32 v138, 0xbfb8aa3b, v138
	v_mul_f32_e32 v139, 0xbfb8aa3b, v139
	v_mul_f32_e32 v140, 0xbfb8aa3b, v140
	v_mul_f32_e32 v141, 0xbfb8aa3b, v141
	v_mul_f32_e32 v130, 0xbfb8aa3b, v130
	v_mul_f32_e32 v131, 0xbfb8aa3b, v131
	v_mul_f32_e32 v132, 0xbfb8aa3b, v132
	v_mul_f32_e32 v133, 0xbfb8aa3b, v133
	v_mul_f32_e32 v134, 0xbfb8aa3b, v134
	v_mul_f32_e32 v135, 0xbfb8aa3b, v135
	v_mul_f32_e32 v136, 0xbfb8aa3b, v136
	v_mul_f32_e32 v137, 0xbfb8aa3b, v137
	v_exp_f32_e32 v142, v142
	v_exp_f32_e32 v143, v143
	v_exp_f32_e32 v144, v144
	v_exp_f32_e32 v145, v145
	v_exp_f32_e32 v138, v138
	v_exp_f32_e32 v139, v139
	v_exp_f32_e32 v140, v140
	v_exp_f32_e32 v141, v141
	v_exp_f32_e32 v130, v130
	v_exp_f32_e32 v131, v131
	v_exp_f32_e32 v132, v132
	v_exp_f32_e32 v133, v133
	v_exp_f32_e32 v134, v134
	v_exp_f32_e32 v135, v135
	v_exp_f32_e32 v136, v136
	v_exp_f32_e32 v137, v137
	v_add_f32_e32 v142, 1.0, v142
	v_add_f32_e32 v143, 1.0, v143
	v_add_f32_e32 v144, 1.0, v144
	v_add_f32_e32 v145, 1.0, v145
	v_add_f32_e32 v138, 1.0, v138
	v_add_f32_e32 v139, 1.0, v139
	v_add_f32_e32 v140, 1.0, v140
	v_add_f32_e32 v141, 1.0, v141
	v_add_f32_e32 v130, 1.0, v130
	v_add_f32_e32 v131, 1.0, v131
	v_add_f32_e32 v132, 1.0, v132
	v_add_f32_e32 v133, 1.0, v133
	v_add_f32_e32 v134, 1.0, v134
	v_add_f32_e32 v135, 1.0, v135
	v_add_f32_e32 v136, 1.0, v136
	v_add_f32_e32 v137, 1.0, v137
	v_rcp_f32_e32 v142, v142
	v_rcp_f32_e32 v143, v143
	v_rcp_f32_e32 v144, v144
	v_rcp_f32_e32 v145, v145
	v_rcp_f32_e32 v138, v138
	v_rcp_f32_e32 v139, v139
	v_rcp_f32_e32 v140, v140
	v_rcp_f32_e32 v141, v141
	v_rcp_f32_e32 v150, v130
	v_rcp_f32_e32 v151, v131
	v_rcp_f32_e32 v152, v132
	v_rcp_f32_e32 v153, v133
	v_cvt_pk_bf16_f32 v130, v142, v143
	v_cvt_pk_bf16_f32 v131, v144, v145
	v_cvt_pk_bf16_f32 v132, v138, v139
	v_cvt_pk_bf16_f32 v133, v140, v141
	v_rcp_f32_e32 v134, v134
	v_rcp_f32_e32 v135, v135
	v_rcp_f32_e32 v136, v136
	v_rcp_f32_e32 v137, v137
	global_store_dwordx4 v[148:149], v[130:133], off
	s_nop 1
	v_cvt_pk_bf16_f32 v130, v134, v135
	v_cvt_pk_bf16_f32 v131, v136, v137
	v_cvt_pk_bf16_f32 v132, v150, v151
	v_cvt_pk_bf16_f32 v133, v152, v153
	global_store_dwordx4 v[146:147], v[130:133], off offset:256

;     __device__ __forceinline__ void operator()(const f32x4 (&acc)[2][2][4][2], const Unit& u, int wr, int wc, int fr, int fq) const {
;     ...
;             size_t okp = 17301504, oks = 22867968;
;             for (int gg = 0; gg < g; ++gg) { okp += (size_t)2 * 4 * (128 << (2 * gg)) * 256; oks += (size_t)2 * 128 * (128 << (2 * gg)) * 256; }
;             if (kind == 2) { okp += (size_t)4 * W * 256; oks += (size_t)128 * W * 256; }
; #pragma unroll
;             for (int ai = 0; ai < 2; ++ai)
; #pragma unroll
;                 for (int m = 0; m < 4; ++m) {
;                     const int row = row0 + ai * HALF + m * 16; const float r = __builtin_amdgcn_rsqf(rss[row] * (1.f / 1024.f) + NEPS);
;                     f32x4 v[2][2];
; #pragma unroll
;                     for (int bj = 0; bj < 2; ++bj)
; #pragma unroll
;                         for (int n = 0; n < 2; ++n) v[bj][n] = acc[ai][bj][m][n] * r;
;                     int posidx, b, tt; float* cdst = nullptr;
;                     if (!samp) { tt = row & 4095; b = row >> 12; posidx = tt; if (kind >= 1 && tt >= 4096 - W) cdst = out + okp + ((size_t)(b * W + (tt - (4096 - W))) * 4 + wc) * 64; }
;                     else { const int sr = row - 16384; b = sr >> 2; tt = sr & 3; posidx = 4096 + tt; if (kind >= 1) cdst = out + oks + ((size_t)(b * W + (W - 4 + tt)) * 4 + wc) * 64; }
.LBB0_401:
	v_ashrrev_i32_e32 v183, 31, v182
	v_lshl_add_u64 v[190:191], v[182:183], 2, s[40:41]
	global_load_dword v236, v[190:191], off
	global_load_dword v237, v[190:191], off offset:64
	global_load_dword v238, v[190:191], off offset:128
	global_load_dword v239, v[190:191], off offset:192
	global_load_dword v240, v[190:191], off offset:512
	global_load_dword v241, v[190:191], off offset:576
	global_load_dword v242, v[190:191], off offset:640
	global_load_dword v243, v[190:191], off offset:704
	s_lshl_b32 s31, s11, 1
	s_lshl_b32 s0, 0x80, s31
	s_add_i32 s11, s38, -10
	s_lshl_b64 s[2:3], s[0:1], 10
	s_lshl_b64 s[12:13], s[0:1], 15
	s_cmp_lt_u32 s11, 3
	s_cselect_b32 s61, s13, 0
	s_cselect_b32 s60, s12, 0
	s_cselect_b32 s63, s3, 0
	s_cselect_b32 s62, s2, 0
	s_cmp_lt_u32 s10, 3
	s_cselect_b64 s[2:3], -1, 0
	s_cmp_gt_u32 s10, 2
	s_cselect_b64 s[10:11], -1, 0
	s_add_i32 s31, s31, 7
	s_ashr_i32 s12, s29, 12
	s_add_i32 s46, s0, 0xfffff000
	s_lshl_b32 s47, s12, s31
	s_sub_i32 s97, 0x1000, s0
	s_add_i32 s47, s47, s46
	s_mov_b64 s[12:13], -1
	s_and_b64 vcc, exec, s[54:55]
	s_cbranch_vccz .LBB0_403
	v_and_b32_e32 v168, 0xfcf, v182
	v_cmp_gt_u32_e32 vcc, s97, v168
	s_or_b64 s[12:13], s[2:3], vcc
	s_lshl_b64 s[66:67], s[58:59], 2
	s_add_u32 s68, s48, s66
	v_add_u32_e32 v148, s47, v168
	s_addc_u32 s69, s49, s67
	s_lshl_b64 s[66:67], s[62:63], 2
	v_ashrrev_i32_e32 v149, 31, v148
	s_add_u32 s66, s68, s66
	v_lshlrev_b64 v[148:149], 10, v[148:149]
	s_addc_u32 s67, s69, s67
	v_lshl_add_u64 v[148:149], s[66:67], 0, v[148:149]
	s_lshl_b32 s66, s85, 2
	s_mov_b32 s67, s1
	v_lshl_add_u64 v[148:149], v[148:149], 0, s[66:67]
	v_cndmask_b32_e64 v197, v149, 0, s[12:13]
	v_cndmask_b32_e64 v196, v148, 0, s[12:13]
	s_mov_b64 s[12:13], 0

;     __device__ __forceinline__ void operator()(const f32x4 (&acc)[2][2][4][2], const Unit& u, int wr, int wc, int fr, int fq) const {
;     ...
;                     const int row = row0 + ai * HALF + m * 16; const float r = __builtin_amdgcn_rsqf(rss[row] * (1.f / 1024.f) + NEPS);
;                     f32x4 v[2][2];
; #pragma unroll
;                     for (int bj = 0; bj < 2; ++bj)
; #pragma unroll
;                         for (int n = 0; n < 2; ++n) v[bj][n] = acc[ai][bj][m][n] * r;
;                     int posidx, b, tt; float* cdst = nullptr;
;                     if (!samp) { tt = row & 4095; b = row >> 12; posidx = tt; if (kind >= 1 && tt >= 4096 - W) cdst = out + okp + ((size_t)(b * W + (tt - (4096 - W))) * 4 + wc) * 64; }
;                     else { const int sr = row - 16384; b = sr >> 2; tt = sr & 3; posidx = 4096 + tt; if (kind >= 1) cdst = out + oks + ((size_t)(b * W + (W - 4 + tt)) * 4 + wc) * 64; }
;                     if (kind < 2) {
;                         float ss = 0.f;
; #pragma unroll
;                         for (int bj = 0; bj < 2; ++bj)
; #pragma unroll
;                             for (int n = 0; n < 2; ++n) ss += (v[bj][n][0] * v[bj][n][0] + v[bj][n][1] * v[bj][n][1]) + (v[bj][n][2] * v[bj][n][2] + v[bj][n][3] * v[bj][n][3]);
;                         ss += __shfl_xor(ss, 16); ss += __shfl_xor(ss, 32);
;                         const float rn = __builtin_amdgcn_rsqf(ss * (1.f / 64.f) + NEPS);
; #pragma unroll
;                         for (int bj = 0; bj < 2; ++bj)
; #pragma unroll
;                             for (int n = 0; n < 2; ++n) v[bj][n] = v[bj][n] * rn * gn[bj][n];
;                         if (fq < 2) {
;                             const f32x4 cs = *(const f32x4*)(rot + (size_t)posidx * 16 + 4 * fq), sn = *(const f32x4*)(rot + (size_t)posidx * 16 + 8 + 4 * fq);
;                             const f32x4 x1 = v[0][0], x2 = v[0][1];
;                             v[0][0] = x1 * cs - x2 * sn; v[0][1] = x2 * cs + x1 * sn;
;                         }
.LBB0_407:
	s_waitcnt vmcnt(0)
	v_mov_b32_e32 v146, v236
	v_fmamk_f32 v146, v146, 0x3a800000, v212
	v_rsq_f32_e32 v146, v146
	s_andn2_b64 vcc, exec, s[14:15]
	v_pk_mul_f32 v[160:161], v[128:129], v[146:147] op_sel_hi:[1,0]
	v_pk_mul_f32 v[158:159], v[126:127], v[146:147] op_sel_hi:[1,0]
	v_pk_mul_f32 v[156:157], v[124:125], v[146:147] op_sel_hi:[1,0]
	v_pk_mul_f32 v[154:155], v[122:123], v[146:147] op_sel_hi:[1,0]
	v_pk_mul_f32 v[152:153], v[120:121], v[146:147] op_sel_hi:[1,0]
	v_pk_mul_f32 v[150:151], v[118:119], v[146:147] op_sel_hi:[1,0]
	v_pk_mul_f32 v[148:149], v[116:117], v[146:147] op_sel_hi:[1,0]
	v_cndmask_b32_e64 v147, 0, 1, s[14:15]
	v_cmp_ne_u32_e64 s[12:13], 1, v147
	v_pk_mul_f32 v[146:147], v[114:115], v[146:147] op_sel_hi:[1,0]
	s_cbranch_vccnz .LBB0_412
	v_pk_mul_f32 v[192:193], v[160:161], v[160:161]
	v_pk_mul_f32 v[194:195], v[158:159], v[158:159]
	s_nop 0
	v_pk_mov_b32 v[198:199], v[194:195], v[192:193] op_sel:[1,0]
	v_mov_b32_e32 v195, v193
	v_pk_add_f32 v[192:193], v[198:199], v[194:195]
	v_pk_mul_f32 v[194:195], v[156:157], v[156:157]
	v_pk_add_f32 v[192:193], v[192:193], v[192:193] op_sel_hi:[0,1]
	v_pk_mul_f32 v[198:199], v[154:155], v[154:155]
	v_mul_f32_e32 v192, v150, v150
	v_pk_mov_b32 v[200:201], v[198:199], v[194:195] op_sel:[1,0]
	v_mov_b32_e32 v199, v195
	v_pk_add_f32 v[194:195], v[200:201], v[198:199]
	v_pk_fma_f32 v[198:199], v[150:151], v[150:151], v[192:193] op_sel_hi:[1,1,0]
	v_mul_f32_e32 v192, v152, v152
	v_pk_add_f32 v[194:195], v[194:195], v[194:195] op_sel_hi:[0,1]
	v_pk_fma_f32 v[200:201], v[152:153], v[152:153], v[192:193] op_sel_hi:[1,1,0]
	v_mul_f32_e32 v198, v146, v146
	v_mul_f32_e32 v200, v147, v147
	v_mul_f32_e32 v192, v148, v148
	v_mul_f32_e32 v194, v149, v149
	v_pk_add_f32 v[198:199], v[198:199], v[200:201]
	v_pk_add_f32 v[192:193], v[192:193], v[194:195]
	s_nop 0
	v_pk_add_f32 v[192:193], v[198:199], v[192:193]
	s_nop 0
	v_add_f32_e32 v189, v192, v193
	v_and_b32_e32 v193, 64, v213
	v_xor_b32_e32 v192, 16, v213
	v_add_u32_e32 v193, 64, v193
	v_cmp_lt_i32_e32 vcc, v192, v193
	s_nop 1
	v_cndmask_b32_e32 v192, v213, v192, vcc
	v_lshlrev_b32_e32 v192, 2, v192
	ds_bpermute_b32 v192, v192, v189
	s_waitcnt lgkmcnt(0)
	v_add_f32_e32 v189, v189, v192
	v_xor_b32_e32 v192, 32, v213
	v_cmp_lt_i32_e32 vcc, v192, v193
	s_nop 1
	v_cndmask_b32_e32 v192, v213, v192, vcc
	v_lshlrev_b32_e32 v192, 2, v192
	ds_bpermute_b32 v192, v192, v189
	s_waitcnt lgkmcnt(0)
	v_add_f32_e32 v189, v189, v192
	v_fmamk_f32 v189, v189, 0x3c800000, v212
	v_rsq_f32_e32 v192, v189
	s_nop 0
	v_pk_mul_f32 v[158:159], v[158:159], v[192:193] op_sel_hi:[1,0]
	v_pk_mul_f32 v[160:161], v[160:161], v[192:193] op_sel_hi:[1,0]
	v_pk_mul_f32 v[154:155], v[154:155], v[192:193] op_sel_hi:[1,0]
	v_pk_mul_f32 v[156:157], v[156:157], v[192:193] op_sel_hi:[1,0]
	v_pk_mul_f32 v[160:161], v[144:145], v[160:161]
	v_pk_mul_f32 v[158:159], v[142:143], v[158:159]
	v_pk_mul_f32 v[156:157], v[140:141], v[156:157]
	v_pk_mul_f32 v[154:155], v[138:139], v[154:155]
	s_and_saveexec_b64 s[14:15], s[6:7]
	s_cbranch_execz .LBB0_410
	v_lshlrev_b64 v[194:195], 6, v[168:169]
	v_lshl_add_u64 v[194:195], v[174:175], 0, v[194:195]
	global_load_dwordx4 v[198:201], v[194:195], off offset:32
	global_load_dwordx4 v[216:219], v[194:195], off
	s_waitcnt vmcnt(1)
	v_pk_mul_f32 v[194:195], v[156:157], v[200:201]
	v_pk_mul_f32 v[202:203], v[154:155], v[198:199]
	v_pk_mul_f32 v[200:201], v[160:161], v[200:201]
	v_pk_mul_f32 v[198:199], v[158:159], v[198:199]
	s_waitcnt vmcnt(0)
	v_pk_fma_f32 v[160:161], v[160:161], v[218:219], v[194:195] neg_lo:[0,0,1] neg_hi:[0,0,1]
	v_pk_fma_f32 v[158:159], v[158:159], v[216:217], v[202:203] neg_lo:[0,0,1] neg_hi:[0,0,1]
	v_pk_fma_f32 v[156:157], v[156:157], v[218:219], v[200:201]
	v_pk_fma_f32 v[154:155], v[154:155], v[216:217], v[198:199]

;     __device__ __forceinline__ void operator()(const f32x4 (&acc)[2][2][4][2], const Unit& u, int wr, int wc, int fr, int fq) const {
;     ...
;                     const int row = row0 + ai * HALF + m * 16; const float r = __builtin_amdgcn_rsqf(rss[row] * (1.f / 1024.f) + NEPS);
;                     f32x4 v[2][2];
; #pragma unroll
;                     for (int bj = 0; bj < 2; ++bj)
; #pragma unroll
;                         for (int n = 0; n < 2; ++n) v[bj][n] = acc[ai][bj][m][n] * r;
;                     int posidx, b, tt; float* cdst = nullptr;
;                     if (!samp) { tt = row & 4095; b = row >> 12; posidx = tt; if (kind >= 1 && tt >= 4096 - W) cdst = out + okp + ((size_t)(b * W + (tt - (4096 - W))) * 4 + wc) * 64; }
;                     else { const int sr = row - 16384; b = sr >> 2; tt = sr & 3; posidx = 4096 + tt; if (kind >= 1) cdst = out + oks + ((size_t)(b * W + (W - 4 + tt)) * 4 + wc) * 64; }
.LBB0_420:
	s_or_b64 exec, exec, s[14:15]
	v_or_b32_e32 v198, 16, v182
	v_ashrrev_i32_e32 v199, 31, v198
	v_lshl_add_u64 v[146:147], v[198:199], 2, s[40:41]
	s_nop 0
	v_cndmask_b32_e64 v147, 0, 1, s[54:55]
	v_cmp_ne_u32_e64 s[14:15], 1, v147
	s_andn2_b64 vcc, exec, s[54:55]
	s_mov_b64 s[66:67], -1
	s_cbranch_vccnz .LBB0_422
	v_and_b32_e32 v200, 0xfdf, v198
	v_cmp_gt_u32_e32 vcc, s97, v200
	s_or_b64 s[66:67], s[2:3], vcc
	s_lshl_b64 vcc, s[58:59], 2
	s_add_u32 s0, s48, vcc_lo
	v_add_u32_e32 v148, s47, v200
	s_addc_u32 s68, s49, vcc_hi
	s_lshl_b64 vcc, s[62:63], 2
	v_ashrrev_i32_e32 v149, 31, v148
	s_add_u32 vcc_lo, s0, vcc_lo
	v_lshlrev_b64 v[148:149], 10, v[148:149]
	s_addc_u32 vcc_hi, s68, vcc_hi
	v_lshl_add_u64 v[148:149], vcc, 0, v[148:149]
	s_lshl_b32 s0, s85, 2
	v_lshl_add_u64 v[148:149], v[148:149], 0, s[0:1]
	v_cndmask_b32_e64 v197, v149, 0, s[66:67]
	v_cndmask_b32_e64 v196, v148, 0, s[66:67]
	s_mov_b64 s[66:67], 0

;     __device__ __forceinline__ void operator()(const f32x4 (&acc)[2][2][4][2], const Unit& u, int wr, int wc, int fr, int fq) const {
;     ...
;                     const int row = row0 + ai * HALF + m * 16; const float r = __builtin_amdgcn_rsqf(rss[row] * (1.f / 1024.f) + NEPS);
;                     f32x4 v[2][2];
; #pragma unroll
;                     for (int bj = 0; bj < 2; ++bj)
; #pragma unroll
;                         for (int n = 0; n < 2; ++n) v[bj][n] = acc[ai][bj][m][n] * r;
;                     int posidx, b, tt; float* cdst = nullptr;
;                     if (!samp) { tt = row & 4095; b = row >> 12; posidx = tt; if (kind >= 1 && tt >= 4096 - W) cdst = out + okp + ((size_t)(b * W + (tt - (4096 - W))) * 4 + wc) * 64; }
;                     else { const int sr = row - 16384; b = sr >> 2; tt = sr & 3; posidx = 4096 + tt; if (kind >= 1) cdst = out + oks + ((size_t)(b * W + (W - 4 + tt)) * 4 + wc) * 64; }
;                     if (kind < 2) {
;                         float ss = 0.f;
; #pragma unroll
;                         for (int bj = 0; bj < 2; ++bj)
; #pragma unroll
;                             for (int n = 0; n < 2; ++n) ss += (v[bj][n][0] * v[bj][n][0] + v[bj][n][1] * v[bj][n][1]) + (v[bj][n][2] * v[bj][n][2] + v[bj][n][3] * v[bj][n][3]);
;                         ss += __shfl_xor(ss, 16); ss += __shfl_xor(ss, 32);
;                         const float rn = __builtin_amdgcn_rsqf(ss * (1.f / 64.f) + NEPS);
; #pragma unroll
;                         for (int bj = 0; bj < 2; ++bj)
; #pragma unroll
;                             for (int n = 0; n < 2; ++n) v[bj][n] = v[bj][n] * rn * gn[bj][n];
;                         if (fq < 2) {
;                             const f32x4 cs = *(const f32x4*)(rot + (size_t)posidx * 16 + 4 * fq), sn = *(const f32x4*)(rot + (size_t)posidx * 16 + 8 + 4 * fq);
;                             const f32x4 x1 = v[0][0], x2 = v[0][1];
;                             v[0][0] = x1 * cs - x2 * sn; v[0][1] = x2 * cs + x1 * sn;
;                         }
.LBB0_426:
	s_waitcnt vmcnt(7)
	v_mov_b32_e32 v146, v237
	v_fmamk_f32 v146, v146, 0x3a800000, v212
	v_rsq_f32_e32 v146, v146
	s_and_b64 vcc, exec, s[12:13]
	v_pk_mul_f32 v[160:161], v[112:113], v[146:147] op_sel_hi:[1,0]
	v_pk_mul_f32 v[158:159], v[110:111], v[146:147] op_sel_hi:[1,0]
	v_pk_mul_f32 v[156:157], v[108:109], v[146:147] op_sel_hi:[1,0]
	v_pk_mul_f32 v[154:155], v[106:107], v[146:147] op_sel_hi:[1,0]
	v_pk_mul_f32 v[152:153], v[104:105], v[146:147] op_sel_hi:[1,0]
	v_pk_mul_f32 v[150:151], v[102:103], v[146:147] op_sel_hi:[1,0]
	v_pk_mul_f32 v[148:149], v[100:101], v[146:147] op_sel_hi:[1,0]
	v_pk_mul_f32 v[146:147], v[98:99], v[146:147] op_sel_hi:[1,0]
	s_cbranch_vccnz .LBB0_431
	v_pk_mul_f32 v[202:203], v[160:161], v[160:161]
	v_pk_mul_f32 v[216:217], v[158:159], v[158:159]
	v_and_b32_e32 v189, 64, v213
	v_pk_mov_b32 v[218:219], v[216:217], v[202:203] op_sel:[1,0]
	v_mov_b32_e32 v217, v203
	v_pk_add_f32 v[202:203], v[218:219], v[216:217]
	v_pk_mul_f32 v[216:217], v[156:157], v[156:157]
	v_pk_add_f32 v[202:203], v[202:203], v[202:203] op_sel_hi:[0,1]
	v_pk_mul_f32 v[218:219], v[154:155], v[154:155]
	v_mul_f32_e32 v202, v150, v150
	v_pk_mov_b32 v[220:221], v[218:219], v[216:217] op_sel:[1,0]
	v_mov_b32_e32 v219, v217
	v_pk_add_f32 v[216:217], v[220:221], v[218:219]
	v_pk_fma_f32 v[218:219], v[150:151], v[150:151], v[202:203] op_sel_hi:[1,1,0]
	v_mul_f32_e32 v202, v152, v152
	v_pk_add_f32 v[216:217], v[216:217], v[216:217] op_sel_hi:[0,1]
	v_pk_fma_f32 v[220:221], v[152:153], v[152:153], v[202:203] op_sel_hi:[1,1,0]
	v_mul_f32_e32 v218, v146, v146
	v_mul_f32_e32 v220, v147, v147
	v_mul_f32_e32 v202, v148, v148
	v_mul_f32_e32 v216, v149, v149
	v_xor_b32_e32 v187, 16, v213
	v_add_u32_e32 v189, 64, v189
	v_pk_add_f32 v[218:219], v[218:219], v[220:221]
	v_pk_add_f32 v[202:203], v[202:203], v[216:217]
	v_cmp_lt_i32_e32 vcc, v187, v189
	v_pk_add_f32 v[202:203], v[218:219], v[202:203]
	s_nop 0
	v_cndmask_b32_e32 v187, v213, v187, vcc
	v_add_f32_e32 v185, v202, v203
	v_lshlrev_b32_e32 v187, 2, v187
	ds_bpermute_b32 v187, v187, v185
	s_waitcnt lgkmcnt(0)
	v_add_f32_e32 v185, v185, v187
	v_xor_b32_e32 v187, 32, v213
	v_cmp_lt_i32_e32 vcc, v187, v189
	s_nop 1
	v_cndmask_b32_e32 v187, v213, v187, vcc
	v_lshlrev_b32_e32 v187, 2, v187
	ds_bpermute_b32 v187, v187, v185
	s_waitcnt lgkmcnt(0)
	v_add_f32_e32 v185, v185, v187
	v_fmamk_f32 v185, v185, 0x3c800000, v212
	v_rsq_f32_e32 v202, v185
	s_nop 0
	v_pk_mul_f32 v[158:159], v[158:159], v[202:203] op_sel_hi:[1,0]
	v_pk_mul_f32 v[160:161], v[160:161], v[202:203] op_sel_hi:[1,0]
	v_pk_mul_f32 v[154:155], v[154:155], v[202:203] op_sel_hi:[1,0]
	v_pk_mul_f32 v[156:157], v[156:157], v[202:203] op_sel_hi:[1,0]
	v_pk_mul_f32 v[160:161], v[144:145], v[160:161]
	v_pk_mul_f32 v[158:159], v[142:143], v[158:159]
	v_pk_mul_f32 v[156:157], v[140:141], v[156:157]
	v_pk_mul_f32 v[154:155], v[138:139], v[154:155]
	s_and_saveexec_b64 s[66:67], s[6:7]
	s_cbranch_execz .LBB0_429
	v_mov_b32_e32 v201, v169
	v_lshlrev_b64 v[200:201], 6, v[200:201]
	v_lshl_add_u64 v[200:201], v[174:175], 0, v[200:201]
	global_load_dwordx4 v[216:219], v[200:201], off offset:32
	global_load_dwordx4 v[220:223], v[200:201], off
	s_waitcnt vmcnt(1)
	v_pk_mul_f32 v[200:201], v[156:157], v[218:219]
	v_pk_mul_f32 v[224:225], v[154:155], v[216:217]
	v_pk_mul_f32 v[218:219], v[160:161], v[218:219]
	v_pk_mul_f32 v[216:217], v[158:159], v[216:217]
	s_waitcnt vmcnt(0)
	v_pk_fma_f32 v[160:161], v[160:161], v[222:223], v[200:201] neg_lo:[0,0,1] neg_hi:[0,0,1]
	v_pk_fma_f32 v[158:159], v[158:159], v[220:221], v[224:225] neg_lo:[0,0,1] neg_hi:[0,0,1]
	v_pk_fma_f32 v[156:157], v[156:157], v[222:223], v[218:219]
	v_pk_fma_f32 v[154:155], v[154:155], v[220:221], v[216:217]

;     __device__ __forceinline__ void operator()(const f32x4 (&acc)[2][2][4][2], const Unit& u, int wr, int wc, int fr, int fq) const {
;     ...
;                     const int row = row0 + ai * HALF + m * 16; const float r = __builtin_amdgcn_rsqf(rss[row] * (1.f / 1024.f) + NEPS);
;                     f32x4 v[2][2];
; #pragma unroll
;                     for (int bj = 0; bj < 2; ++bj)
; #pragma unroll
;                         for (int n = 0; n < 2; ++n) v[bj][n] = acc[ai][bj][m][n] * r;
;                     int posidx, b, tt; float* cdst = nullptr;
;                     if (!samp) { tt = row & 4095; b = row >> 12; posidx = tt; if (kind >= 1 && tt >= 4096 - W) cdst = out + okp + ((size_t)(b * W + (tt - (4096 - W))) * 4 + wc) * 64; }
;                     else { const int sr = row - 16384; b = sr >> 2; tt = sr & 3; posidx = 4096 + tt; if (kind >= 1) cdst = out + oks + ((size_t)(b * W + (W - 4 + tt)) * 4 + wc) * 64; }
.LBB0_439:
	s_or_b64 exec, exec, s[66:67]
	v_or_b32_e32 v198, 32, v182
	v_ashrrev_i32_e32 v199, 31, v198
	v_lshl_add_u64 v[146:147], v[198:199], 2, s[40:41]
	s_nop 0
	s_and_b64 vcc, exec, s[14:15]
	s_mov_b64 s[66:67], -1
	s_cbranch_vccnz .LBB0_441
	v_and_b32_e32 v200, 0xfef, v198
	v_cmp_gt_u32_e32 vcc, s97, v200
	s_or_b64 s[66:67], s[2:3], vcc
	s_lshl_b64 s[68:69], s[58:59], 2
	s_add_u32 s0, s48, s68
	v_add_u32_e32 v148, s47, v200
	s_addc_u32 vcc_lo, s49, s69
	s_lshl_b64 s[68:69], s[62:63], 2
	v_ashrrev_i32_e32 v149, 31, v148
	s_add_u32 s68, s0, s68
	v_lshlrev_b64 v[148:149], 10, v[148:149]
	s_addc_u32 s69, vcc_lo, s69
	v_lshl_add_u64 v[148:149], s[68:69], 0, v[148:149]
	s_lshl_b32 s0, s85, 2
	v_lshl_add_u64 v[148:149], v[148:149], 0, s[0:1]
	v_cndmask_b32_e64 v197, v149, 0, s[66:67]
	v_cndmask_b32_e64 v196, v148, 0, s[66:67]
	s_mov_b64 s[66:67], 0

;     __device__ __forceinline__ void operator()(const f32x4 (&acc)[2][2][4][2], const Unit& u, int wr, int wc, int fr, int fq) const {
;     ...
;                     const int row = row0 + ai * HALF + m * 16; const float r = __builtin_amdgcn_rsqf(rss[row] * (1.f / 1024.f) + NEPS);
;                     f32x4 v[2][2];
; #pragma unroll
;                     for (int bj = 0; bj < 2; ++bj)
; #pragma unroll
;                         for (int n = 0; n < 2; ++n) v[bj][n] = acc[ai][bj][m][n] * r;
;                     int posidx, b, tt; float* cdst = nullptr;
;                     if (!samp) { tt = row & 4095; b = row >> 12; posidx = tt; if (kind >= 1 && tt >= 4096 - W) cdst = out + okp + ((size_t)(b * W + (tt - (4096 - W))) * 4 + wc) * 64; }
;                     else { const int sr = row - 16384; b = sr >> 2; tt = sr & 3; posidx = 4096 + tt; if (kind >= 1) cdst = out + oks + ((size_t)(b * W + (W - 4 + tt)) * 4 + wc) * 64; }
;                     if (kind < 2) {
;                         float ss = 0.f;
; #pragma unroll
;                         for (int bj = 0; bj < 2; ++bj)
; #pragma unroll
;                             for (int n = 0; n < 2; ++n) ss += (v[bj][n][0] * v[bj][n][0] + v[bj][n][1] * v[bj][n][1]) + (v[bj][n][2] * v[bj][n][2] + v[bj][n][3] * v[bj][n][3]);
;                         ss += __shfl_xor(ss, 16); ss += __shfl_xor(ss, 32);
;                         const float rn = __builtin_amdgcn_rsqf(ss * (1.f / 64.f) + NEPS);
; #pragma unroll
;                         for (int bj = 0; bj < 2; ++bj)
; #pragma unroll
;                             for (int n = 0; n < 2; ++n) v[bj][n] = v[bj][n] * rn * gn[bj][n];
;                         if (fq < 2) {
;                             const f32x4 cs = *(const f32x4*)(rot + (size_t)posidx * 16 + 4 * fq), sn = *(const f32x4*)(rot + (size_t)posidx * 16 + 8 + 4 * fq);
;                             const f32x4 x1 = v[0][0], x2 = v[0][1];
;                             v[0][0] = x1 * cs - x2 * sn; v[0][1] = x2 * cs + x1 * sn;
;                         }
.LBB0_445:
	s_waitcnt vmcnt(7)
	v_mov_b32_e32 v146, v238
	v_fmamk_f32 v146, v146, 0x3a800000, v212
	v_rsq_f32_e32 v146, v146
	s_and_b64 vcc, exec, s[12:13]
	v_pk_mul_f32 v[160:161], v[96:97], v[146:147] op_sel_hi:[1,0]
	v_pk_mul_f32 v[158:159], v[94:95], v[146:147] op_sel_hi:[1,0]
	v_pk_mul_f32 v[156:157], v[92:93], v[146:147] op_sel_hi:[1,0]
	v_pk_mul_f32 v[154:155], v[90:91], v[146:147] op_sel_hi:[1,0]
	v_pk_mul_f32 v[152:153], v[88:89], v[146:147] op_sel_hi:[1,0]
	v_pk_mul_f32 v[150:151], v[86:87], v[146:147] op_sel_hi:[1,0]
	v_pk_mul_f32 v[148:149], v[84:85], v[146:147] op_sel_hi:[1,0]
	v_pk_mul_f32 v[146:147], v[82:83], v[146:147] op_sel_hi:[1,0]
	s_cbranch_vccnz .LBB0_450
	v_pk_mul_f32 v[202:203], v[160:161], v[160:161]
	v_pk_mul_f32 v[216:217], v[158:159], v[158:159]
	v_and_b32_e32 v189, 64, v213
	v_pk_mov_b32 v[218:219], v[216:217], v[202:203] op_sel:[1,0]
	v_mov_b32_e32 v217, v203
	v_pk_add_f32 v[202:203], v[218:219], v[216:217]
	v_pk_mul_f32 v[216:217], v[156:157], v[156:157]
	v_pk_add_f32 v[202:203], v[202:203], v[202:203] op_sel_hi:[0,1]
	v_pk_mul_f32 v[218:219], v[154:155], v[154:155]
	v_mul_f32_e32 v202, v150, v150
	v_pk_mov_b32 v[220:221], v[218:219], v[216:217] op_sel:[1,0]
	v_mov_b32_e32 v219, v217
	v_pk_add_f32 v[216:217], v[220:221], v[218:219]
	v_pk_fma_f32 v[218:219], v[150:151], v[150:151], v[202:203] op_sel_hi:[1,1,0]
	v_mul_f32_e32 v202, v152, v152
	v_pk_add_f32 v[216:217], v[216:217], v[216:217] op_sel_hi:[0,1]
	v_pk_fma_f32 v[220:221], v[152:153], v[152:153], v[202:203] op_sel_hi:[1,1,0]
	v_mul_f32_e32 v218, v146, v146
	v_mul_f32_e32 v220, v147, v147
	v_mul_f32_e32 v202, v148, v148
	v_mul_f32_e32 v216, v149, v149
	v_xor_b32_e32 v187, 16, v213
	v_add_u32_e32 v189, 64, v189
	v_pk_add_f32 v[218:219], v[218:219], v[220:221]
	v_pk_add_f32 v[202:203], v[202:203], v[216:217]
	v_cmp_lt_i32_e32 vcc, v187, v189
	v_pk_add_f32 v[202:203], v[218:219], v[202:203]
	s_nop 0
	v_cndmask_b32_e32 v187, v213, v187, vcc
	v_add_f32_e32 v185, v202, v203
	v_lshlrev_b32_e32 v187, 2, v187
	ds_bpermute_b32 v187, v187, v185
	s_waitcnt lgkmcnt(0)
	v_add_f32_e32 v185, v185, v187
	v_xor_b32_e32 v187, 32, v213
	v_cmp_lt_i32_e32 vcc, v187, v189
	s_nop 1
	v_cndmask_b32_e32 v187, v213, v187, vcc
	v_lshlrev_b32_e32 v187, 2, v187
	ds_bpermute_b32 v187, v187, v185
	s_waitcnt lgkmcnt(0)
	v_add_f32_e32 v185, v185, v187
	v_fmamk_f32 v185, v185, 0x3c800000, v212
	v_rsq_f32_e32 v202, v185
	s_nop 0
	v_pk_mul_f32 v[158:159], v[158:159], v[202:203] op_sel_hi:[1,0]
	v_pk_mul_f32 v[160:161], v[160:161], v[202:203] op_sel_hi:[1,0]
	v_pk_mul_f32 v[154:155], v[154:155], v[202:203] op_sel_hi:[1,0]
	v_pk_mul_f32 v[156:157], v[156:157], v[202:203] op_sel_hi:[1,0]
	v_pk_mul_f32 v[160:161], v[144:145], v[160:161]
	v_pk_mul_f32 v[158:159], v[142:143], v[158:159]
	v_pk_mul_f32 v[156:157], v[140:141], v[156:157]
	v_pk_mul_f32 v[154:155], v[138:139], v[154:155]
	s_and_saveexec_b64 s[66:67], s[6:7]
	s_cbranch_execz .LBB0_448
	v_mov_b32_e32 v201, v169
	v_lshlrev_b64 v[200:201], 6, v[200:201]
	v_lshl_add_u64 v[200:201], v[174:175], 0, v[200:201]
	global_load_dwordx4 v[216:219], v[200:201], off offset:32
	global_load_dwordx4 v[220:223], v[200:201], off
	s_waitcnt vmcnt(1)
	v_pk_mul_f32 v[200:201], v[156:157], v[218:219]
	v_pk_mul_f32 v[224:225], v[154:155], v[216:217]
	v_pk_mul_f32 v[218:219], v[160:161], v[218:219]
	v_pk_mul_f32 v[216:217], v[158:159], v[216:217]
	s_waitcnt vmcnt(0)
	v_pk_fma_f32 v[160:161], v[160:161], v[222:223], v[200:201] neg_lo:[0,0,1] neg_hi:[0,0,1]
	v_pk_fma_f32 v[158:159], v[158:159], v[220:221], v[224:225] neg_lo:[0,0,1] neg_hi:[0,0,1]
	v_pk_fma_f32 v[156:157], v[156:157], v[222:223], v[218:219]
	v_pk_fma_f32 v[154:155], v[154:155], v[220:221], v[216:217]

;     __device__ __forceinline__ void operator()(const f32x4 (&acc)[2][2][4][2], const Unit& u, int wr, int wc, int fr, int fq) const {
;     ...
;                     const int row = row0 + ai * HALF + m * 16; const float r = __builtin_amdgcn_rsqf(rss[row] * (1.f / 1024.f) + NEPS);
;                     f32x4 v[2][2];
; #pragma unroll
;                     for (int bj = 0; bj < 2; ++bj)
; #pragma unroll
;                         for (int n = 0; n < 2; ++n) v[bj][n] = acc[ai][bj][m][n] * r;
;                     int posidx, b, tt; float* cdst = nullptr;
;                     if (!samp) { tt = row & 4095; b = row >> 12; posidx = tt; if (kind >= 1 && tt >= 4096 - W) cdst = out + okp + ((size_t)(b * W + (tt - (4096 - W))) * 4 + wc) * 64; }
;                     else { const int sr = row - 16384; b = sr >> 2; tt = sr & 3; posidx = 4096 + tt; if (kind >= 1) cdst = out + oks + ((size_t)(b * W + (W - 4 + tt)) * 4 + wc) * 64; }
.LBB0_458:
	s_or_b64 exec, exec, s[66:67]
	v_or_b32_e32 v198, 48, v182
	v_ashrrev_i32_e32 v199, 31, v198
	v_lshl_add_u64 v[146:147], v[198:199], 2, s[40:41]
	s_nop 0
	s_and_b64 vcc, exec, s[14:15]
	s_mov_b64 s[66:67], -1
	s_cbranch_vccnz .LBB0_460
	v_and_b32_e32 v200, 0xfff, v198
	v_cmp_gt_u32_e32 vcc, s97, v200
	s_or_b64 s[66:67], s[2:3], vcc
	s_lshl_b64 s[68:69], s[58:59], 2
	s_add_u32 s0, s48, s68
	v_add_u32_e32 v148, s47, v200
	s_addc_u32 s47, s49, s69
	s_lshl_b64 s[68:69], s[62:63], 2
	v_ashrrev_i32_e32 v149, 31, v148
	s_add_u32 s68, s0, s68
	v_lshlrev_b64 v[148:149], 10, v[148:149]
	s_addc_u32 s69, s47, s69
	v_lshl_add_u64 v[148:149], s[68:69], 0, v[148:149]
	s_lshl_b32 s0, s85, 2
	v_lshl_add_u64 v[148:149], v[148:149], 0, s[0:1]
	v_cndmask_b32_e64 v197, v149, 0, s[66:67]
	v_cndmask_b32_e64 v196, v148, 0, s[66:67]
	s_mov_b64 s[66:67], 0

;     __device__ __forceinline__ void operator()(const f32x4 (&acc)[2][2][4][2], const Unit& u, int wr, int wc, int fr, int fq) const {
;     ...
;                     const int row = row0 + ai * HALF + m * 16; const float r = __builtin_amdgcn_rsqf(rss[row] * (1.f / 1024.f) + NEPS);
;                     f32x4 v[2][2];
; #pragma unroll
;                     for (int bj = 0; bj < 2; ++bj)
; #pragma unroll
;                         for (int n = 0; n < 2; ++n) v[bj][n] = acc[ai][bj][m][n] * r;
;                     int posidx, b, tt; float* cdst = nullptr;
;                     if (!samp) { tt = row & 4095; b = row >> 12; posidx = tt; if (kind >= 1 && tt >= 4096 - W) cdst = out + okp + ((size_t)(b * W + (tt - (4096 - W))) * 4 + wc) * 64; }
;                     else { const int sr = row - 16384; b = sr >> 2; tt = sr & 3; posidx = 4096 + tt; if (kind >= 1) cdst = out + oks + ((size_t)(b * W + (W - 4 + tt)) * 4 + wc) * 64; }
;                     if (kind < 2) {
;                         float ss = 0.f;
; #pragma unroll
;                         for (int bj = 0; bj < 2; ++bj)
; #pragma unroll
;                             for (int n = 0; n < 2; ++n) ss += (v[bj][n][0] * v[bj][n][0] + v[bj][n][1] * v[bj][n][1]) + (v[bj][n][2] * v[bj][n][2] + v[bj][n][3] * v[bj][n][3]);
;                         ss += __shfl_xor(ss, 16); ss += __shfl_xor(ss, 32);
;                         const float rn = __builtin_amdgcn_rsqf(ss * (1.f / 64.f) + NEPS);
; #pragma unroll
;                         for (int bj = 0; bj < 2; ++bj)
; #pragma unroll
;                             for (int n = 0; n < 2; ++n) v[bj][n] = v[bj][n] * rn * gn[bj][n];
;                         if (fq < 2) {
;                             const f32x4 cs = *(const f32x4*)(rot + (size_t)posidx * 16 + 4 * fq), sn = *(const f32x4*)(rot + (size_t)posidx * 16 + 8 + 4 * fq);
;                             const f32x4 x1 = v[0][0], x2 = v[0][1];
;                             v[0][0] = x1 * cs - x2 * sn; v[0][1] = x2 * cs + x1 * sn;
;                         }
.LBB0_464:
	s_waitcnt vmcnt(7)
	v_mov_b32_e32 v146, v239
	v_fmamk_f32 v146, v146, 0x3a800000, v212
	v_rsq_f32_e32 v146, v146
	s_and_b64 vcc, exec, s[12:13]
	v_pk_mul_f32 v[160:161], v[80:81], v[146:147] op_sel_hi:[1,0]
	v_pk_mul_f32 v[158:159], v[78:79], v[146:147] op_sel_hi:[1,0]
	v_pk_mul_f32 v[156:157], v[76:77], v[146:147] op_sel_hi:[1,0]
	v_pk_mul_f32 v[154:155], v[74:75], v[146:147] op_sel_hi:[1,0]
	v_pk_mul_f32 v[152:153], v[72:73], v[146:147] op_sel_hi:[1,0]
	v_pk_mul_f32 v[150:151], v[70:71], v[146:147] op_sel_hi:[1,0]
	v_pk_mul_f32 v[148:149], v[68:69], v[146:147] op_sel_hi:[1,0]
	v_pk_mul_f32 v[146:147], v[66:67], v[146:147] op_sel_hi:[1,0]
	s_cbranch_vccnz .LBB0_469
	v_pk_mul_f32 v[202:203], v[160:161], v[160:161]
	v_pk_mul_f32 v[216:217], v[158:159], v[158:159]
	v_and_b32_e32 v189, 64, v213
	v_pk_mov_b32 v[218:219], v[216:217], v[202:203] op_sel:[1,0]
	v_mov_b32_e32 v217, v203
	v_pk_add_f32 v[202:203], v[218:219], v[216:217]
	v_pk_mul_f32 v[216:217], v[156:157], v[156:157]
	v_pk_add_f32 v[202:203], v[202:203], v[202:203] op_sel_hi:[0,1]
	v_pk_mul_f32 v[218:219], v[154:155], v[154:155]
	v_mul_f32_e32 v202, v150, v150
	v_pk_mov_b32 v[220:221], v[218:219], v[216:217] op_sel:[1,0]
	v_mov_b32_e32 v219, v217
	v_pk_add_f32 v[216:217], v[220:221], v[218:219]
	v_pk_fma_f32 v[218:219], v[150:151], v[150:151], v[202:203] op_sel_hi:[1,1,0]
	v_mul_f32_e32 v202, v152, v152
	v_pk_add_f32 v[216:217], v[216:217], v[216:217] op_sel_hi:[0,1]
	v_pk_fma_f32 v[220:221], v[152:153], v[152:153], v[202:203] op_sel_hi:[1,1,0]
	v_mul_f32_e32 v218, v146, v146
	v_mul_f32_e32 v220, v147, v147
	v_mul_f32_e32 v202, v148, v148
	v_mul_f32_e32 v216, v149, v149
	v_xor_b32_e32 v187, 16, v213
	v_add_u32_e32 v189, 64, v189
	v_pk_add_f32 v[218:219], v[218:219], v[220:221]
	v_pk_add_f32 v[202:203], v[202:203], v[216:217]
	v_cmp_lt_i32_e32 vcc, v187, v189
	v_pk_add_f32 v[202:203], v[218:219], v[202:203]
	s_nop 0
	v_cndmask_b32_e32 v187, v213, v187, vcc
	v_add_f32_e32 v185, v202, v203
	v_lshlrev_b32_e32 v187, 2, v187
	ds_bpermute_b32 v187, v187, v185
	s_waitcnt lgkmcnt(0)
	v_add_f32_e32 v185, v185, v187
	v_xor_b32_e32 v187, 32, v213
	v_cmp_lt_i32_e32 vcc, v187, v189
	s_nop 1
	v_cndmask_b32_e32 v187, v213, v187, vcc
	v_lshlrev_b32_e32 v187, 2, v187
	ds_bpermute_b32 v187, v187, v185
	s_waitcnt lgkmcnt(0)
	v_add_f32_e32 v185, v185, v187
	v_fmamk_f32 v185, v185, 0x3c800000, v212
	v_rsq_f32_e32 v202, v185
	s_nop 0
	v_pk_mul_f32 v[158:159], v[158:159], v[202:203] op_sel_hi:[1,0]
	v_pk_mul_f32 v[160:161], v[160:161], v[202:203] op_sel_hi:[1,0]
	v_pk_mul_f32 v[154:155], v[154:155], v[202:203] op_sel_hi:[1,0]
	v_pk_mul_f32 v[156:157], v[156:157], v[202:203] op_sel_hi:[1,0]
	v_pk_mul_f32 v[160:161], v[144:145], v[160:161]
	v_pk_mul_f32 v[158:159], v[142:143], v[158:159]
	v_pk_mul_f32 v[156:157], v[140:141], v[156:157]
	v_pk_mul_f32 v[154:155], v[138:139], v[154:155]
	s_and_saveexec_b64 s[66:67], s[6:7]
	s_cbranch_execz .LBB0_467
	v_mov_b32_e32 v201, v169
	v_lshlrev_b64 v[200:201], 6, v[200:201]
	v_lshl_add_u64 v[200:201], v[174:175], 0, v[200:201]
	global_load_dwordx4 v[216:219], v[200:201], off offset:32
	global_load_dwordx4 v[220:223], v[200:201], off
	s_waitcnt vmcnt(1)
	v_pk_mul_f32 v[200:201], v[156:157], v[218:219]
	v_pk_mul_f32 v[224:225], v[154:155], v[216:217]
	v_pk_mul_f32 v[218:219], v[160:161], v[218:219]
	v_pk_mul_f32 v[216:217], v[158:159], v[216:217]
	s_waitcnt vmcnt(0)
	v_pk_fma_f32 v[160:161], v[160:161], v[222:223], v[200:201] neg_lo:[0,0,1] neg_hi:[0,0,1]
	v_pk_fma_f32 v[158:159], v[158:159], v[220:221], v[224:225] neg_lo:[0,0,1] neg_hi:[0,0,1]
	v_pk_fma_f32 v[156:157], v[156:157], v[222:223], v[218:219]
	v_pk_fma_f32 v[154:155], v[154:155], v[220:221], v[216:217]

;     __device__ __forceinline__ void operator()(const f32x4 (&acc)[2][2][4][2], const Unit& u, int wr, int wc, int fr, int fq) const {
;     ...
;                     const int row = row0 + ai * HALF + m * 16; const float r = __builtin_amdgcn_rsqf(rss[row] * (1.f / 1024.f) + NEPS);
;                     f32x4 v[2][2];
; #pragma unroll
;                     for (int bj = 0; bj < 2; ++bj)
; #pragma unroll
;                         for (int n = 0; n < 2; ++n) v[bj][n] = acc[ai][bj][m][n] * r;
;                     int posidx, b, tt; float* cdst = nullptr;
;                     if (!samp) { tt = row & 4095; b = row >> 12; posidx = tt; if (kind >= 1 && tt >= 4096 - W) cdst = out + okp + ((size_t)(b * W + (tt - (4096 - W))) * 4 + wc) * 64; }
;                     else { const int sr = row - 16384; b = sr >> 2; tt = sr & 3; posidx = 4096 + tt; if (kind >= 1) cdst = out + oks + ((size_t)(b * W + (W - 4 + tt)) * 4 + wc) * 64; }
.LBB0_477:
	s_or_b64 exec, exec, s[66:67]
	s_nop 0
	v_add_u32_e32 v198, 0x80, v182
	v_ashrrev_i32_e32 v147, 12, v198
	v_lshlrev_b32_e32 v147, s31, v147
	v_add_u32_e32 v215, s46, v147
	s_and_b64 vcc, exec, s[14:15]
	s_mov_b64 s[66:67], -1
	s_cbranch_vccnz .LBB0_479
	v_and_b32_e32 v200, 0xfcf, v198
	v_cmp_gt_u32_e32 vcc, s97, v200
	s_or_b64 s[46:47], s[2:3], vcc
	s_lshl_b64 s[66:67], s[58:59], 2
	s_add_u32 s0, s48, s66
	v_add_u32_e32 v148, v215, v200
	s_addc_u32 s68, s49, s67
	s_lshl_b64 s[66:67], s[62:63], 2
	v_ashrrev_i32_e32 v149, 31, v148
	s_add_u32 s66, s0, s66
	v_lshlrev_b64 v[148:149], 10, v[148:149]
	s_addc_u32 s67, s68, s67
	v_lshl_add_u64 v[148:149], s[66:67], 0, v[148:149]
	s_lshl_b32 s0, s85, 2
	v_lshl_add_u64 v[148:149], v[148:149], 0, s[0:1]
	v_cndmask_b32_e64 v197, v149, 0, s[46:47]
	v_cndmask_b32_e64 v196, v148, 0, s[46:47]
	s_mov_b64 s[66:67], 0

;     __device__ __forceinline__ void operator()(const f32x4 (&acc)[2][2][4][2], const Unit& u, int wr, int wc, int fr, int fq) const {
;     ...
;                     const int row = row0 + ai * HALF + m * 16; const float r = __builtin_amdgcn_rsqf(rss[row] * (1.f / 1024.f) + NEPS);
;                     f32x4 v[2][2];
; #pragma unroll
;                     for (int bj = 0; bj < 2; ++bj)
; #pragma unroll
;                         for (int n = 0; n < 2; ++n) v[bj][n] = acc[ai][bj][m][n] * r;
;                     int posidx, b, tt; float* cdst = nullptr;
;                     if (!samp) { tt = row & 4095; b = row >> 12; posidx = tt; if (kind >= 1 && tt >= 4096 - W) cdst = out + okp + ((size_t)(b * W + (tt - (4096 - W))) * 4 + wc) * 64; }
;                     else { const int sr = row - 16384; b = sr >> 2; tt = sr & 3; posidx = 4096 + tt; if (kind >= 1) cdst = out + oks + ((size_t)(b * W + (W - 4 + tt)) * 4 + wc) * 64; }
;                     if (kind < 2) {
;                         float ss = 0.f;
; #pragma unroll
;                         for (int bj = 0; bj < 2; ++bj)
; #pragma unroll
;                             for (int n = 0; n < 2; ++n) ss += (v[bj][n][0] * v[bj][n][0] + v[bj][n][1] * v[bj][n][1]) + (v[bj][n][2] * v[bj][n][2] + v[bj][n][3] * v[bj][n][3]);
;                         ss += __shfl_xor(ss, 16); ss += __shfl_xor(ss, 32);
;                         const float rn = __builtin_amdgcn_rsqf(ss * (1.f / 64.f) + NEPS);
; #pragma unroll
;                         for (int bj = 0; bj < 2; ++bj)
; #pragma unroll
;                             for (int n = 0; n < 2; ++n) v[bj][n] = v[bj][n] * rn * gn[bj][n];
;                         if (fq < 2) {
;                             const f32x4 cs = *(const f32x4*)(rot + (size_t)posidx * 16 + 4 * fq), sn = *(const f32x4*)(rot + (size_t)posidx * 16 + 8 + 4 * fq);
;                             const f32x4 x1 = v[0][0], x2 = v[0][1];
;                             v[0][0] = x1 * cs - x2 * sn; v[0][1] = x2 * cs + x1 * sn;
;                         }
.LBB0_483:
	s_waitcnt vmcnt(7)
	v_mov_b32_e32 v146, v240
	v_fmamk_f32 v146, v146, 0x3a800000, v212
	v_rsq_f32_e32 v146, v146
	s_and_b64 vcc, exec, s[12:13]
	v_pk_mul_f32 v[160:161], v[64:65], v[146:147] op_sel_hi:[1,0]
	v_pk_mul_f32 v[158:159], v[62:63], v[146:147] op_sel_hi:[1,0]
	v_pk_mul_f32 v[156:157], v[60:61], v[146:147] op_sel_hi:[1,0]
	v_pk_mul_f32 v[154:155], v[58:59], v[146:147] op_sel_hi:[1,0]
	v_pk_mul_f32 v[152:153], v[56:57], v[146:147] op_sel_hi:[1,0]
	v_pk_mul_f32 v[150:151], v[54:55], v[146:147] op_sel_hi:[1,0]
	v_pk_mul_f32 v[148:149], v[52:53], v[146:147] op_sel_hi:[1,0]
	v_pk_mul_f32 v[146:147], v[50:51], v[146:147] op_sel_hi:[1,0]
	s_cbranch_vccnz .LBB0_488
	v_pk_mul_f32 v[202:203], v[160:161], v[160:161]
	v_pk_mul_f32 v[216:217], v[158:159], v[158:159]
	v_and_b32_e32 v189, 64, v213
	v_pk_mov_b32 v[218:219], v[216:217], v[202:203] op_sel:[1,0]
	v_mov_b32_e32 v217, v203
	v_pk_add_f32 v[202:203], v[218:219], v[216:217]
	v_pk_mul_f32 v[216:217], v[156:157], v[156:157]
	v_pk_add_f32 v[202:203], v[202:203], v[202:203] op_sel_hi:[0,1]
	v_pk_mul_f32 v[218:219], v[154:155], v[154:155]
	v_mul_f32_e32 v202, v150, v150
	v_pk_mov_b32 v[220:221], v[218:219], v[216:217] op_sel:[1,0]
	v_mov_b32_e32 v219, v217
	v_pk_add_f32 v[216:217], v[220:221], v[218:219]
	v_pk_fma_f32 v[218:219], v[150:151], v[150:151], v[202:203] op_sel_hi:[1,1,0]
	v_mul_f32_e32 v202, v152, v152
	v_pk_add_f32 v[216:217], v[216:217], v[216:217] op_sel_hi:[0,1]
	v_pk_fma_f32 v[220:221], v[152:153], v[152:153], v[202:203] op_sel_hi:[1,1,0]
	v_mul_f32_e32 v218, v146, v146
	v_mul_f32_e32 v220, v147, v147
	v_mul_f32_e32 v202, v148, v148
	v_mul_f32_e32 v216, v149, v149
	v_xor_b32_e32 v187, 16, v213
	v_add_u32_e32 v189, 64, v189
	v_pk_add_f32 v[218:219], v[218:219], v[220:221]
	v_pk_add_f32 v[202:203], v[202:203], v[216:217]
	v_cmp_lt_i32_e32 vcc, v187, v189
	v_pk_add_f32 v[202:203], v[218:219], v[202:203]
	s_nop 0
	v_cndmask_b32_e32 v187, v213, v187, vcc
	v_add_f32_e32 v185, v202, v203
	v_lshlrev_b32_e32 v187, 2, v187
	ds_bpermute_b32 v187, v187, v185
	s_waitcnt lgkmcnt(0)
	v_add_f32_e32 v185, v185, v187
	v_xor_b32_e32 v187, 32, v213
	v_cmp_lt_i32_e32 vcc, v187, v189
	s_nop 1
	v_cndmask_b32_e32 v187, v213, v187, vcc
	v_lshlrev_b32_e32 v187, 2, v187
	ds_bpermute_b32 v187, v187, v185
	s_waitcnt lgkmcnt(0)
	v_add_f32_e32 v185, v185, v187
	v_fmamk_f32 v185, v185, 0x3c800000, v212
	v_rsq_f32_e32 v202, v185
	s_nop 0
	v_pk_mul_f32 v[158:159], v[158:159], v[202:203] op_sel_hi:[1,0]
	v_pk_mul_f32 v[160:161], v[160:161], v[202:203] op_sel_hi:[1,0]
	v_pk_mul_f32 v[154:155], v[154:155], v[202:203] op_sel_hi:[1,0]
	v_pk_mul_f32 v[156:157], v[156:157], v[202:203] op_sel_hi:[1,0]
	v_pk_mul_f32 v[160:161], v[144:145], v[160:161]
	v_pk_mul_f32 v[158:159], v[142:143], v[158:159]
	v_pk_mul_f32 v[156:157], v[140:141], v[156:157]
	v_pk_mul_f32 v[154:155], v[138:139], v[154:155]
	s_and_saveexec_b64 s[66:67], s[6:7]
	s_cbranch_execz .LBB0_486
	v_mov_b32_e32 v201, v169
	v_lshlrev_b64 v[200:201], 6, v[200:201]
	v_lshl_add_u64 v[200:201], v[174:175], 0, v[200:201]
	global_load_dwordx4 v[216:219], v[200:201], off offset:32
	global_load_dwordx4 v[220:223], v[200:201], off
	s_waitcnt vmcnt(1)
	v_pk_mul_f32 v[200:201], v[156:157], v[218:219]
	v_pk_mul_f32 v[224:225], v[154:155], v[216:217]
	v_pk_mul_f32 v[218:219], v[160:161], v[218:219]
	v_pk_mul_f32 v[216:217], v[158:159], v[216:217]
	s_waitcnt vmcnt(0)
	v_pk_fma_f32 v[160:161], v[160:161], v[222:223], v[200:201] neg_lo:[0,0,1] neg_hi:[0,0,1]
	v_pk_fma_f32 v[158:159], v[158:159], v[220:221], v[224:225] neg_lo:[0,0,1] neg_hi:[0,0,1]
	v_pk_fma_f32 v[156:157], v[156:157], v[222:223], v[218:219]
	v_pk_fma_f32 v[154:155], v[154:155], v[220:221], v[216:217]

;     __device__ __forceinline__ void operator()(const f32x4 (&acc)[2][2][4][2], const Unit& u, int wr, int wc, int fr, int fq) const {
;     ...
;                     const int row = row0 + ai * HALF + m * 16; const float r = __builtin_amdgcn_rsqf(rss[row] * (1.f / 1024.f) + NEPS);
;                     f32x4 v[2][2];
; #pragma unroll
;                     for (int bj = 0; bj < 2; ++bj)
; #pragma unroll
;                         for (int n = 0; n < 2; ++n) v[bj][n] = acc[ai][bj][m][n] * r;
;                     int posidx, b, tt; float* cdst = nullptr;
;                     if (!samp) { tt = row & 4095; b = row >> 12; posidx = tt; if (kind >= 1 && tt >= 4096 - W) cdst = out + okp + ((size_t)(b * W + (tt - (4096 - W))) * 4 + wc) * 64; }
;                     else { const int sr = row - 16384; b = sr >> 2; tt = sr & 3; posidx = 4096 + tt; if (kind >= 1) cdst = out + oks + ((size_t)(b * W + (W - 4 + tt)) * 4 + wc) * 64; }
.LBB0_496:
	s_or_b64 exec, exec, s[66:67]
	s_nop 0
	v_add_u32_e32 v198, 0x90, v182
	s_and_b64 vcc, exec, s[14:15]
	s_mov_b64 s[66:67], -1
	s_cbranch_vccnz .LBB0_498
	v_and_b32_e32 v200, 0xfdf, v198
	v_cmp_gt_u32_e32 vcc, s97, v200
	s_or_b64 s[46:47], s[2:3], vcc
	s_lshl_b64 s[66:67], s[58:59], 2
	s_add_u32 s0, s48, s66
	v_add_u32_e32 v148, v215, v200
	s_addc_u32 s68, s49, s67
	s_lshl_b64 s[66:67], s[62:63], 2
	v_ashrrev_i32_e32 v149, 31, v148
	s_add_u32 s66, s0, s66
	v_lshlrev_b64 v[148:149], 10, v[148:149]
	s_addc_u32 s67, s68, s67
	v_lshl_add_u64 v[148:149], s[66:67], 0, v[148:149]
	s_lshl_b32 s0, s85, 2
	v_lshl_add_u64 v[148:149], v[148:149], 0, s[0:1]
	v_cndmask_b32_e64 v197, v149, 0, s[46:47]
	v_cndmask_b32_e64 v196, v148, 0, s[46:47]
	s_mov_b64 s[66:67], 0

;     __device__ __forceinline__ void operator()(const f32x4 (&acc)[2][2][4][2], const Unit& u, int wr, int wc, int fr, int fq) const {
;     ...
;                     const int row = row0 + ai * HALF + m * 16; const float r = __builtin_amdgcn_rsqf(rss[row] * (1.f / 1024.f) + NEPS);
;                     f32x4 v[2][2];
; #pragma unroll
;                     for (int bj = 0; bj < 2; ++bj)
; #pragma unroll
;                         for (int n = 0; n < 2; ++n) v[bj][n] = acc[ai][bj][m][n] * r;
;                     int posidx, b, tt; float* cdst = nullptr;
;                     if (!samp) { tt = row & 4095; b = row >> 12; posidx = tt; if (kind >= 1 && tt >= 4096 - W) cdst = out + okp + ((size_t)(b * W + (tt - (4096 - W))) * 4 + wc) * 64; }
;                     else { const int sr = row - 16384; b = sr >> 2; tt = sr & 3; posidx = 4096 + tt; if (kind >= 1) cdst = out + oks + ((size_t)(b * W + (W - 4 + tt)) * 4 + wc) * 64; }
;                     if (kind < 2) {
;                         float ss = 0.f;
; #pragma unroll
;                         for (int bj = 0; bj < 2; ++bj)
; #pragma unroll
;                             for (int n = 0; n < 2; ++n) ss += (v[bj][n][0] * v[bj][n][0] + v[bj][n][1] * v[bj][n][1]) + (v[bj][n][2] * v[bj][n][2] + v[bj][n][3] * v[bj][n][3]);
;                         ss += __shfl_xor(ss, 16); ss += __shfl_xor(ss, 32);
;                         const float rn = __builtin_amdgcn_rsqf(ss * (1.f / 64.f) + NEPS);
; #pragma unroll
;                         for (int bj = 0; bj < 2; ++bj)
; #pragma unroll
;                             for (int n = 0; n < 2; ++n) v[bj][n] = v[bj][n] * rn * gn[bj][n];
;                         if (fq < 2) {
;                             const f32x4 cs = *(const f32x4*)(rot + (size_t)posidx * 16 + 4 * fq), sn = *(const f32x4*)(rot + (size_t)posidx * 16 + 8 + 4 * fq);
;                             const f32x4 x1 = v[0][0], x2 = v[0][1];
;                             v[0][0] = x1 * cs - x2 * sn; v[0][1] = x2 * cs + x1 * sn;
;                         }
.LBB0_502:
	s_waitcnt vmcnt(7)
	v_mov_b32_e32 v146, v241
	v_fmamk_f32 v146, v146, 0x3a800000, v212
	v_rsq_f32_e32 v146, v146
	s_and_b64 vcc, exec, s[12:13]
	v_pk_mul_f32 v[160:161], v[48:49], v[146:147] op_sel_hi:[1,0]
	v_pk_mul_f32 v[158:159], v[46:47], v[146:147] op_sel_hi:[1,0]
	v_pk_mul_f32 v[156:157], v[44:45], v[146:147] op_sel_hi:[1,0]
	v_pk_mul_f32 v[154:155], v[42:43], v[146:147] op_sel_hi:[1,0]
	v_pk_mul_f32 v[152:153], v[40:41], v[146:147] op_sel_hi:[1,0]
	v_pk_mul_f32 v[150:151], v[38:39], v[146:147] op_sel_hi:[1,0]
	v_pk_mul_f32 v[148:149], v[36:37], v[146:147] op_sel_hi:[1,0]
	v_pk_mul_f32 v[146:147], v[34:35], v[146:147] op_sel_hi:[1,0]
	s_cbranch_vccnz .LBB0_507
	v_pk_mul_f32 v[202:203], v[160:161], v[160:161]
	v_pk_mul_f32 v[216:217], v[158:159], v[158:159]
	v_and_b32_e32 v189, 64, v213
	v_pk_mov_b32 v[218:219], v[216:217], v[202:203] op_sel:[1,0]
	v_mov_b32_e32 v217, v203
	v_pk_add_f32 v[202:203], v[218:219], v[216:217]
	v_pk_mul_f32 v[216:217], v[156:157], v[156:157]
	v_pk_add_f32 v[202:203], v[202:203], v[202:203] op_sel_hi:[0,1]
	v_pk_mul_f32 v[218:219], v[154:155], v[154:155]
	v_mul_f32_e32 v202, v150, v150
	v_pk_mov_b32 v[220:221], v[218:219], v[216:217] op_sel:[1,0]
	v_mov_b32_e32 v219, v217
	v_pk_add_f32 v[216:217], v[220:221], v[218:219]
	v_pk_fma_f32 v[218:219], v[150:151], v[150:151], v[202:203] op_sel_hi:[1,1,0]
	v_mul_f32_e32 v202, v152, v152
	v_pk_add_f32 v[216:217], v[216:217], v[216:217] op_sel_hi:[0,1]
	v_pk_fma_f32 v[220:221], v[152:153], v[152:153], v[202:203] op_sel_hi:[1,1,0]
	v_mul_f32_e32 v218, v146, v146
	v_mul_f32_e32 v220, v147, v147
	v_mul_f32_e32 v202, v148, v148
	v_mul_f32_e32 v216, v149, v149
	v_xor_b32_e32 v187, 16, v213
	v_add_u32_e32 v189, 64, v189
	v_pk_add_f32 v[218:219], v[218:219], v[220:221]
	v_pk_add_f32 v[202:203], v[202:203], v[216:217]
	v_cmp_lt_i32_e32 vcc, v187, v189
	v_pk_add_f32 v[202:203], v[218:219], v[202:203]
	s_nop 0
	v_cndmask_b32_e32 v187, v213, v187, vcc
	v_add_f32_e32 v185, v202, v203
	v_lshlrev_b32_e32 v187, 2, v187
	ds_bpermute_b32 v187, v187, v185
	s_waitcnt lgkmcnt(0)
	v_add_f32_e32 v185, v185, v187
	v_xor_b32_e32 v187, 32, v213
	v_cmp_lt_i32_e32 vcc, v187, v189
	s_nop 1
	v_cndmask_b32_e32 v187, v213, v187, vcc
	v_lshlrev_b32_e32 v187, 2, v187
	ds_bpermute_b32 v187, v187, v185
	s_waitcnt lgkmcnt(0)
	v_add_f32_e32 v185, v185, v187
	v_fmamk_f32 v185, v185, 0x3c800000, v212
	v_rsq_f32_e32 v202, v185
	s_nop 0
	v_pk_mul_f32 v[158:159], v[158:159], v[202:203] op_sel_hi:[1,0]
	v_pk_mul_f32 v[160:161], v[160:161], v[202:203] op_sel_hi:[1,0]
	v_pk_mul_f32 v[154:155], v[154:155], v[202:203] op_sel_hi:[1,0]
	v_pk_mul_f32 v[156:157], v[156:157], v[202:203] op_sel_hi:[1,0]
	v_pk_mul_f32 v[160:161], v[144:145], v[160:161]
	v_pk_mul_f32 v[158:159], v[142:143], v[158:159]
	v_pk_mul_f32 v[156:157], v[140:141], v[156:157]
	v_pk_mul_f32 v[154:155], v[138:139], v[154:155]
	s_and_saveexec_b64 s[66:67], s[6:7]
	s_cbranch_execz .LBB0_505
	v_mov_b32_e32 v201, v169
	v_lshlrev_b64 v[200:201], 6, v[200:201]
	v_lshl_add_u64 v[200:201], v[174:175], 0, v[200:201]
	global_load_dwordx4 v[216:219], v[200:201], off offset:32
	global_load_dwordx4 v[220:223], v[200:201], off
	s_waitcnt vmcnt(1)
	v_pk_mul_f32 v[200:201], v[156:157], v[218:219]
	v_pk_mul_f32 v[224:225], v[154:155], v[216:217]
	v_pk_mul_f32 v[218:219], v[160:161], v[218:219]
	v_pk_mul_f32 v[216:217], v[158:159], v[216:217]
	s_waitcnt vmcnt(0)
	v_pk_fma_f32 v[160:161], v[160:161], v[222:223], v[200:201] neg_lo:[0,0,1] neg_hi:[0,0,1]
	v_pk_fma_f32 v[158:159], v[158:159], v[220:221], v[224:225] neg_lo:[0,0,1] neg_hi:[0,0,1]
	v_pk_fma_f32 v[156:157], v[156:157], v[222:223], v[218:219]
	v_pk_fma_f32 v[154:155], v[154:155], v[220:221], v[216:217]

;     __device__ __forceinline__ void operator()(const f32x4 (&acc)[2][2][4][2], const Unit& u, int wr, int wc, int fr, int fq) const {
;     ...
;                     const int row = row0 + ai * HALF + m * 16; const float r = __builtin_amdgcn_rsqf(rss[row] * (1.f / 1024.f) + NEPS);
;                     f32x4 v[2][2];
; #pragma unroll
;                     for (int bj = 0; bj < 2; ++bj)
; #pragma unroll
;                         for (int n = 0; n < 2; ++n) v[bj][n] = acc[ai][bj][m][n] * r;
;                     int posidx, b, tt; float* cdst = nullptr;
;                     if (!samp) { tt = row & 4095; b = row >> 12; posidx = tt; if (kind >= 1 && tt >= 4096 - W) cdst = out + okp + ((size_t)(b * W + (tt - (4096 - W))) * 4 + wc) * 64; }
;                     else { const int sr = row - 16384; b = sr >> 2; tt = sr & 3; posidx = 4096 + tt; if (kind >= 1) cdst = out + oks + ((size_t)(b * W + (W - 4 + tt)) * 4 + wc) * 64; }
.LBB0_515:
	s_or_b64 exec, exec, s[66:67]
	s_nop 0
	v_add_u32_e32 v198, 0xa0, v182
	s_and_b64 vcc, exec, s[14:15]
	s_mov_b64 s[66:67], -1
	s_cbranch_vccnz .LBB0_517
	v_and_b32_e32 v200, 0xfef, v198
	v_cmp_gt_u32_e32 vcc, s97, v200
	s_or_b64 s[46:47], s[2:3], vcc
	s_lshl_b64 s[66:67], s[58:59], 2
	s_add_u32 s0, s48, s66
	v_add_u32_e32 v148, v215, v200
	s_addc_u32 s68, s49, s67
	s_lshl_b64 s[66:67], s[62:63], 2
	v_ashrrev_i32_e32 v149, 31, v148
	s_add_u32 s66, s0, s66
	v_lshlrev_b64 v[148:149], 10, v[148:149]
	s_addc_u32 s67, s68, s67
	v_lshl_add_u64 v[148:149], s[66:67], 0, v[148:149]
	s_lshl_b32 s0, s85, 2
	v_lshl_add_u64 v[148:149], v[148:149], 0, s[0:1]
	v_cndmask_b32_e64 v197, v149, 0, s[46:47]
	v_cndmask_b32_e64 v196, v148, 0, s[46:47]
	s_mov_b64 s[66:67], 0

;     __device__ __forceinline__ void operator()(const f32x4 (&acc)[2][2][4][2], const Unit& u, int wr, int wc, int fr, int fq) const {
;     ...
;                     const int row = row0 + ai * HALF + m * 16; const float r = __builtin_amdgcn_rsqf(rss[row] * (1.f / 1024.f) + NEPS);
;                     f32x4 v[2][2];
; #pragma unroll
;                     for (int bj = 0; bj < 2; ++bj)
; #pragma unroll
;                         for (int n = 0; n < 2; ++n) v[bj][n] = acc[ai][bj][m][n] * r;
;                     int posidx, b, tt; float* cdst = nullptr;
;                     if (!samp) { tt = row & 4095; b = row >> 12; posidx = tt; if (kind >= 1 && tt >= 4096 - W) cdst = out + okp + ((size_t)(b * W + (tt - (4096 - W))) * 4 + wc) * 64; }
;                     else { const int sr = row - 16384; b = sr >> 2; tt = sr & 3; posidx = 4096 + tt; if (kind >= 1) cdst = out + oks + ((size_t)(b * W + (W - 4 + tt)) * 4 + wc) * 64; }
;                     if (kind < 2) {
;                         float ss = 0.f;
; #pragma unroll
;                         for (int bj = 0; bj < 2; ++bj)
; #pragma unroll
;                             for (int n = 0; n < 2; ++n) ss += (v[bj][n][0] * v[bj][n][0] + v[bj][n][1] * v[bj][n][1]) + (v[bj][n][2] * v[bj][n][2] + v[bj][n][3] * v[bj][n][3]);
;                         ss += __shfl_xor(ss, 16); ss += __shfl_xor(ss, 32);
;                         const float rn = __builtin_amdgcn_rsqf(ss * (1.f / 64.f) + NEPS);
; #pragma unroll
;                         for (int bj = 0; bj < 2; ++bj)
; #pragma unroll
;                             for (int n = 0; n < 2; ++n) v[bj][n] = v[bj][n] * rn * gn[bj][n];
;                         if (fq < 2) {
;                             const f32x4 cs = *(const f32x4*)(rot + (size_t)posidx * 16 + 4 * fq), sn = *(const f32x4*)(rot + (size_t)posidx * 16 + 8 + 4 * fq);
;                             const f32x4 x1 = v[0][0], x2 = v[0][1];
;                             v[0][0] = x1 * cs - x2 * sn; v[0][1] = x2 * cs + x1 * sn;
;                         }
.LBB0_521:
	s_waitcnt vmcnt(7)
	v_mov_b32_e32 v146, v242
	v_fmamk_f32 v146, v146, 0x3a800000, v212
	v_rsq_f32_e32 v146, v146
	s_and_b64 vcc, exec, s[12:13]
	v_pk_mul_f32 v[160:161], v[32:33], v[146:147] op_sel_hi:[1,0]
	v_pk_mul_f32 v[158:159], v[30:31], v[146:147] op_sel_hi:[1,0]
	v_pk_mul_f32 v[156:157], v[28:29], v[146:147] op_sel_hi:[1,0]
	v_pk_mul_f32 v[154:155], v[26:27], v[146:147] op_sel_hi:[1,0]
	v_pk_mul_f32 v[152:153], v[24:25], v[146:147] op_sel_hi:[1,0]
	v_pk_mul_f32 v[150:151], v[22:23], v[146:147] op_sel_hi:[1,0]
	v_pk_mul_f32 v[148:149], v[20:21], v[146:147] op_sel_hi:[1,0]
	v_pk_mul_f32 v[146:147], v[18:19], v[146:147] op_sel_hi:[1,0]
	s_cbranch_vccnz .LBB0_526
	v_pk_mul_f32 v[202:203], v[160:161], v[160:161]
	v_pk_mul_f32 v[216:217], v[158:159], v[158:159]
	v_and_b32_e32 v189, 64, v213
	v_pk_mov_b32 v[218:219], v[216:217], v[202:203] op_sel:[1,0]
	v_mov_b32_e32 v217, v203
	v_pk_add_f32 v[202:203], v[218:219], v[216:217]
	v_pk_mul_f32 v[216:217], v[156:157], v[156:157]
	v_pk_add_f32 v[202:203], v[202:203], v[202:203] op_sel_hi:[0,1]
	v_pk_mul_f32 v[218:219], v[154:155], v[154:155]
	v_mul_f32_e32 v202, v150, v150
	v_pk_mov_b32 v[220:221], v[218:219], v[216:217] op_sel:[1,0]
	v_mov_b32_e32 v219, v217
	v_pk_add_f32 v[216:217], v[220:221], v[218:219]
	v_pk_fma_f32 v[218:219], v[150:151], v[150:151], v[202:203] op_sel_hi:[1,1,0]
	v_mul_f32_e32 v202, v152, v152
	v_pk_add_f32 v[216:217], v[216:217], v[216:217] op_sel_hi:[0,1]
	v_pk_fma_f32 v[220:221], v[152:153], v[152:153], v[202:203] op_sel_hi:[1,1,0]
	v_mul_f32_e32 v218, v146, v146
	v_mul_f32_e32 v220, v147, v147
	v_mul_f32_e32 v202, v148, v148
	v_mul_f32_e32 v216, v149, v149
	v_xor_b32_e32 v187, 16, v213
	v_add_u32_e32 v189, 64, v189
	v_pk_add_f32 v[218:219], v[218:219], v[220:221]
	v_pk_add_f32 v[202:203], v[202:203], v[216:217]
	v_cmp_lt_i32_e32 vcc, v187, v189
	v_pk_add_f32 v[202:203], v[218:219], v[202:203]
	s_nop 0
	v_cndmask_b32_e32 v187, v213, v187, vcc
	v_add_f32_e32 v185, v202, v203
	v_lshlrev_b32_e32 v187, 2, v187
	ds_bpermute_b32 v187, v187, v185
	s_waitcnt lgkmcnt(0)
	v_add_f32_e32 v185, v185, v187
	v_xor_b32_e32 v187, 32, v213
	v_cmp_lt_i32_e32 vcc, v187, v189
	s_nop 1
	v_cndmask_b32_e32 v187, v213, v187, vcc
	v_lshlrev_b32_e32 v187, 2, v187
	ds_bpermute_b32 v187, v187, v185
	s_waitcnt lgkmcnt(0)
	v_add_f32_e32 v185, v185, v187
	v_fmamk_f32 v185, v185, 0x3c800000, v212
	v_rsq_f32_e32 v202, v185
	s_nop 0
	v_pk_mul_f32 v[158:159], v[158:159], v[202:203] op_sel_hi:[1,0]
	v_pk_mul_f32 v[160:161], v[160:161], v[202:203] op_sel_hi:[1,0]
	v_pk_mul_f32 v[154:155], v[154:155], v[202:203] op_sel_hi:[1,0]
	v_pk_mul_f32 v[156:157], v[156:157], v[202:203] op_sel_hi:[1,0]
	v_pk_mul_f32 v[160:161], v[144:145], v[160:161]
	v_pk_mul_f32 v[158:159], v[142:143], v[158:159]
	v_pk_mul_f32 v[156:157], v[140:141], v[156:157]
	v_pk_mul_f32 v[154:155], v[138:139], v[154:155]
	s_and_saveexec_b64 s[66:67], s[6:7]
	s_cbranch_execz .LBB0_524
	v_mov_b32_e32 v201, v169
	v_lshlrev_b64 v[200:201], 6, v[200:201]
	v_lshl_add_u64 v[200:201], v[174:175], 0, v[200:201]
	global_load_dwordx4 v[216:219], v[200:201], off offset:32
	global_load_dwordx4 v[220:223], v[200:201], off
	s_waitcnt vmcnt(1)
	v_pk_mul_f32 v[200:201], v[156:157], v[218:219]
	v_pk_mul_f32 v[224:225], v[154:155], v[216:217]
	v_pk_mul_f32 v[218:219], v[160:161], v[218:219]
	v_pk_mul_f32 v[216:217], v[158:159], v[216:217]
	s_waitcnt vmcnt(0)
	v_pk_fma_f32 v[160:161], v[160:161], v[222:223], v[200:201] neg_lo:[0,0,1] neg_hi:[0,0,1]
	v_pk_fma_f32 v[158:159], v[158:159], v[220:221], v[224:225] neg_lo:[0,0,1] neg_hi:[0,0,1]
	v_pk_fma_f32 v[156:157], v[156:157], v[222:223], v[218:219]
	v_pk_fma_f32 v[154:155], v[154:155], v[220:221], v[216:217]

;     __device__ __forceinline__ void operator()(const f32x4 (&acc)[2][2][4][2], const Unit& u, int wr, int wc, int fr, int fq) const {
;     ...
;                     const int row = row0 + ai * HALF + m * 16; const float r = __builtin_amdgcn_rsqf(rss[row] * (1.f / 1024.f) + NEPS);
;                     f32x4 v[2][2];
; #pragma unroll
;                     for (int bj = 0; bj < 2; ++bj)
; #pragma unroll
;                         for (int n = 0; n < 2; ++n) v[bj][n] = acc[ai][bj][m][n] * r;
;                     int posidx, b, tt; float* cdst = nullptr;
;                     if (!samp) { tt = row & 4095; b = row >> 12; posidx = tt; if (kind >= 1 && tt >= 4096 - W) cdst = out + okp + ((size_t)(b * W + (tt - (4096 - W))) * 4 + wc) * 64; }
;                     else { const int sr = row - 16384; b = sr >> 2; tt = sr & 3; posidx = 4096 + tt; if (kind >= 1) cdst = out + oks + ((size_t)(b * W + (W - 4 + tt)) * 4 + wc) * 64; }
.LBB0_534:
	s_or_b64 exec, exec, s[66:67]
	s_nop 0
	v_add_u32_e32 v196, 0xb0, v182
	s_and_b64 vcc, exec, s[14:15]
	s_mov_b64 s[14:15], -1
	s_cbranch_vccnz .LBB0_536
	v_and_b32_e32 v198, 0xfff, v196
	v_cmp_gt_u32_e32 vcc, s97, v198
	s_or_b64 s[14:15], s[2:3], vcc
	s_lshl_b64 s[46:47], s[58:59], 2
	s_add_u32 s0, s48, s46
	v_add_u32_e32 v148, v215, v198
	s_addc_u32 s58, s49, s47
	s_lshl_b64 s[46:47], s[62:63], 2
	v_ashrrev_i32_e32 v149, 31, v148
	s_add_u32 s46, s0, s46
	v_lshlrev_b64 v[148:149], 10, v[148:149]
	s_addc_u32 s47, s58, s47
	v_lshl_add_u64 v[148:149], s[46:47], 0, v[148:149]
	s_lshl_b32 s0, s85, 2
	v_lshl_add_u64 v[148:149], v[148:149], 0, s[0:1]
	v_cndmask_b32_e64 v191, v149, 0, s[14:15]
	v_cndmask_b32_e64 v190, v148, 0, s[14:15]
	s_mov_b64 s[14:15], 0

;     __device__ __forceinline__ void operator()(const f32x4 (&acc)[2][2][4][2], const Unit& u, int wr, int wc, int fr, int fq) const {
;     ...
;                     const int row = row0 + ai * HALF + m * 16; const float r = __builtin_amdgcn_rsqf(rss[row] * (1.f / 1024.f) + NEPS);
;                     f32x4 v[2][2];
; #pragma unroll
;                     for (int bj = 0; bj < 2; ++bj)
; #pragma unroll
;                         for (int n = 0; n < 2; ++n) v[bj][n] = acc[ai][bj][m][n] * r;
;                     int posidx, b, tt; float* cdst = nullptr;
;                     if (!samp) { tt = row & 4095; b = row >> 12; posidx = tt; if (kind >= 1 && tt >= 4096 - W) cdst = out + okp + ((size_t)(b * W + (tt - (4096 - W))) * 4 + wc) * 64; }
;                     else { const int sr = row - 16384; b = sr >> 2; tt = sr & 3; posidx = 4096 + tt; if (kind >= 1) cdst = out + oks + ((size_t)(b * W + (W - 4 + tt)) * 4 + wc) * 64; }
;                     if (kind < 2) {
;                         float ss = 0.f;
; #pragma unroll
;                         for (int bj = 0; bj < 2; ++bj)
; #pragma unroll
;                             for (int n = 0; n < 2; ++n) ss += (v[bj][n][0] * v[bj][n][0] + v[bj][n][1] * v[bj][n][1]) + (v[bj][n][2] * v[bj][n][2] + v[bj][n][3] * v[bj][n][3]);
;                         ss += __shfl_xor(ss, 16); ss += __shfl_xor(ss, 32);
;                         const float rn = __builtin_amdgcn_rsqf(ss * (1.f / 64.f) + NEPS);
; #pragma unroll
;                         for (int bj = 0; bj < 2; ++bj)
; #pragma unroll
;                             for (int n = 0; n < 2; ++n) v[bj][n] = v[bj][n] * rn * gn[bj][n];
;                         if (fq < 2) {
;                             const f32x4 cs = *(const f32x4*)(rot + (size_t)posidx * 16 + 4 * fq), sn = *(const f32x4*)(rot + (size_t)posidx * 16 + 8 + 4 * fq);
;                             const f32x4 x1 = v[0][0], x2 = v[0][1];
;                             v[0][0] = x1 * cs - x2 * sn; v[0][1] = x2 * cs + x1 * sn;
;                         }
.LBB0_540:
	s_waitcnt vmcnt(7)
	v_mov_b32_e32 v146, v243
	v_fmamk_f32 v146, v146, 0x3a800000, v212
	v_rsq_f32_e32 v146, v146
	s_and_b64 vcc, exec, s[12:13]
	v_pk_mul_f32 v[160:161], v[16:17], v[146:147] op_sel_hi:[1,0]
	v_pk_mul_f32 v[158:159], v[14:15], v[146:147] op_sel_hi:[1,0]
	v_pk_mul_f32 v[156:157], v[12:13], v[146:147] op_sel_hi:[1,0]
	v_pk_mul_f32 v[154:155], v[10:11], v[146:147] op_sel_hi:[1,0]
	v_pk_mul_f32 v[152:153], v[8:9], v[146:147] op_sel_hi:[1,0]
	v_pk_mul_f32 v[150:151], v[6:7], v[146:147] op_sel_hi:[1,0]
	v_pk_mul_f32 v[148:149], v[4:5], v[146:147] op_sel_hi:[1,0]
	v_pk_mul_f32 v[146:147], v[2:3], v[146:147] op_sel_hi:[1,0]
	s_cbranch_vccnz .LBB0_545
	v_pk_mul_f32 v[200:201], v[160:161], v[160:161]
	v_pk_mul_f32 v[202:203], v[158:159], v[158:159]
	v_and_b32_e32 v187, 64, v213
	v_pk_mov_b32 v[216:217], v[202:203], v[200:201] op_sel:[1,0]
	v_mov_b32_e32 v203, v201
	v_pk_add_f32 v[200:201], v[216:217], v[202:203]
	v_pk_mul_f32 v[202:203], v[156:157], v[156:157]
	v_pk_add_f32 v[200:201], v[200:201], v[200:201] op_sel_hi:[0,1]
	v_pk_mul_f32 v[216:217], v[154:155], v[154:155]
	v_mul_f32_e32 v200, v150, v150
	v_pk_mov_b32 v[218:219], v[216:217], v[202:203] op_sel:[1,0]
	v_mov_b32_e32 v217, v203
	v_pk_add_f32 v[202:203], v[218:219], v[216:217]
	v_pk_fma_f32 v[216:217], v[150:151], v[150:151], v[200:201] op_sel_hi:[1,1,0]
	v_mul_f32_e32 v200, v152, v152
	v_pk_add_f32 v[202:203], v[202:203], v[202:203] op_sel_hi:[0,1]
	v_pk_fma_f32 v[218:219], v[152:153], v[152:153], v[200:201] op_sel_hi:[1,1,0]
	v_mul_f32_e32 v216, v146, v146
	v_mul_f32_e32 v218, v147, v147
	v_mul_f32_e32 v200, v148, v148
	v_mul_f32_e32 v202, v149, v149
	v_xor_b32_e32 v185, 16, v213
	v_add_u32_e32 v187, 64, v187
	v_pk_add_f32 v[216:217], v[216:217], v[218:219]
	v_pk_add_f32 v[200:201], v[200:201], v[202:203]
	v_cmp_lt_i32_e32 vcc, v185, v187
	v_pk_add_f32 v[200:201], v[216:217], v[200:201]
	s_nop 0
	v_cndmask_b32_e32 v185, v213, v185, vcc
	v_add_f32_e32 v183, v200, v201
	v_lshlrev_b32_e32 v185, 2, v185
	ds_bpermute_b32 v185, v185, v183
	s_waitcnt lgkmcnt(0)
	v_add_f32_e32 v183, v183, v185
	v_xor_b32_e32 v185, 32, v213
	v_cmp_lt_i32_e32 vcc, v185, v187
	s_nop 1
	v_cndmask_b32_e32 v185, v213, v185, vcc
	v_lshlrev_b32_e32 v185, 2, v185
	ds_bpermute_b32 v185, v185, v183
	s_waitcnt lgkmcnt(0)
	v_add_f32_e32 v183, v183, v185
	v_fmamk_f32 v183, v183, 0x3c800000, v212
	v_rsq_f32_e32 v200, v183
	s_nop 0
	v_pk_mul_f32 v[158:159], v[158:159], v[200:201] op_sel_hi:[1,0]
	v_pk_mul_f32 v[160:161], v[160:161], v[200:201] op_sel_hi:[1,0]
	v_pk_mul_f32 v[158:159], v[142:143], v[158:159]
	v_pk_mul_f32 v[160:161], v[144:145], v[160:161]
	v_pk_mul_f32 v[142:143], v[154:155], v[200:201] op_sel_hi:[1,0]
	v_pk_mul_f32 v[144:145], v[156:157], v[200:201] op_sel_hi:[1,0]
	v_pk_mul_f32 v[154:155], v[138:139], v[142:143]
	v_pk_mul_f32 v[156:157], v[140:141], v[144:145]
	s_and_saveexec_b64 s[4:5], s[6:7]
	s_cbranch_execz .LBB0_543
	v_mov_b32_e32 v199, v169
	v_lshlrev_b64 v[138:139], 6, v[198:199]
	v_lshl_add_u64 v[142:143], v[174:175], 0, v[138:139]
	global_load_dwordx4 v[138:141], v[142:143], off offset:32
	s_nop 0
	global_load_dwordx4 v[142:145], v[142:143], off
	s_waitcnt vmcnt(1)
	v_pk_mul_f32 v[198:199], v[156:157], v[140:141]
	v_pk_mul_f32 v[202:203], v[154:155], v[138:139]
	v_pk_mul_f32 v[140:141], v[160:161], v[140:141]
	v_pk_mul_f32 v[138:139], v[158:159], v[138:139]
	s_waitcnt vmcnt(0)
	v_pk_fma_f32 v[160:161], v[160:161], v[144:145], v[198:199] neg_lo:[0,0,1] neg_hi:[0,0,1]
	v_pk_fma_f32 v[158:159], v[158:159], v[142:143], v[202:203] neg_lo:[0,0,1] neg_hi:[0,0,1]
	v_pk_fma_f32 v[156:157], v[156:157], v[144:145], v[140:141]
	v_pk_fma_f32 v[154:155], v[154:155], v[142:143], v[138:139]

; __device__ __forceinline__ unsigned cvt_pk_bf16(float lo, float hi) { unsigned r; asm volatile("v_cvt_pk_bf16_f32 %0, %1, %2" : "=v"(r) : "v"(lo), "v"(hi)); return r; }
; __device__ __forceinline__ float sigmoid_f(float x) { return __builtin_amdgcn_rcpf(1.f + __builtin_amdgcn_exp2f(-1.4426950408889634f * x)); }
;     __device__ __forceinline__ void operator()(const f32x4 (&acc)[2][2][4][2], const Unit& u, int wr, int wc, int fr, int fq) const {
;     ...
;                     const int row = row0 + ai * HALF + m * 16; const float r = __builtin_amdgcn_rsqf(rss[row] * (1.f / 1024.f) + NEPS);
;                     float o[8];
; #pragma unroll
;                     for (int n = 0; n < 2; ++n)
; #pragma unroll
;                         for (int e = 0; e < 4; ++e) o[4 * n + e] = (acc[ai][0][m][n][e] * r) * sigmoid_f(acc[ai][1][m][n][e] * r);
;                     u32x4 w; w.x = cvt_pk_bf16(o[0], o[1]); w.y = cvt_pk_bf16(o[2], o[3]); w.z = cvt_pk_bf16(o[4], o[5]); w.w = cvt_pk_bf16(o[6], o[7]);
;                     *(u32x4*)(U + (size_t)row * 512 + col0) = w;
;                     float* cp = nullptr;
;                     if (!samp) { const int t = row & 4095, b = row >> 12; if (t >= 4066) cp = out + 22806528 + ((size_t)(b * 30 + (t - 4066))) * 512 + col0; }
;                     else { const int sr = row - 16384; cp = out + 199028736 + ((size_t)((sr >> 2) * 30 + 26 + (sr & 3))) * 512 + col0; }
;                     if (cp) { *(f32x4*)cp = (f32x4){o[0], o[1], o[2], o[3]}; *(f32x4*)(cp + 4) = (f32x4){o[4], o[5], o[6], o[7]}; }
.LBB0_557:
	v_ashrrev_i32_e32 v183, 31, v182
	v_lshl_add_u64 v[132:133], v[182:183], 2, s[40:41]
	global_load_dword v236, v[132:133], off
	global_load_dword v237, v[132:133], off offset:64
	global_load_dword v238, v[132:133], off offset:128
	global_load_dword v239, v[132:133], off offset:192
	global_load_dword v240, v[132:133], off offset:512
	global_load_dword v241, v[132:133], off offset:576
	global_load_dword v242, v[132:133], off offset:640
	global_load_dword v243, v[132:133], off offset:704
	v_cndmask_b32_e64 v137, 0, 1, s[56:57]
	v_cmp_ne_u32_e64 s[12:13], 1, v137
	v_readlane_b32 s2, v250, 10
	v_lshl_or_b32 v130, s38, 7, v173
	v_lshlrev_b64 v[134:135], 10, v[182:183]
	v_readlane_b32 s3, v250, 11
	v_ashrrev_i32_e32 v131, 31, v130
	s_andn2_b64 vcc, exec, s[56:57]
	v_lshl_add_u64 v[134:135], s[2:3], 0, v[134:135]
	v_lshl_add_u64 v[134:135], v[130:131], 1, v[134:135]
	s_waitcnt vmcnt(0)
	v_mov_b32_e32 v136, v236
	v_fmamk_f32 v136, v136, 0x3a800000, v212
	v_rsq_f32_e32 v136, v136
	s_nop 0
	v_mul_f32_e32 v137, v118, v136
	v_mul_f32_e32 v138, v119, v136
	v_pk_mul_f32 v[118:119], v[126:127], v[136:137] op_sel_hi:[1,0]
	v_mul_f32_e32 v126, v120, v136
	v_mul_f32_e32 v127, v121, v136
	v_pk_mul_f32 v[120:121], v[128:129], v[136:137] op_sel_hi:[1,0]
	v_mul_f32_e32 v128, v114, v136
	v_mul_f32_e32 v129, v115, v136
	v_pk_mul_f32 v[114:115], v[122:123], v[136:137] op_sel_hi:[1,0]
	v_mul_f32_e32 v122, v116, v136
	v_mul_f32_e32 v123, v117, v136
	v_pk_mul_f32 v[116:117], v[124:125], v[136:137] op_sel_hi:[1,0]
	v_mul_f32_e32 v124, 0xbfb8aa3b, v137
	v_mul_f32_e32 v125, 0xbfb8aa3b, v138
	v_mul_f32_e32 v126, 0xbfb8aa3b, v126
	v_mul_f32_e32 v127, 0xbfb8aa3b, v127
	v_mul_f32_e32 v128, 0xbfb8aa3b, v128
	v_mul_f32_e32 v129, 0xbfb8aa3b, v129
	v_mul_f32_e32 v122, 0xbfb8aa3b, v122
	v_mul_f32_e32 v123, 0xbfb8aa3b, v123
	v_exp_f32_e32 v124, v124
	v_exp_f32_e32 v125, v125
	v_exp_f32_e32 v126, v126
	v_exp_f32_e32 v127, v127
	v_exp_f32_e32 v128, v128
	v_exp_f32_e32 v129, v129
	v_exp_f32_e32 v122, v122
	v_exp_f32_e32 v123, v123
	v_add_f32_e32 v124, 1.0, v124
	v_add_f32_e32 v125, 1.0, v125
	v_add_f32_e32 v126, 1.0, v126
	v_add_f32_e32 v127, 1.0, v127
	v_add_f32_e32 v128, 1.0, v128
	v_add_f32_e32 v129, 1.0, v129
	v_add_f32_e32 v136, 1.0, v122
	v_add_f32_e32 v137, 1.0, v123
	v_rcp_f32_e32 v122, v124
	v_rcp_f32_e32 v123, v125
	v_rcp_f32_e32 v124, v126
	v_rcp_f32_e32 v125, v127
	v_rcp_f32_e32 v126, v128
	v_rcp_f32_e32 v127, v129
	v_rcp_f32_e32 v128, v136
	v_rcp_f32_e32 v129, v137
	v_pk_mul_f32 v[118:119], v[118:119], v[122:123]
	v_pk_mul_f32 v[120:121], v[120:121], v[124:125]
	v_cvt_pk_bf16_f32 v122, v118, v119
	v_pk_mul_f32 v[114:115], v[114:115], v[126:127]
	v_cvt_pk_bf16_f32 v123, v120, v121
	v_pk_mul_f32 v[116:117], v[116:117], v[128:129]
	v_cvt_pk_bf16_f32 v124, v114, v115
	s_nop 0
	v_cvt_pk_bf16_f32 v125, v116, v117
	global_store_dwordx4 v[134:135], v[122:125], off
	s_nop 1
	v_mov_b64_e32 v[122:123], 0
	s_cbranch_vccnz .LBB0_559
	v_add_u32_e32 v122, 0xffffc000, v182
	v_ashrrev_i32_e32 v122, 2, v122
	v_mad_u64_u32 v[122:123], s[2:3], v122, 30, v[172:173]
	v_ashrrev_i32_e32 v123, 31, v122
	v_lshlrev_b64 v[122:123], 11, v[122:123]
	v_lshl_add_u64 v[122:123], s[22:23], 0, v[122:123]
	v_lshl_add_u64 v[122:123], v[130:131], 2, v[122:123]

; __device__ __forceinline__ unsigned cvt_pk_bf16(float lo, float hi) { unsigned r; asm volatile("v_cvt_pk_bf16_f32 %0, %1, %2" : "=v"(r) : "v"(lo), "v"(hi)); return r; }
; __device__ __forceinline__ float sigmoid_f(float x) { return __builtin_amdgcn_rcpf(1.f + __builtin_amdgcn_exp2f(-1.4426950408889634f * x)); }
;     __device__ __forceinline__ void operator()(const f32x4 (&acc)[2][2][4][2], const Unit& u, int wr, int wc, int fr, int fq) const {
;     ...
;                     const int row = row0 + ai * HALF + m * 16; const float r = __builtin_amdgcn_rsqf(rss[row] * (1.f / 1024.f) + NEPS);
;                     float o[8];
; #pragma unroll
;                     for (int n = 0; n < 2; ++n)
; #pragma unroll
;                         for (int e = 0; e < 4; ++e) o[4 * n + e] = (acc[ai][0][m][n][e] * r) * sigmoid_f(acc[ai][1][m][n][e] * r);
;                     u32x4 w; w.x = cvt_pk_bf16(o[0], o[1]); w.y = cvt_pk_bf16(o[2], o[3]); w.z = cvt_pk_bf16(o[4], o[5]); w.w = cvt_pk_bf16(o[6], o[7]);
;                     *(u32x4*)(U + (size_t)row * 512 + col0) = w;
;                     float* cp = nullptr;
;                     if (!samp) { const int t = row & 4095, b = row >> 12; if (t >= 4066) cp = out + 22806528 + ((size_t)(b * 30 + (t - 4066))) * 512 + col0; }
;                     else { const int sr = row - 16384; cp = out + 199028736 + ((size_t)((sr >> 2) * 30 + 26 + (sr & 3))) * 512 + col0; }
;                     if (cp) { *(f32x4*)cp = (f32x4){o[0], o[1], o[2], o[3]}; *(f32x4*)(cp + 4) = (f32x4){o[4], o[5], o[6], o[7]}; }
.LBB0_561:
	s_or_b64 exec, exec, s[2:3]
	s_nop 0
	v_or_b32_e32 v114, 16, v182
	v_ashrrev_i32_e32 v115, 31, v114
	v_lshl_add_u64 v[116:117], v[114:115], 2, s[40:41]
	s_nop 0
	v_readlane_b32 s2, v250, 10
	v_lshlrev_b64 v[114:115], 10, v[114:115]
	v_readlane_b32 s3, v250, 11
	s_and_b64 vcc, exec, s[12:13]
	s_waitcnt vmcnt(7)
	v_mov_b32_e32 v116, v237
	v_fmamk_f32 v116, v116, 0x3a800000, v212
	v_rsq_f32_e32 v116, v116
	v_lshl_add_u64 v[114:115], s[2:3], 0, v[114:115]
	v_lshl_add_u64 v[114:115], v[130:131], 1, v[114:115]
	v_mul_f32_e32 v117, v102, v116
	v_mul_f32_e32 v118, v103, v116
	v_pk_mul_f32 v[102:103], v[110:111], v[116:117] op_sel_hi:[1,0]
	v_mul_f32_e32 v110, v104, v116
	v_mul_f32_e32 v111, v105, v116
	v_pk_mul_f32 v[104:105], v[112:113], v[116:117] op_sel_hi:[1,0]
	v_mul_f32_e32 v112, v98, v116
	v_mul_f32_e32 v113, v99, v116
	v_pk_mul_f32 v[98:99], v[106:107], v[116:117] op_sel_hi:[1,0]
	v_mul_f32_e32 v106, v100, v116
	v_mul_f32_e32 v107, v101, v116
	v_pk_mul_f32 v[100:101], v[108:109], v[116:117] op_sel_hi:[1,0]
	v_mul_f32_e32 v108, 0xbfb8aa3b, v117
	v_mul_f32_e32 v109, 0xbfb8aa3b, v118
	v_mul_f32_e32 v110, 0xbfb8aa3b, v110
	v_mul_f32_e32 v111, 0xbfb8aa3b, v111
	v_mul_f32_e32 v112, 0xbfb8aa3b, v112
	v_mul_f32_e32 v113, 0xbfb8aa3b, v113
	v_mul_f32_e32 v106, 0xbfb8aa3b, v106
	v_mul_f32_e32 v107, 0xbfb8aa3b, v107
	v_exp_f32_e32 v108, v108
	v_exp_f32_e32 v109, v109
	v_exp_f32_e32 v110, v110
	v_exp_f32_e32 v111, v111
	v_exp_f32_e32 v112, v112
	v_exp_f32_e32 v113, v113
	v_exp_f32_e32 v106, v106
	v_exp_f32_e32 v107, v107
	v_add_f32_e32 v108, 1.0, v108
	v_add_f32_e32 v109, 1.0, v109
	v_add_f32_e32 v110, 1.0, v110
	v_add_f32_e32 v111, 1.0, v111
	v_add_f32_e32 v112, 1.0, v112
	v_add_f32_e32 v113, 1.0, v113
	v_add_f32_e32 v116, 1.0, v106
	v_add_f32_e32 v117, 1.0, v107
	v_rcp_f32_e32 v106, v108
	v_rcp_f32_e32 v107, v109
	v_rcp_f32_e32 v108, v110
	v_rcp_f32_e32 v109, v111
	v_rcp_f32_e32 v110, v112
	v_rcp_f32_e32 v111, v113
	v_rcp_f32_e32 v112, v116
	v_rcp_f32_e32 v113, v117
	v_pk_mul_f32 v[102:103], v[102:103], v[106:107]
	v_pk_mul_f32 v[104:105], v[104:105], v[108:109]
	v_cvt_pk_bf16_f32 v106, v102, v103
	v_pk_mul_f32 v[98:99], v[98:99], v[110:111]
	v_cvt_pk_bf16_f32 v107, v104, v105
	v_pk_mul_f32 v[100:101], v[100:101], v[112:113]
	v_cvt_pk_bf16_f32 v108, v98, v99
	s_nop 0
	v_cvt_pk_bf16_f32 v109, v100, v101
	global_store_dwordx4 v[114:115], v[106:109], off
	s_nop 1
	v_mov_b64_e32 v[106:107], 0
	s_cbranch_vccnz .LBB0_563
	v_add_u32_e32 v106, 0xffffc010, v182
	v_ashrrev_i32_e32 v106, 2, v106
	v_mad_u64_u32 v[106:107], s[2:3], v106, 30, v[172:173]
	v_ashrrev_i32_e32 v107, 31, v106
	v_lshlrev_b64 v[106:107], 11, v[106:107]
	v_lshl_add_u64 v[106:107], s[22:23], 0, v[106:107]
	v_lshl_add_u64 v[106:107], v[130:131], 2, v[106:107]

; __device__ __forceinline__ unsigned cvt_pk_bf16(float lo, float hi) { unsigned r; asm volatile("v_cvt_pk_bf16_f32 %0, %1, %2" : "=v"(r) : "v"(lo), "v"(hi)); return r; }
; __device__ __forceinline__ float sigmoid_f(float x) { return __builtin_amdgcn_rcpf(1.f + __builtin_amdgcn_exp2f(-1.4426950408889634f * x)); }
;     __device__ __forceinline__ void operator()(const f32x4 (&acc)[2][2][4][2], const Unit& u, int wr, int wc, int fr, int fq) const {
;     ...
;                     const int row = row0 + ai * HALF + m * 16; const float r = __builtin_amdgcn_rsqf(rss[row] * (1.f / 1024.f) + NEPS);
;                     float o[8];
; #pragma unroll
;                     for (int n = 0; n < 2; ++n)
; #pragma unroll
;                         for (int e = 0; e < 4; ++e) o[4 * n + e] = (acc[ai][0][m][n][e] * r) * sigmoid_f(acc[ai][1][m][n][e] * r);
;                     u32x4 w; w.x = cvt_pk_bf16(o[0], o[1]); w.y = cvt_pk_bf16(o[2], o[3]); w.z = cvt_pk_bf16(o[4], o[5]); w.w = cvt_pk_bf16(o[6], o[7]);
;                     *(u32x4*)(U + (size_t)row * 512 + col0) = w;
;                     float* cp = nullptr;
;                     if (!samp) { const int t = row & 4095, b = row >> 12; if (t >= 4066) cp = out + 22806528 + ((size_t)(b * 30 + (t - 4066))) * 512 + col0; }
;                     else { const int sr = row - 16384; cp = out + 199028736 + ((size_t)((sr >> 2) * 30 + 26 + (sr & 3))) * 512 + col0; }
;                     if (cp) { *(f32x4*)cp = (f32x4){o[0], o[1], o[2], o[3]}; *(f32x4*)(cp + 4) = (f32x4){o[4], o[5], o[6], o[7]}; }
.LBB0_565:
	s_or_b64 exec, exec, s[2:3]
	s_nop 0
	v_or_b32_e32 v98, 32, v182
	v_ashrrev_i32_e32 v99, 31, v98
	v_lshl_add_u64 v[100:101], v[98:99], 2, s[40:41]
	s_nop 0
	v_cndmask_b32_e64 v100, 0, 1, s[54:55]
	v_cmp_ne_u32_e64 s[10:11], 1, v100
	v_lshlrev_b64 v[100:101], 10, v[98:99]
	v_readlane_b32 s2, v250, 10
	s_ashr_i32 s0, s29, 12
	v_readlane_b32 s3, v250, 11
	s_mul_i32 s0, s0, 30
	s_addk_i32 s0, 0xf01e
	v_lshl_add_u64 v[100:101], s[2:3], 0, v[100:101]
	s_andn2_b64 vcc, exec, s[54:55]
	v_lshl_add_u64 v[100:101], v[130:131], 1, v[100:101]
	s_mov_b64 s[2:3], -1
	s_waitcnt vmcnt(7)
	v_mov_b32_e32 v102, v238
	v_fmamk_f32 v99, v102, 0x3a800000, v212
	v_rsq_f32_e32 v102, v99
	s_nop 0
	v_mul_f32_e32 v103, v87, v102
	v_mul_f32_e32 v99, v86, v102
	v_pk_mul_f32 v[86:87], v[94:95], v[102:103] op_sel_hi:[1,0]
	v_mul_f32_e32 v94, v88, v102
	v_mul_f32_e32 v95, v89, v102
	v_pk_mul_f32 v[88:89], v[96:97], v[102:103] op_sel_hi:[1,0]
	v_mul_f32_e32 v96, v82, v102
	v_mul_f32_e32 v97, v83, v102
	v_pk_mul_f32 v[82:83], v[90:91], v[102:103] op_sel_hi:[1,0]
	v_mul_f32_e32 v90, v84, v102
	v_mul_f32_e32 v91, v85, v102
	v_pk_mul_f32 v[84:85], v[92:93], v[102:103] op_sel_hi:[1,0]
	v_mul_f32_e32 v92, 0xbfb8aa3b, v99
	v_mul_f32_e32 v93, 0xbfb8aa3b, v103
	v_mul_f32_e32 v94, 0xbfb8aa3b, v94
	v_mul_f32_e32 v95, 0xbfb8aa3b, v95
	v_mul_f32_e32 v96, 0xbfb8aa3b, v96
	v_mul_f32_e32 v97, 0xbfb8aa3b, v97
	v_mul_f32_e32 v90, 0xbfb8aa3b, v90
	v_mul_f32_e32 v91, 0xbfb8aa3b, v91
	v_exp_f32_e32 v92, v92
	v_exp_f32_e32 v93, v93
	v_exp_f32_e32 v94, v94
	v_exp_f32_e32 v95, v95
	v_exp_f32_e32 v96, v96
	v_exp_f32_e32 v97, v97
	v_exp_f32_e32 v90, v90
	v_exp_f32_e32 v91, v91
	v_add_f32_e32 v92, 1.0, v92
	v_add_f32_e32 v93, 1.0, v93
	v_add_f32_e32 v94, 1.0, v94
	v_add_f32_e32 v95, 1.0, v95
	v_add_f32_e32 v96, 1.0, v96
	v_add_f32_e32 v97, 1.0, v97
	v_add_f32_e32 v99, 1.0, v90
	v_add_f32_e32 v102, 1.0, v91
	v_rcp_f32_e32 v90, v92
	v_rcp_f32_e32 v91, v93
	v_rcp_f32_e32 v92, v94
	v_rcp_f32_e32 v93, v95
	v_rcp_f32_e32 v94, v96
	v_rcp_f32_e32 v95, v97
	v_rcp_f32_e32 v96, v99
	v_rcp_f32_e32 v97, v102
	v_pk_mul_f32 v[86:87], v[86:87], v[90:91]
	v_pk_mul_f32 v[88:89], v[88:89], v[92:93]
	v_pk_mul_f32 v[82:83], v[82:83], v[94:95]
	v_pk_mul_f32 v[84:85], v[84:85], v[96:97]
	v_cvt_pk_bf16_f32 v90, v86, v87
	v_cvt_pk_bf16_f32 v91, v88, v89
	v_cvt_pk_bf16_f32 v92, v82, v83
	s_nop 0
	v_cvt_pk_bf16_f32 v93, v84, v85
	global_store_dwordx4 v[100:101], v[90:93], off
	s_cbranch_vccnz .LBB0_592
	s_nop 0
	v_and_b32_e32 v92, 0xfef, v98
	v_add_u32_e32 v90, s0, v92
	v_ashrrev_i32_e32 v91, 31, v90
	v_lshlrev_b64 v[90:91], 11, v[90:91]
	v_lshl_add_u64 v[90:91], s[24:25], 0, v[90:91]
	v_lshl_add_u64 v[90:91], v[130:131], 2, v[90:91]
	v_cmp_lt_u32_e32 vcc, s91, v92
	s_nop 1
	v_cndmask_b32_e32 v91, 0, v91, vcc
	v_cndmask_b32_e32 v90, 0, v90, vcc
	s_cbranch_execz .LBB0_593

; __device__ __forceinline__ unsigned cvt_pk_bf16(float lo, float hi) { unsigned r; asm volatile("v_cvt_pk_bf16_f32 %0, %1, %2" : "=v"(r) : "v"(lo), "v"(hi)); return r; }
; __device__ __forceinline__ float sigmoid_f(float x) { return __builtin_amdgcn_rcpf(1.f + __builtin_amdgcn_exp2f(-1.4426950408889634f * x)); }
;     __device__ __forceinline__ void operator()(const f32x4 (&acc)[2][2][4][2], const Unit& u, int wr, int wc, int fr, int fq) const {
;     ...
;                     const int row = row0 + ai * HALF + m * 16; const float r = __builtin_amdgcn_rsqf(rss[row] * (1.f / 1024.f) + NEPS);
;                     float o[8];
; #pragma unroll
;                     for (int n = 0; n < 2; ++n)
; #pragma unroll
;                         for (int e = 0; e < 4; ++e) o[4 * n + e] = (acc[ai][0][m][n][e] * r) * sigmoid_f(acc[ai][1][m][n][e] * r);
;                     u32x4 w; w.x = cvt_pk_bf16(o[0], o[1]); w.y = cvt_pk_bf16(o[2], o[3]); w.z = cvt_pk_bf16(o[4], o[5]); w.w = cvt_pk_bf16(o[6], o[7]);
;                     *(u32x4*)(U + (size_t)row * 512 + col0) = w;
;                     float* cp = nullptr;
;                     if (!samp) { const int t = row & 4095, b = row >> 12; if (t >= 4066) cp = out + 22806528 + ((size_t)(b * 30 + (t - 4066))) * 512 + col0; }
;                     else { const int sr = row - 16384; cp = out + 199028736 + ((size_t)((sr >> 2) * 30 + 26 + (sr & 3))) * 512 + col0; }
;                     if (cp) { *(f32x4*)cp = (f32x4){o[0], o[1], o[2], o[3]}; *(f32x4*)(cp + 4) = (f32x4){o[4], o[5], o[6], o[7]}; }
.LBB0_569:
	s_or_b64 exec, exec, s[2:3]
	s_nop 0
	v_or_b32_e32 v82, 48, v182
	v_ashrrev_i32_e32 v83, 31, v82
	v_lshl_add_u64 v[84:85], v[82:83], 2, s[40:41]
	s_nop 0
	v_lshlrev_b64 v[86:87], 10, v[82:83]
	v_readlane_b32 s2, v250, 10
	v_readlane_b32 s3, v250, 11
	s_and_b64 vcc, exec, s[10:11]
	s_waitcnt vmcnt(7)
	v_mov_b32_e32 v84, v239
	v_fmamk_f32 v84, v84, 0x3a800000, v212
	v_rsq_f32_e32 v84, v84
	v_lshl_add_u64 v[86:87], s[2:3], 0, v[86:87]
	v_lshl_add_u64 v[86:87], v[130:131], 1, v[86:87]
	s_mov_b64 s[2:3], -1
	v_mul_f32_e32 v85, v71, v84
	v_mul_f32_e32 v83, v70, v84
	v_pk_mul_f32 v[70:71], v[78:79], v[84:85] op_sel_hi:[1,0]
	v_mul_f32_e32 v78, v72, v84
	v_mul_f32_e32 v79, v73, v84
	v_pk_mul_f32 v[72:73], v[80:81], v[84:85] op_sel_hi:[1,0]
	v_mul_f32_e32 v80, v66, v84
	v_mul_f32_e32 v81, v67, v84
	v_pk_mul_f32 v[66:67], v[74:75], v[84:85] op_sel_hi:[1,0]
	v_mul_f32_e32 v74, v68, v84
	v_mul_f32_e32 v75, v69, v84
	v_pk_mul_f32 v[68:69], v[76:77], v[84:85] op_sel_hi:[1,0]
	v_mul_f32_e32 v76, 0xbfb8aa3b, v83
	v_mul_f32_e32 v77, 0xbfb8aa3b, v85
	v_mul_f32_e32 v78, 0xbfb8aa3b, v78
	v_mul_f32_e32 v79, 0xbfb8aa3b, v79
	v_mul_f32_e32 v80, 0xbfb8aa3b, v80
	v_mul_f32_e32 v81, 0xbfb8aa3b, v81
	v_mul_f32_e32 v74, 0xbfb8aa3b, v74
	v_mul_f32_e32 v75, 0xbfb8aa3b, v75
	v_exp_f32_e32 v76, v76
	v_exp_f32_e32 v77, v77
	v_exp_f32_e32 v78, v78
	v_exp_f32_e32 v79, v79
	v_exp_f32_e32 v80, v80
	v_exp_f32_e32 v81, v81
	v_exp_f32_e32 v74, v74
	v_exp_f32_e32 v75, v75
	v_add_f32_e32 v76, 1.0, v76
	v_add_f32_e32 v77, 1.0, v77
	v_add_f32_e32 v78, 1.0, v78
	v_add_f32_e32 v79, 1.0, v79
	v_add_f32_e32 v80, 1.0, v80
	v_add_f32_e32 v81, 1.0, v81
	v_add_f32_e32 v83, 1.0, v74
	v_add_f32_e32 v84, 1.0, v75
	v_rcp_f32_e32 v74, v76
	v_rcp_f32_e32 v75, v77
	v_rcp_f32_e32 v76, v78
	v_rcp_f32_e32 v77, v79
	v_rcp_f32_e32 v78, v80
	v_rcp_f32_e32 v79, v81
	v_rcp_f32_e32 v80, v83
	v_rcp_f32_e32 v81, v84
	v_pk_mul_f32 v[70:71], v[70:71], v[74:75]
	v_pk_mul_f32 v[72:73], v[72:73], v[76:77]
	v_pk_mul_f32 v[66:67], v[66:67], v[78:79]
	v_pk_mul_f32 v[68:69], v[68:69], v[80:81]
	v_cvt_pk_bf16_f32 v74, v70, v71
	v_cvt_pk_bf16_f32 v75, v72, v73
	v_cvt_pk_bf16_f32 v76, v66, v67
	s_nop 0
	v_cvt_pk_bf16_f32 v77, v68, v69
	global_store_dwordx4 v[86:87], v[74:77], off
	s_cbranch_vccnz .LBB0_594
	s_nop 0
	v_and_b32_e32 v76, 0xfff, v82
	v_add_u32_e32 v74, s0, v76
	v_ashrrev_i32_e32 v75, 31, v74
	v_lshlrev_b64 v[74:75], 11, v[74:75]
	v_lshl_add_u64 v[74:75], s[24:25], 0, v[74:75]
	v_lshl_add_u64 v[74:75], v[130:131], 2, v[74:75]
	v_cmp_lt_u32_e32 vcc, s91, v76
	s_nop 1
	v_cndmask_b32_e32 v75, 0, v75, vcc
	v_cndmask_b32_e32 v74, 0, v74, vcc
	s_cbranch_execz .LBB0_595

; __device__ __forceinline__ unsigned cvt_pk_bf16(float lo, float hi) { unsigned r; asm volatile("v_cvt_pk_bf16_f32 %0, %1, %2" : "=v"(r) : "v"(lo), "v"(hi)); return r; }
; __device__ __forceinline__ float sigmoid_f(float x) { return __builtin_amdgcn_rcpf(1.f + __builtin_amdgcn_exp2f(-1.4426950408889634f * x)); }
;     __device__ __forceinline__ void operator()(const f32x4 (&acc)[2][2][4][2], const Unit& u, int wr, int wc, int fr, int fq) const {
;     ...
;                     const int row = row0 + ai * HALF + m * 16; const float r = __builtin_amdgcn_rsqf(rss[row] * (1.f / 1024.f) + NEPS);
;                     float o[8];
; #pragma unroll
;                     for (int n = 0; n < 2; ++n)
; #pragma unroll
;                         for (int e = 0; e < 4; ++e) o[4 * n + e] = (acc[ai][0][m][n][e] * r) * sigmoid_f(acc[ai][1][m][n][e] * r);
;                     u32x4 w; w.x = cvt_pk_bf16(o[0], o[1]); w.y = cvt_pk_bf16(o[2], o[3]); w.z = cvt_pk_bf16(o[4], o[5]); w.w = cvt_pk_bf16(o[6], o[7]);
;                     *(u32x4*)(U + (size_t)row * 512 + col0) = w;
;                     float* cp = nullptr;
;                     if (!samp) { const int t = row & 4095, b = row >> 12; if (t >= 4066) cp = out + 22806528 + ((size_t)(b * 30 + (t - 4066))) * 512 + col0; }
;                     else { const int sr = row - 16384; cp = out + 199028736 + ((size_t)((sr >> 2) * 30 + 26 + (sr & 3))) * 512 + col0; }
;                     if (cp) { *(f32x4*)cp = (f32x4){o[0], o[1], o[2], o[3]}; *(f32x4*)(cp + 4) = (f32x4){o[4], o[5], o[6], o[7]}; }
.LBB0_573:
	s_or_b64 exec, exec, s[2:3]
	s_nop 0
	v_add_u32_e32 v66, 0x80, v182
	v_ashrrev_i32_e32 v67, 31, v66
	v_lshlrev_b64 v[70:71], 10, v[66:67]
	v_readlane_b32 s2, v250, 10
	v_readlane_b32 s3, v250, 11
	s_and_b64 vcc, exec, s[12:13]
	s_waitcnt vmcnt(7)
	v_mov_b32_e32 v68, v240
	v_fmamk_f32 v68, v68, 0x3a800000, v212
	v_rsq_f32_e32 v68, v68
	v_lshl_add_u64 v[70:71], s[2:3], 0, v[70:71]
	v_lshl_add_u64 v[70:71], v[130:131], 1, v[70:71]
	v_mul_f32_e32 v69, v55, v68
	v_mul_f32_e32 v67, v54, v68
	v_pk_mul_f32 v[54:55], v[62:63], v[68:69] op_sel_hi:[1,0]
	v_mul_f32_e32 v62, v56, v68
	v_mul_f32_e32 v63, v57, v68
	v_pk_mul_f32 v[56:57], v[64:65], v[68:69] op_sel_hi:[1,0]
	v_mul_f32_e32 v64, v50, v68
	v_mul_f32_e32 v65, v51, v68
	v_pk_mul_f32 v[50:51], v[58:59], v[68:69] op_sel_hi:[1,0]
	v_mul_f32_e32 v58, v52, v68
	v_mul_f32_e32 v59, v53, v68
	v_pk_mul_f32 v[52:53], v[60:61], v[68:69] op_sel_hi:[1,0]
	v_mul_f32_e32 v60, 0xbfb8aa3b, v67
	v_mul_f32_e32 v61, 0xbfb8aa3b, v69
	v_mul_f32_e32 v62, 0xbfb8aa3b, v62
	v_mul_f32_e32 v63, 0xbfb8aa3b, v63
	v_mul_f32_e32 v64, 0xbfb8aa3b, v64
	v_mul_f32_e32 v65, 0xbfb8aa3b, v65
	v_mul_f32_e32 v58, 0xbfb8aa3b, v58
	v_mul_f32_e32 v59, 0xbfb8aa3b, v59
	v_exp_f32_e32 v60, v60
	v_exp_f32_e32 v61, v61
	v_exp_f32_e32 v62, v62
	v_exp_f32_e32 v63, v63
	v_exp_f32_e32 v64, v64
	v_exp_f32_e32 v65, v65
	v_exp_f32_e32 v58, v58
	v_exp_f32_e32 v59, v59
	v_add_f32_e32 v60, 1.0, v60
	v_add_f32_e32 v61, 1.0, v61
	v_add_f32_e32 v62, 1.0, v62
	v_add_f32_e32 v63, 1.0, v63
	v_add_f32_e32 v64, 1.0, v64
	v_add_f32_e32 v65, 1.0, v65
	v_add_f32_e32 v67, 1.0, v58
	v_add_f32_e32 v68, 1.0, v59
	v_rcp_f32_e32 v58, v60
	v_rcp_f32_e32 v59, v61
	v_rcp_f32_e32 v60, v62
	v_rcp_f32_e32 v61, v63
	v_rcp_f32_e32 v62, v64
	v_rcp_f32_e32 v63, v65
	v_rcp_f32_e32 v64, v67
	v_rcp_f32_e32 v65, v68
	v_pk_mul_f32 v[54:55], v[54:55], v[58:59]
	v_pk_mul_f32 v[56:57], v[56:57], v[60:61]
	v_cvt_pk_bf16_f32 v58, v54, v55
	v_pk_mul_f32 v[50:51], v[50:51], v[62:63]
	v_cvt_pk_bf16_f32 v59, v56, v57
	v_pk_mul_f32 v[52:53], v[52:53], v[64:65]
	v_cvt_pk_bf16_f32 v60, v50, v51
	s_nop 0
	v_cvt_pk_bf16_f32 v61, v52, v53
	global_store_dwordx4 v[70:71], v[58:61], off
	s_nop 1
	v_mov_b64_e32 v[58:59], 0
	s_cbranch_vccnz .LBB0_575
	v_add_u32_e32 v58, 0xffffc080, v182
	v_ashrrev_i32_e32 v58, 2, v58
	v_mad_u64_u32 v[58:59], s[2:3], v58, 30, v[172:173]
	v_ashrrev_i32_e32 v59, 31, v58
	v_lshlrev_b64 v[58:59], 11, v[58:59]
	v_lshl_add_u64 v[58:59], s[22:23], 0, v[58:59]
	v_lshl_add_u64 v[58:59], v[130:131], 2, v[58:59]

; __device__ __forceinline__ unsigned cvt_pk_bf16(float lo, float hi) { unsigned r; asm volatile("v_cvt_pk_bf16_f32 %0, %1, %2" : "=v"(r) : "v"(lo), "v"(hi)); return r; }
; __device__ __forceinline__ float sigmoid_f(float x) { return __builtin_amdgcn_rcpf(1.f + __builtin_amdgcn_exp2f(-1.4426950408889634f * x)); }
;     __device__ __forceinline__ void operator()(const f32x4 (&acc)[2][2][4][2], const Unit& u, int wr, int wc, int fr, int fq) const {
;     ...
;                     const int row = row0 + ai * HALF + m * 16; const float r = __builtin_amdgcn_rsqf(rss[row] * (1.f / 1024.f) + NEPS);
;                     float o[8];
; #pragma unroll
;                     for (int n = 0; n < 2; ++n)
; #pragma unroll
;                         for (int e = 0; e < 4; ++e) o[4 * n + e] = (acc[ai][0][m][n][e] * r) * sigmoid_f(acc[ai][1][m][n][e] * r);
;                     u32x4 w; w.x = cvt_pk_bf16(o[0], o[1]); w.y = cvt_pk_bf16(o[2], o[3]); w.z = cvt_pk_bf16(o[4], o[5]); w.w = cvt_pk_bf16(o[6], o[7]);
;                     *(u32x4*)(U + (size_t)row * 512 + col0) = w;
;                     float* cp = nullptr;
;                     if (!samp) { const int t = row & 4095, b = row >> 12; if (t >= 4066) cp = out + 22806528 + ((size_t)(b * 30 + (t - 4066))) * 512 + col0; }
;                     else { const int sr = row - 16384; cp = out + 199028736 + ((size_t)((sr >> 2) * 30 + 26 + (sr & 3))) * 512 + col0; }
;                     if (cp) { *(f32x4*)cp = (f32x4){o[0], o[1], o[2], o[3]}; *(f32x4*)(cp + 4) = (f32x4){o[4], o[5], o[6], o[7]}; }
.LBB0_577:
	s_or_b64 exec, exec, s[2:3]
	s_nop 0
	v_readlane_b32 s2, v250, 10
	v_lshlrev_b64 v[50:51], 10, v[182:183]
	v_readlane_b32 s3, v250, 11
	s_waitcnt vmcnt(7)
	v_mov_b32_e32 v52, v241
	v_fmamk_f32 v52, v52, 0x3a800000, v212
	v_rsq_f32_e32 v52, v52
	v_lshl_add_u64 v[50:51], s[2:3], 0, v[50:51]
	v_lshl_add_u64 v[50:51], v[130:131], 1, v[50:51]
	v_add_co_u32_e32 v50, vcc, 0x24000, v50
	v_mul_f32_e32 v53, v38, v52
	v_mul_f32_e32 v54, v39, v52
	v_pk_mul_f32 v[38:39], v[46:47], v[52:53] op_sel_hi:[1,0]
	v_mul_f32_e32 v46, v40, v52
	v_mul_f32_e32 v47, v41, v52
	v_pk_mul_f32 v[40:41], v[48:49], v[52:53] op_sel_hi:[1,0]
	v_mul_f32_e32 v48, v34, v52
	v_mul_f32_e32 v49, v35, v52
	v_pk_mul_f32 v[34:35], v[42:43], v[52:53] op_sel_hi:[1,0]
	v_mul_f32_e32 v42, v36, v52
	v_mul_f32_e32 v43, v37, v52
	v_pk_mul_f32 v[36:37], v[44:45], v[52:53] op_sel_hi:[1,0]
	v_mul_f32_e32 v44, 0xbfb8aa3b, v53
	v_mul_f32_e32 v45, 0xbfb8aa3b, v54
	v_mul_f32_e32 v46, 0xbfb8aa3b, v46
	v_mul_f32_e32 v47, 0xbfb8aa3b, v47
	v_mul_f32_e32 v48, 0xbfb8aa3b, v48
	v_mul_f32_e32 v49, 0xbfb8aa3b, v49
	v_mul_f32_e32 v42, 0xbfb8aa3b, v42
	v_mul_f32_e32 v43, 0xbfb8aa3b, v43
	v_exp_f32_e32 v44, v44
	v_exp_f32_e32 v45, v45
	v_exp_f32_e32 v46, v46
	v_exp_f32_e32 v47, v47
	v_exp_f32_e32 v48, v48
	v_exp_f32_e32 v49, v49
	v_exp_f32_e32 v42, v42
	v_exp_f32_e32 v43, v43
	v_add_f32_e32 v44, 1.0, v44
	v_add_f32_e32 v45, 1.0, v45
	v_add_f32_e32 v46, 1.0, v46
	v_add_f32_e32 v47, 1.0, v47
	v_add_f32_e32 v48, 1.0, v48
	v_add_f32_e32 v49, 1.0, v49
	v_add_f32_e32 v52, 1.0, v42
	v_add_f32_e32 v53, 1.0, v43
	v_rcp_f32_e32 v42, v44
	v_rcp_f32_e32 v43, v45
	v_rcp_f32_e32 v44, v46
	v_rcp_f32_e32 v45, v47
	v_rcp_f32_e32 v46, v48
	v_rcp_f32_e32 v47, v49
	v_rcp_f32_e32 v48, v52
	v_rcp_f32_e32 v49, v53
	s_mov_b64 s[14:15], vcc
	s_and_b64 vcc, exec, s[12:13]
	v_addc_co_u32_e64 v51, s[12:13], 0, v51, s[14:15]
	v_pk_mul_f32 v[38:39], v[38:39], v[42:43]
	v_pk_mul_f32 v[40:41], v[40:41], v[44:45]
	v_cvt_pk_bf16_f32 v42, v38, v39
	v_pk_mul_f32 v[34:35], v[34:35], v[46:47]
	v_cvt_pk_bf16_f32 v43, v40, v41
	v_pk_mul_f32 v[36:37], v[36:37], v[48:49]
	v_cvt_pk_bf16_f32 v44, v34, v35
	s_nop 0
	v_cvt_pk_bf16_f32 v45, v36, v37
	global_store_dwordx4 v[50:51], v[42:45], off
	s_nop 1
	v_mov_b64_e32 v[42:43], 0
	s_cbranch_vccnz .LBB0_579
	v_add_u32_e32 v42, 0xffffc090, v182
	v_ashrrev_i32_e32 v42, 2, v42
	v_mad_u64_u32 v[42:43], s[2:3], v42, 30, v[172:173]
	v_ashrrev_i32_e32 v43, 31, v42
	v_lshlrev_b64 v[42:43], 11, v[42:43]
	v_lshl_add_u64 v[42:43], s[22:23], 0, v[42:43]
	v_lshl_add_u64 v[42:43], v[130:131], 2, v[42:43]

; __device__ __forceinline__ unsigned cvt_pk_bf16(float lo, float hi) { unsigned r; asm volatile("v_cvt_pk_bf16_f32 %0, %1, %2" : "=v"(r) : "v"(lo), "v"(hi)); return r; }
; __device__ __forceinline__ float sigmoid_f(float x) { return __builtin_amdgcn_rcpf(1.f + __builtin_amdgcn_exp2f(-1.4426950408889634f * x)); }
;     __device__ __forceinline__ void operator()(const f32x4 (&acc)[2][2][4][2], const Unit& u, int wr, int wc, int fr, int fq) const {
;     ...
;                     const int row = row0 + ai * HALF + m * 16; const float r = __builtin_amdgcn_rsqf(rss[row] * (1.f / 1024.f) + NEPS);
;                     float o[8];
; #pragma unroll
;                     for (int n = 0; n < 2; ++n)
; #pragma unroll
;                         for (int e = 0; e < 4; ++e) o[4 * n + e] = (acc[ai][0][m][n][e] * r) * sigmoid_f(acc[ai][1][m][n][e] * r);
;                     u32x4 w; w.x = cvt_pk_bf16(o[0], o[1]); w.y = cvt_pk_bf16(o[2], o[3]); w.z = cvt_pk_bf16(o[4], o[5]); w.w = cvt_pk_bf16(o[6], o[7]);
;                     *(u32x4*)(U + (size_t)row * 512 + col0) = w;
;                     float* cp = nullptr;
;                     if (!samp) { const int t = row & 4095, b = row >> 12; if (t >= 4066) cp = out + 22806528 + ((size_t)(b * 30 + (t - 4066))) * 512 + col0; }
;                     else { const int sr = row - 16384; cp = out + 199028736 + ((size_t)((sr >> 2) * 30 + 26 + (sr & 3))) * 512 + col0; }
;                     if (cp) { *(f32x4*)cp = (f32x4){o[0], o[1], o[2], o[3]}; *(f32x4*)(cp + 4) = (f32x4){o[4], o[5], o[6], o[7]}; }
.LBB0_581:
	s_or_b64 exec, exec, s[2:3]
	s_nop 0
	v_ashrrev_i32_e32 v35, 12, v66
	v_add_u32_e32 v34, 0xa0, v182
	v_mad_i32_i24 v36, v35, 30, v214
	v_ashrrev_i32_e32 v35, 31, v34
	v_lshlrev_b64 v[40:41], 10, v[34:35]
	v_readlane_b32 s2, v250, 10
	v_readlane_b32 s3, v250, 11
	s_and_b64 vcc, exec, s[10:11]
	s_waitcnt vmcnt(7)
	v_mov_b32_e32 v37, v242
	v_fmamk_f32 v37, v37, 0x3a800000, v212
	v_rsq_f32_e32 v38, v37
	v_lshl_add_u64 v[40:41], s[2:3], 0, v[40:41]
	v_lshl_add_u64 v[40:41], v[130:131], 1, v[40:41]
	s_mov_b64 s[2:3], -1
	v_mul_f32_e32 v35, v22, v38
	v_mul_f32_e32 v37, v23, v38
	v_pk_mul_f32 v[22:23], v[30:31], v[38:39] op_sel_hi:[1,0]
	v_mul_f32_e32 v30, v24, v38
	v_mul_f32_e32 v31, v25, v38
	v_pk_mul_f32 v[24:25], v[32:33], v[38:39] op_sel_hi:[1,0]
	v_mul_f32_e32 v32, v18, v38
	v_mul_f32_e32 v33, v19, v38
	v_pk_mul_f32 v[18:19], v[26:27], v[38:39] op_sel_hi:[1,0]
	v_mul_f32_e32 v26, v20, v38
	v_mul_f32_e32 v27, v21, v38
	v_pk_mul_f32 v[20:21], v[28:29], v[38:39] op_sel_hi:[1,0]
	v_mul_f32_e32 v28, 0xbfb8aa3b, v35
	v_mul_f32_e32 v29, 0xbfb8aa3b, v37
	v_mul_f32_e32 v30, 0xbfb8aa3b, v30
	v_mul_f32_e32 v31, 0xbfb8aa3b, v31
	v_mul_f32_e32 v32, 0xbfb8aa3b, v32
	v_mul_f32_e32 v33, 0xbfb8aa3b, v33
	v_mul_f32_e32 v26, 0xbfb8aa3b, v26
	v_mul_f32_e32 v27, 0xbfb8aa3b, v27
	v_exp_f32_e32 v28, v28
	v_exp_f32_e32 v29, v29
	v_exp_f32_e32 v30, v30
	v_exp_f32_e32 v31, v31
	v_exp_f32_e32 v32, v32
	v_exp_f32_e32 v33, v33
	v_exp_f32_e32 v26, v26
	v_exp_f32_e32 v27, v27
	v_add_f32_e32 v28, 1.0, v28
	v_add_f32_e32 v29, 1.0, v29
	v_add_f32_e32 v30, 1.0, v30
	v_add_f32_e32 v31, 1.0, v31
	v_add_f32_e32 v32, 1.0, v32
	v_add_f32_e32 v33, 1.0, v33
	v_add_f32_e32 v35, 1.0, v26
	v_add_f32_e32 v37, 1.0, v27
	v_rcp_f32_e32 v26, v28
	v_rcp_f32_e32 v27, v29
	v_rcp_f32_e32 v28, v30
	v_rcp_f32_e32 v29, v31
	v_rcp_f32_e32 v30, v32
	v_rcp_f32_e32 v31, v33
	v_rcp_f32_e32 v32, v35
	v_rcp_f32_e32 v33, v37
	v_pk_mul_f32 v[22:23], v[22:23], v[26:27]
	v_pk_mul_f32 v[24:25], v[24:25], v[28:29]
	v_pk_mul_f32 v[18:19], v[18:19], v[30:31]
	v_pk_mul_f32 v[20:21], v[20:21], v[32:33]
	v_cvt_pk_bf16_f32 v26, v22, v23
	v_cvt_pk_bf16_f32 v27, v24, v25
	v_cvt_pk_bf16_f32 v28, v18, v19
	s_nop 0
	v_cvt_pk_bf16_f32 v29, v20, v21
	global_store_dwordx4 v[40:41], v[26:29], off
	s_cbranch_vccnz .LBB0_596
	s_nop 0
	v_and_b32_e32 v28, 0xfef, v34
	v_add_u32_e32 v26, v36, v28
	v_ashrrev_i32_e32 v27, 31, v26
	v_lshlrev_b64 v[26:27], 11, v[26:27]
	v_lshl_add_u64 v[26:27], s[24:25], 0, v[26:27]
	v_lshl_add_u64 v[26:27], v[130:131], 2, v[26:27]
	v_cmp_lt_u32_e32 vcc, s91, v28
	s_nop 1
	v_cndmask_b32_e32 v27, 0, v27, vcc
	v_cndmask_b32_e32 v26, 0, v26, vcc
	s_cbranch_execz .LBB0_597

; __device__ __forceinline__ unsigned cvt_pk_bf16(float lo, float hi) { unsigned r; asm volatile("v_cvt_pk_bf16_f32 %0, %1, %2" : "=v"(r) : "v"(lo), "v"(hi)); return r; }
; __device__ __forceinline__ float sigmoid_f(float x) { return __builtin_amdgcn_rcpf(1.f + __builtin_amdgcn_exp2f(-1.4426950408889634f * x)); }
;     __device__ __forceinline__ void operator()(const f32x4 (&acc)[2][2][4][2], const Unit& u, int wr, int wc, int fr, int fq) const {
;     ...
;                     const int row = row0 + ai * HALF + m * 16; const float r = __builtin_amdgcn_rsqf(rss[row] * (1.f / 1024.f) + NEPS);
;                     float o[8];
; #pragma unroll
;                     for (int n = 0; n < 2; ++n)
; #pragma unroll
;                         for (int e = 0; e < 4; ++e) o[4 * n + e] = (acc[ai][0][m][n][e] * r) * sigmoid_f(acc[ai][1][m][n][e] * r);
;                     u32x4 w; w.x = cvt_pk_bf16(o[0], o[1]); w.y = cvt_pk_bf16(o[2], o[3]); w.z = cvt_pk_bf16(o[4], o[5]); w.w = cvt_pk_bf16(o[6], o[7]);
;                     *(u32x4*)(U + (size_t)row * 512 + col0) = w;
;                     float* cp = nullptr;
;                     if (!samp) { const int t = row & 4095, b = row >> 12; if (t >= 4066) cp = out + 22806528 + ((size_t)(b * 30 + (t - 4066))) * 512 + col0; }
;                     else { const int sr = row - 16384; cp = out + 199028736 + ((size_t)((sr >> 2) * 30 + 26 + (sr & 3))) * 512 + col0; }
;                     if (cp) { *(f32x4*)cp = (f32x4){o[0], o[1], o[2], o[3]}; *(f32x4*)(cp + 4) = (f32x4){o[4], o[5], o[6], o[7]}; }
.LBB0_585:
	s_or_b64 exec, exec, s[2:3]
	s_nop 0
	v_add_u32_e32 v18, 0xb0, v182
	v_ashrrev_i32_e32 v19, 31, v18
	v_lshlrev_b64 v[22:23], 10, v[18:19]
	v_readlane_b32 s2, v250, 10
	v_readlane_b32 s3, v250, 11
	s_and_b64 vcc, exec, s[10:11]
	s_waitcnt vmcnt(7)
	v_mov_b32_e32 v20, v243
	v_fmamk_f32 v20, v20, 0x3a800000, v212
	v_rsq_f32_e32 v20, v20
	v_lshl_add_u64 v[22:23], s[2:3], 0, v[22:23]
	v_lshl_add_u64 v[22:23], v[130:131], 1, v[22:23]
	s_mov_b64 s[2:3], -1
	v_mul_f32_e32 v21, v7, v20
	v_mul_f32_e32 v19, v6, v20
	v_pk_mul_f32 v[6:7], v[14:15], v[20:21] op_sel_hi:[1,0]
	v_mul_f32_e32 v14, v8, v20
	v_mul_f32_e32 v15, v9, v20
	v_pk_mul_f32 v[8:9], v[16:17], v[20:21] op_sel_hi:[1,0]
	v_mul_f32_e32 v16, v2, v20
	v_mul_f32_e32 v17, v3, v20
	v_pk_mul_f32 v[2:3], v[10:11], v[20:21] op_sel_hi:[1,0]
	v_mul_f32_e32 v10, v4, v20
	v_mul_f32_e32 v11, v5, v20
	v_pk_mul_f32 v[4:5], v[12:13], v[20:21] op_sel_hi:[1,0]
	v_mul_f32_e32 v12, 0xbfb8aa3b, v19
	v_mul_f32_e32 v13, 0xbfb8aa3b, v21
	v_mul_f32_e32 v14, 0xbfb8aa3b, v14
	v_mul_f32_e32 v15, 0xbfb8aa3b, v15
	v_mul_f32_e32 v16, 0xbfb8aa3b, v16
	v_mul_f32_e32 v17, 0xbfb8aa3b, v17
	v_mul_f32_e32 v10, 0xbfb8aa3b, v10
	v_mul_f32_e32 v11, 0xbfb8aa3b, v11
	v_exp_f32_e32 v12, v12
	v_exp_f32_e32 v13, v13
	v_exp_f32_e32 v14, v14
	v_exp_f32_e32 v15, v15
	v_exp_f32_e32 v16, v16
	v_exp_f32_e32 v17, v17
	v_exp_f32_e32 v10, v10
	v_exp_f32_e32 v11, v11
	v_add_f32_e32 v12, 1.0, v12
	v_add_f32_e32 v13, 1.0, v13
	v_add_f32_e32 v14, 1.0, v14
	v_add_f32_e32 v15, 1.0, v15
	v_add_f32_e32 v16, 1.0, v16
	v_add_f32_e32 v17, 1.0, v17
	v_add_f32_e32 v19, 1.0, v10
	v_add_f32_e32 v20, 1.0, v11
	v_rcp_f32_e32 v10, v12
	v_rcp_f32_e32 v11, v13
	v_rcp_f32_e32 v12, v14
	v_rcp_f32_e32 v13, v15
	v_rcp_f32_e32 v14, v16
	v_rcp_f32_e32 v15, v17
	v_rcp_f32_e32 v16, v19
	v_rcp_f32_e32 v17, v20
	v_pk_mul_f32 v[6:7], v[6:7], v[10:11]
	v_pk_mul_f32 v[8:9], v[8:9], v[12:13]
	v_pk_mul_f32 v[2:3], v[2:3], v[14:15]
	v_pk_mul_f32 v[4:5], v[4:5], v[16:17]
	v_cvt_pk_bf16_f32 v10, v6, v7
	v_cvt_pk_bf16_f32 v11, v8, v9
	v_cvt_pk_bf16_f32 v12, v2, v3
	s_nop 0
	v_cvt_pk_bf16_f32 v13, v4, v5
	global_store_dwordx4 v[22:23], v[10:13], off
	s_cbranch_vccnz .LBB0_598
	s_nop 0
	v_and_b32_e32 v12, 0xfff, v18
	v_add_u32_e32 v10, v36, v12
	v_ashrrev_i32_e32 v11, 31, v10
	v_lshlrev_b64 v[10:11], 11, v[10:11]
	v_lshl_add_u64 v[10:11], s[24:25], 0, v[10:11]
	v_lshl_add_u64 v[10:11], v[130:131], 2, v[10:11]
	v_cmp_lt_u32_e32 vcc, s91, v12
	s_nop 1
	v_cndmask_b32_e32 v11, 0, v11, vcc
	v_cndmask_b32_e32 v10, 0, v10, vcc
	s_cbranch_execz .LBB0_599

; __device__ __forceinline__ unsigned cvt_pk_bf16(float lo, float hi) { unsigned r; asm volatile("v_cvt_pk_bf16_f32 %0, %1, %2" : "=v"(r) : "v"(lo), "v"(hi)); return r; }
; __device__ __forceinline__ float silu_f(float x) { return x * sigmoid_f(x); }
;     __device__ __forceinline__ void operator()(const f32x4 (&acc)[2][2][4][2], const Unit& u, int wr, int wc, int fr, int fq) const {
;     ...
;             for (int m = 0; m < 4; ++m) {
;                 const int row = row0 + ai * HALF + m * 16;
;                 const float r = __builtin_amdgcn_rsqf(rss[row] * (1.f / 1024.f) + NEPS);
;                 float o[8];
; #pragma unroll
;                 for (int n = 0; n < 2; ++n)
; #pragma unroll
;                     for (int e = 0; e < 4; ++e) o[4 * n + e] = silu_f(acc[ai][0][m][n][e] * r) * (acc[ai][1][m][n][e] * r);
;                 u32x4 w; w.x = cvt_pk_bf16(o[0], o[1]); w.y = cvt_pk_bf16(o[2], o[3]); w.z = cvt_pk_bf16(o[4], o[5]); w.w = cvt_pk_bf16(o[6], o[7]);
;                 *(u32x4*)(O + (size_t)row * 2816 + col0) = w;
.LBB0_1492:
	v_lshl_add_u32 v140, s62, 8, v1
	v_ashrrev_i32_e32 v141, 31, v140
	v_lshl_add_u64 v[142:143], v[140:141], 2, s[10:11]
	global_load_dword v200, v[142:143], off
	global_load_dword v201, v[142:143], off offset:64
	global_load_dword v202, v[142:143], off offset:128
	global_load_dword v203, v[142:143], off offset:192
	global_load_dword v204, v[142:143], off offset:512
	global_load_dword v205, v[142:143], off offset:576
	global_load_dword v206, v[142:143], off offset:640
	global_load_dword v207, v[142:143], off offset:704
	v_lshl_or_b32 v150, s63, 7, v145
	v_ashrrev_i32_e32 v151, 31, v150
	v_mov_b32_e32 v154, v124
	v_mov_b32_e32 v155, v116
	v_mov_b32_e32 v116, v125
	v_lshlrev_b64 v[124:125], 1, v[150:151]
	v_mov_b32_e32 v152, v126
	v_mov_b32_e32 v153, v118
	v_mov_b32_e32 v118, v127
	v_mov_b32_e32 v126, v128
	v_mov_b32_e32 v127, v120
	v_mov_b32_e32 v120, v129
	v_mov_b32_e32 v128, v122
	v_mov_b32_e32 v129, v114
	v_mov_b32_e32 v114, v123
	v_or_b32_e32 v158, 16, v140
	v_ashrrev_i32_e32 v159, 31, v158
	v_lshl_add_u64 v[160:161], v[158:159], 2, s[10:11]
	v_readlane_b32 s70, v250, 5
	v_readlane_b32 s71, v250, 6
	s_andn2_b64 vcc, exec, s[4:5]
	s_mov_b64 s[4:5], -1
	v_mov_b64_e32 v[122:123], s[70:71]
	v_mad_i64_i32 v[156:157], s[36:37], v140, s61, v[122:123]
	v_lshl_add_u64 v[156:157], v[156:157], 0, v[124:125]
	s_mov_b32 s68, s72
	s_waitcnt vmcnt(0)
	v_mov_b32_e32 v141, v200
	v_fmamk_f32 v141, v141, 0x3a800000, v149
	v_rsq_f32_e32 v150, v141
	s_nop 0
	v_pk_mul_f32 v[116:117], v[116:117], v[150:151] op_sel_hi:[1,0]
	v_pk_mul_f32 v[152:153], v[152:153], v[150:151] op_sel_hi:[1,0]
	v_pk_mul_f32 v[118:119], v[118:119], v[150:151] op_sel_hi:[1,0]
	v_pk_mul_f32 v[126:127], v[126:127], v[150:151] op_sel_hi:[1,0]
	v_pk_mul_f32 v[120:121], v[120:121], v[150:151] op_sel_hi:[1,0]
	v_pk_mul_f32 v[128:129], v[128:129], v[150:151] op_sel_hi:[1,0]
	v_pk_mul_f32 v[114:115], v[114:115], v[150:151] op_sel_hi:[1,0]
	v_pk_mul_f32 v[154:155], v[154:155], v[150:151] op_sel_hi:[1,0]
	v_mul_f32_e32 v165, 0xbfb8aa3b, v117
	v_mul_f32_e32 v141, 0xbfb8aa3b, v153
	v_mul_f32_e32 v150, 0xbfb8aa3b, v119
	v_mul_f32_e32 v151, 0xbfb8aa3b, v127
	v_mul_f32_e32 v159, 0xbfb8aa3b, v121
	v_mul_f32_e32 v162, 0xbfb8aa3b, v129
	v_mul_f32_e32 v163, 0xbfb8aa3b, v115
	v_mul_f32_e32 v164, 0xbfb8aa3b, v155
	v_exp_f32_e32 v165, v165
	v_exp_f32_e32 v141, v141
	v_exp_f32_e32 v150, v150
	v_exp_f32_e32 v151, v151
	v_exp_f32_e32 v159, v159
	v_exp_f32_e32 v162, v162
	v_exp_f32_e32 v163, v163
	v_exp_f32_e32 v164, v164
	v_add_f32_e32 v165, 1.0, v165
	v_add_f32_e32 v141, 1.0, v141
	v_add_f32_e32 v150, 1.0, v150
	v_add_f32_e32 v151, 1.0, v151
	v_add_f32_e32 v159, 1.0, v159
	v_add_f32_e32 v162, 1.0, v162
	v_add_f32_e32 v163, 1.0, v163
	v_add_f32_e32 v164, 1.0, v164
	v_rcp_f32_e32 v165, v165
	v_rcp_f32_e32 v141, v141
	v_rcp_f32_e32 v150, v150
	v_rcp_f32_e32 v151, v151
	v_rcp_f32_e32 v159, v159
	v_rcp_f32_e32 v162, v162
	v_rcp_f32_e32 v163, v163
	v_rcp_f32_e32 v164, v164
	v_mul_f32_e32 v117, v117, v165
	v_mul_f32_e32 v141, v153, v141
	v_mul_f32_e32 v119, v119, v150
	v_mul_f32_e32 v127, v127, v151
	v_mul_f32_e32 v121, v121, v159
	v_mul_f32_e32 v129, v129, v162
	v_mul_f32_e32 v115, v115, v163
	v_mul_f32_e32 v150, v155, v164
	v_mul_f32_e32 v117, v116, v117
	v_mul_f32_e32 v141, v152, v141
	v_mul_f32_e32 v118, v118, v119
	v_mul_f32_e32 v119, v126, v127
	v_mul_f32_e32 v120, v120, v121
	v_mul_f32_e32 v121, v128, v129
	v_mul_f32_e32 v126, v114, v115
	v_mul_f32_e32 v127, v154, v150
	v_cvt_pk_bf16_f32 v114, v141, v118
	v_cvt_pk_bf16_f32 v115, v119, v120
	v_cvt_pk_bf16_f32 v116, v121, v126
	v_cvt_pk_bf16_f32 v117, v127, v117
	global_store_dwordx4 v[156:157], v[114:117], off
	s_nop 0
	s_nop 0
	v_mov_b32_e32 v115, v106
	v_mov_b32_e32 v106, v111
	v_mov_b32_e32 v111, v108
	v_mov_b32_e32 v108, v113
	v_mov_b32_e32 v113, v98
	v_mov_b32_e32 v98, v103
	v_mov_b32_e32 v103, v100
	v_mov_b32_e32 v100, v105
	v_mov_b32_e32 v114, v110
	v_mov_b32_e32 v110, v112
	v_mov_b32_e32 v112, v102
	v_mov_b32_e32 v102, v104
	v_or_b32_e32 v104, 32, v140
	v_mad_i64_i32 v[116:117], s[36:37], v158, s61, v[122:123]
	v_lshl_add_u64 v[116:117], v[116:117], 0, v[124:125]
	s_waitcnt vmcnt(7)
	v_mov_b32_e32 v118, v201
	v_fmamk_f32 v105, v118, 0x3a800000, v149
	v_rsq_f32_e32 v118, v105
	v_ashrrev_i32_e32 v105, 31, v104
	v_lshl_add_u64 v[120:121], v[104:105], 2, s[10:11]
	v_pk_mul_f32 v[100:101], v[100:101], v[118:119] op_sel_hi:[1,0]
	v_pk_mul_f32 v[114:115], v[114:115], v[118:119] op_sel_hi:[1,0]
	v_pk_mul_f32 v[106:107], v[106:107], v[118:119] op_sel_hi:[1,0]
	v_pk_mul_f32 v[110:111], v[110:111], v[118:119] op_sel_hi:[1,0]
	v_pk_mul_f32 v[108:109], v[108:109], v[118:119] op_sel_hi:[1,0]
	v_pk_mul_f32 v[112:113], v[112:113], v[118:119] op_sel_hi:[1,0]
	v_pk_mul_f32 v[98:99], v[98:99], v[118:119] op_sel_hi:[1,0]
	v_pk_mul_f32 v[102:103], v[102:103], v[118:119] op_sel_hi:[1,0]
	v_mul_f32_e32 v141, 0xbfb8aa3b, v101
	v_mul_f32_e32 v105, 0xbfb8aa3b, v115
	v_mul_f32_e32 v118, 0xbfb8aa3b, v107
	v_mul_f32_e32 v119, 0xbfb8aa3b, v111
	v_mul_f32_e32 v126, 0xbfb8aa3b, v109
	v_mul_f32_e32 v127, 0xbfb8aa3b, v113
	v_mul_f32_e32 v128, 0xbfb8aa3b, v99
	v_mul_f32_e32 v129, 0xbfb8aa3b, v103
	v_exp_f32_e32 v141, v141
	v_exp_f32_e32 v105, v105
	v_exp_f32_e32 v118, v118
	v_exp_f32_e32 v119, v119
	v_exp_f32_e32 v126, v126
	v_exp_f32_e32 v127, v127
	v_exp_f32_e32 v128, v128
	v_exp_f32_e32 v129, v129
	v_add_f32_e32 v141, 1.0, v141
	v_add_f32_e32 v105, 1.0, v105
	v_add_f32_e32 v118, 1.0, v118
	v_add_f32_e32 v119, 1.0, v119
	v_add_f32_e32 v126, 1.0, v126
	v_add_f32_e32 v127, 1.0, v127
	v_add_f32_e32 v128, 1.0, v128
	v_add_f32_e32 v129, 1.0, v129
	v_rcp_f32_e32 v141, v141
	v_rcp_f32_e32 v105, v105
	v_rcp_f32_e32 v118, v118
	v_rcp_f32_e32 v119, v119
	v_rcp_f32_e32 v126, v126
	v_rcp_f32_e32 v127, v127
	v_rcp_f32_e32 v128, v128
	v_rcp_f32_e32 v129, v129
	v_mul_f32_e32 v101, v101, v141
	v_mul_f32_e32 v105, v115, v105
	v_mul_f32_e32 v107, v107, v118
	v_mul_f32_e32 v111, v111, v119
	v_mul_f32_e32 v109, v109, v126
	v_mul_f32_e32 v113, v113, v127
	v_mul_f32_e32 v99, v99, v128
	v_mul_f32_e32 v103, v103, v129
	v_mul_f32_e32 v101, v100, v101
	v_mul_f32_e32 v105, v114, v105
	v_mul_f32_e32 v106, v106, v107
	v_mul_f32_e32 v107, v110, v111
	v_mul_f32_e32 v108, v108, v109
	v_mul_f32_e32 v109, v112, v113
	v_mul_f32_e32 v110, v98, v99
	v_mul_f32_e32 v102, v102, v103
	v_cvt_pk_bf16_f32 v98, v105, v106
	v_cvt_pk_bf16_f32 v99, v107, v108
	v_cvt_pk_bf16_f32 v100, v109, v110
	v_cvt_pk_bf16_f32 v101, v102, v101
	global_store_dwordx4 v[116:117], v[98:101], off
	s_nop 0
	s_nop 0
	v_mov_b32_e32 v99, v90
	v_mov_b32_e32 v90, v95
	v_mov_b32_e32 v95, v92
	v_mov_b32_e32 v92, v97
	v_mov_b32_e32 v97, v82
	v_mov_b32_e32 v82, v87
	v_mov_b32_e32 v87, v84
	v_mov_b32_e32 v84, v89
	v_mov_b32_e32 v98, v94
	v_mov_b32_e32 v94, v96
	v_mov_b32_e32 v96, v86
	v_mov_b32_e32 v86, v88
	v_or_b32_e32 v88, 48, v140
	v_mad_i64_i32 v[100:101], s[36:37], v104, s61, v[122:123]
	v_lshl_add_u64 v[100:101], v[100:101], 0, v[124:125]
	s_waitcnt vmcnt(7)
; __device__ __forceinline__ unsigned cvt_pk_bf16(float lo, float hi) { unsigned r; asm volatile("v_cvt_pk_bf16_f32 %0, %1, %2" : "=v"(r) : "v"(lo), "v"(hi)); return r; }
; __device__ __forceinline__ float silu_f(float x) { return x * sigmoid_f(x); }
;     __device__ __forceinline__ void operator()(const f32x4 (&acc)[2][2][4][2], const Unit& u, int wr, int wc, int fr, int fq) const {
;     ...
;             for (int m = 0; m < 4; ++m) {
;                 const int row = row0 + ai * HALF + m * 16;
;                 const float r = __builtin_amdgcn_rsqf(rss[row] * (1.f / 1024.f) + NEPS);
;                 float o[8];
; #pragma unroll
;                 for (int n = 0; n < 2; ++n)
; #pragma unroll
;                     for (int e = 0; e < 4; ++e) o[4 * n + e] = silu_f(acc[ai][0][m][n][e] * r) * (acc[ai][1][m][n][e] * r);
;                 u32x4 w; w.x = cvt_pk_bf16(o[0], o[1]); w.y = cvt_pk_bf16(o[2], o[3]); w.z = cvt_pk_bf16(o[4], o[5]); w.w = cvt_pk_bf16(o[6], o[7]);
;                 *(u32x4*)(O + (size_t)row * 2816 + col0) = w;
	v_mov_b32_e32 v102, v202
	v_fmamk_f32 v89, v102, 0x3a800000, v149
	v_rsq_f32_e32 v102, v89
	v_ashrrev_i32_e32 v89, 31, v88
	v_lshl_add_u64 v[104:105], v[88:89], 2, s[10:11]
	v_pk_mul_f32 v[84:85], v[84:85], v[102:103] op_sel_hi:[1,0]
	v_pk_mul_f32 v[98:99], v[98:99], v[102:103] op_sel_hi:[1,0]
	v_pk_mul_f32 v[90:91], v[90:91], v[102:103] op_sel_hi:[1,0]
	v_pk_mul_f32 v[94:95], v[94:95], v[102:103] op_sel_hi:[1,0]
	v_pk_mul_f32 v[92:93], v[92:93], v[102:103] op_sel_hi:[1,0]
	v_pk_mul_f32 v[96:97], v[96:97], v[102:103] op_sel_hi:[1,0]
	v_pk_mul_f32 v[82:83], v[82:83], v[102:103] op_sel_hi:[1,0]
	v_pk_mul_f32 v[86:87], v[86:87], v[102:103] op_sel_hi:[1,0]
	v_mul_f32_e32 v110, 0xbfb8aa3b, v85
	v_mul_f32_e32 v89, 0xbfb8aa3b, v99
	v_mul_f32_e32 v102, 0xbfb8aa3b, v91
	v_mul_f32_e32 v103, 0xbfb8aa3b, v95
	v_mul_f32_e32 v106, 0xbfb8aa3b, v93
	v_mul_f32_e32 v107, 0xbfb8aa3b, v97
	v_mul_f32_e32 v108, 0xbfb8aa3b, v83
	v_mul_f32_e32 v109, 0xbfb8aa3b, v87
	v_exp_f32_e32 v110, v110
	v_exp_f32_e32 v89, v89
	v_exp_f32_e32 v102, v102
	v_exp_f32_e32 v103, v103
	v_exp_f32_e32 v106, v106
	v_exp_f32_e32 v107, v107
	v_exp_f32_e32 v108, v108
	v_exp_f32_e32 v109, v109
	v_add_f32_e32 v110, 1.0, v110
	v_add_f32_e32 v89, 1.0, v89
	v_add_f32_e32 v102, 1.0, v102
	v_add_f32_e32 v103, 1.0, v103
	v_add_f32_e32 v106, 1.0, v106
	v_add_f32_e32 v107, 1.0, v107
	v_add_f32_e32 v108, 1.0, v108
	v_add_f32_e32 v109, 1.0, v109
	v_rcp_f32_e32 v110, v110
	v_rcp_f32_e32 v89, v89
	v_rcp_f32_e32 v102, v102
	v_rcp_f32_e32 v103, v103
	v_rcp_f32_e32 v106, v106
	v_rcp_f32_e32 v107, v107
	v_rcp_f32_e32 v108, v108
	v_rcp_f32_e32 v109, v109
	v_mul_f32_e32 v85, v85, v110
	v_mul_f32_e32 v89, v99, v89
	v_mul_f32_e32 v91, v91, v102
	v_mul_f32_e32 v95, v95, v103
	v_mul_f32_e32 v93, v93, v106
	v_mul_f32_e32 v97, v97, v107
	v_mul_f32_e32 v83, v83, v108
	v_mul_f32_e32 v87, v87, v109
	v_mul_f32_e32 v85, v84, v85
	v_mul_f32_e32 v89, v98, v89
	v_mul_f32_e32 v90, v90, v91
	v_mul_f32_e32 v91, v94, v95
	v_mul_f32_e32 v92, v92, v93
	v_mul_f32_e32 v93, v96, v97
	v_mul_f32_e32 v94, v82, v83
	v_mul_f32_e32 v86, v86, v87
	v_cvt_pk_bf16_f32 v82, v89, v90
	v_cvt_pk_bf16_f32 v83, v91, v92
	v_cvt_pk_bf16_f32 v84, v93, v94
	v_cvt_pk_bf16_f32 v85, v86, v85
	global_store_dwordx4 v[100:101], v[82:85], off
	s_nop 0
	s_nop 0
	v_mov_b32_e32 v82, v78
	v_mov_b32_e32 v78, v80
	v_mov_b32_e32 v80, v66
	v_mov_b32_e32 v66, v68
	v_mov_b32_e32 v83, v74
	v_mov_b32_e32 v74, v79
	v_mov_b32_e32 v79, v76
	v_mov_b32_e32 v76, v81
	v_mov_b32_e32 v81, v70
	v_mov_b32_e32 v70, v67
	v_mov_b32_e32 v67, v72
	v_mov_b32_e32 v72, v69
	s_waitcnt vmcnt(7)
	v_mov_b32_e32 v84, v203
	v_fmamk_f32 v68, v84, 0x3a800000, v149
	v_rsq_f32_e32 v68, v68
	v_mad_i64_i32 v[84:85], s[36:37], v88, s61, v[122:123]
	v_lshl_add_u64 v[84:85], v[84:85], 0, v[124:125]
	v_pk_mul_f32 v[82:83], v[82:83], v[68:69] op_sel_hi:[1,0]
	v_pk_mul_f32 v[74:75], v[74:75], v[68:69] op_sel_hi:[1,0]
	v_pk_mul_f32 v[78:79], v[78:79], v[68:69] op_sel_hi:[1,0]
	v_pk_mul_f32 v[76:77], v[76:77], v[68:69] op_sel_hi:[1,0]
	v_pk_mul_f32 v[80:81], v[80:81], v[68:69] op_sel_hi:[1,0]
	v_pk_mul_f32 v[70:71], v[70:71], v[68:69] op_sel_hi:[1,0]
	v_pk_mul_f32 v[66:67], v[66:67], v[68:69] op_sel_hi:[1,0]
	v_pk_mul_f32 v[68:69], v[72:73], v[68:69] op_sel_hi:[1,0]
	v_mul_f32_e32 v72, 0xbfb8aa3b, v83
	v_mul_f32_e32 v91, 0xbfb8aa3b, v69
	v_mul_f32_e32 v73, 0xbfb8aa3b, v75
	v_mul_f32_e32 v86, 0xbfb8aa3b, v79
	v_mul_f32_e32 v87, 0xbfb8aa3b, v77
	v_mul_f32_e32 v88, 0xbfb8aa3b, v81
	v_mul_f32_e32 v89, 0xbfb8aa3b, v71
	v_mul_f32_e32 v90, 0xbfb8aa3b, v67
	v_exp_f32_e32 v91, v91
	v_exp_f32_e32 v72, v72
	v_exp_f32_e32 v73, v73
	v_exp_f32_e32 v86, v86
	v_exp_f32_e32 v87, v87
	v_exp_f32_e32 v88, v88
	v_exp_f32_e32 v89, v89
	v_exp_f32_e32 v90, v90
	v_add_f32_e32 v91, 1.0, v91
	v_add_f32_e32 v72, 1.0, v72
	v_add_f32_e32 v73, 1.0, v73
	v_add_f32_e32 v86, 1.0, v86
	v_add_f32_e32 v87, 1.0, v87
	v_add_f32_e32 v88, 1.0, v88
	v_add_f32_e32 v89, 1.0, v89
	v_add_f32_e32 v90, 1.0, v90
	v_rcp_f32_e32 v91, v91
	v_rcp_f32_e32 v72, v72
	v_rcp_f32_e32 v73, v73
	v_rcp_f32_e32 v86, v86
	v_rcp_f32_e32 v87, v87
	v_rcp_f32_e32 v88, v88
	v_rcp_f32_e32 v89, v89
	v_rcp_f32_e32 v90, v90
	v_mul_f32_e32 v69, v69, v91
	v_mul_f32_e32 v72, v83, v72
	v_mul_f32_e32 v73, v75, v73
	v_mul_f32_e32 v75, v79, v86
	v_mul_f32_e32 v77, v77, v87
	v_mul_f32_e32 v79, v81, v88
	v_mul_f32_e32 v71, v71, v89
	v_mul_f32_e32 v67, v67, v90
	v_mul_f32_e32 v69, v68, v69
	v_mul_f32_e32 v72, v82, v72
	v_mul_f32_e32 v73, v74, v73
	v_mul_f32_e32 v74, v78, v75
	v_mul_f32_e32 v75, v76, v77
	v_mul_f32_e32 v76, v80, v79
	v_mul_f32_e32 v70, v70, v71
	v_mul_f32_e32 v71, v66, v67
	v_cvt_pk_bf16_f32 v66, v72, v73
	v_cvt_pk_bf16_f32 v67, v74, v75
	v_cvt_pk_bf16_f32 v68, v76, v70
	v_cvt_pk_bf16_f32 v69, v71, v69
	global_store_dwordx4 v[84:85], v[66:69], off
	s_nop 0
	s_nop 0
	v_mov_b32_e32 v66, v62
	v_mov_b32_e32 v62, v64
	v_mov_b32_e32 v64, v50
	v_mov_b32_e32 v50, v52
	v_mov_b32_e32 v67, v58
	v_mov_b32_e32 v58, v63
	v_mov_b32_e32 v63, v60
	v_mov_b32_e32 v60, v65
	v_mov_b32_e32 v65, v54
	v_mov_b32_e32 v54, v51
	v_mov_b32_e32 v51, v56
	v_mov_b32_e32 v56, v53
	v_add_u32_e32 v53, 0x80, v140
	s_waitcnt vmcnt(7)
; __device__ __forceinline__ unsigned cvt_pk_bf16(float lo, float hi) { unsigned r; asm volatile("v_cvt_pk_bf16_f32 %0, %1, %2" : "=v"(r) : "v"(lo), "v"(hi)); return r; }
; __device__ __forceinline__ float silu_f(float x) { return x * sigmoid_f(x); }
;     __device__ __forceinline__ void operator()(const f32x4 (&acc)[2][2][4][2], const Unit& u, int wr, int wc, int fr, int fq) const {
;     ...
;             for (int m = 0; m < 4; ++m) {
;                 const int row = row0 + ai * HALF + m * 16;
;                 const float r = __builtin_amdgcn_rsqf(rss[row] * (1.f / 1024.f) + NEPS);
;                 float o[8];
; #pragma unroll
;                 for (int n = 0; n < 2; ++n)
; #pragma unroll
;                     for (int e = 0; e < 4; ++e) o[4 * n + e] = silu_f(acc[ai][0][m][n][e] * r) * (acc[ai][1][m][n][e] * r);
;                 u32x4 w; w.x = cvt_pk_bf16(o[0], o[1]); w.y = cvt_pk_bf16(o[2], o[3]); w.z = cvt_pk_bf16(o[4], o[5]); w.w = cvt_pk_bf16(o[6], o[7]);
;                 *(u32x4*)(O + (size_t)row * 2816 + col0) = w;
	v_mov_b32_e32 v68, v204
	v_fmamk_f32 v52, v68, 0x3a800000, v149
	v_rsq_f32_e32 v52, v52
	v_mad_i64_i32 v[68:69], s[36:37], v53, s61, v[122:123]
	v_lshl_add_u64 v[68:69], v[68:69], 0, v[124:125]
	v_pk_mul_f32 v[66:67], v[66:67], v[52:53] op_sel_hi:[1,0]
	v_pk_mul_f32 v[58:59], v[58:59], v[52:53] op_sel_hi:[1,0]
	v_pk_mul_f32 v[62:63], v[62:63], v[52:53] op_sel_hi:[1,0]
	v_pk_mul_f32 v[60:61], v[60:61], v[52:53] op_sel_hi:[1,0]
	v_pk_mul_f32 v[64:65], v[64:65], v[52:53] op_sel_hi:[1,0]
	v_pk_mul_f32 v[54:55], v[54:55], v[52:53] op_sel_hi:[1,0]
	v_pk_mul_f32 v[50:51], v[50:51], v[52:53] op_sel_hi:[1,0]
	v_pk_mul_f32 v[52:53], v[56:57], v[52:53] op_sel_hi:[1,0]
	v_mul_f32_e32 v56, 0xbfb8aa3b, v67
	v_mul_f32_e32 v75, 0xbfb8aa3b, v53
	v_mul_f32_e32 v57, 0xbfb8aa3b, v59
	v_mul_f32_e32 v70, 0xbfb8aa3b, v63
	v_mul_f32_e32 v71, 0xbfb8aa3b, v61
	v_mul_f32_e32 v72, 0xbfb8aa3b, v65
	v_mul_f32_e32 v73, 0xbfb8aa3b, v55
	v_mul_f32_e32 v74, 0xbfb8aa3b, v51
	v_exp_f32_e32 v75, v75
	v_exp_f32_e32 v56, v56
	v_exp_f32_e32 v57, v57
	v_exp_f32_e32 v70, v70
	v_exp_f32_e32 v71, v71
	v_exp_f32_e32 v72, v72
	v_exp_f32_e32 v73, v73
	v_exp_f32_e32 v74, v74
	v_add_f32_e32 v75, 1.0, v75
	v_add_f32_e32 v56, 1.0, v56
	v_add_f32_e32 v57, 1.0, v57
	v_add_f32_e32 v70, 1.0, v70
	v_add_f32_e32 v71, 1.0, v71
	v_add_f32_e32 v72, 1.0, v72
	v_add_f32_e32 v73, 1.0, v73
	v_add_f32_e32 v74, 1.0, v74
	v_rcp_f32_e32 v75, v75
	v_rcp_f32_e32 v56, v56
	v_rcp_f32_e32 v57, v57
	v_rcp_f32_e32 v70, v70
	v_rcp_f32_e32 v71, v71
	v_rcp_f32_e32 v72, v72
	v_rcp_f32_e32 v73, v73
	v_rcp_f32_e32 v74, v74
	v_mul_f32_e32 v53, v53, v75
	v_mul_f32_e32 v56, v67, v56
	v_mul_f32_e32 v57, v59, v57
	v_mul_f32_e32 v59, v63, v70
	v_mul_f32_e32 v61, v61, v71
	v_mul_f32_e32 v63, v65, v72
	v_mul_f32_e32 v55, v55, v73
	v_mul_f32_e32 v51, v51, v74
	v_mul_f32_e32 v53, v52, v53
	v_mul_f32_e32 v56, v66, v56
	v_mul_f32_e32 v57, v58, v57
	v_mul_f32_e32 v58, v62, v59
	v_mul_f32_e32 v59, v60, v61
	v_mul_f32_e32 v60, v64, v63
	v_mul_f32_e32 v54, v54, v55
	v_mul_f32_e32 v55, v50, v51
	v_cvt_pk_bf16_f32 v50, v56, v57
	v_cvt_pk_bf16_f32 v51, v58, v59
	v_cvt_pk_bf16_f32 v52, v60, v54
	v_cvt_pk_bf16_f32 v53, v55, v53
	global_store_dwordx4 v[68:69], v[50:53], off
	s_nop 0
	s_nop 0
	v_mov_b32_e32 v50, v46
	v_mov_b32_e32 v46, v48
	v_mov_b32_e32 v48, v34
	v_mov_b32_e32 v34, v36
	v_mov_b32_e32 v51, v42
	v_mov_b32_e32 v42, v47
	v_mov_b32_e32 v47, v44
	v_mov_b32_e32 v44, v49
	v_mov_b32_e32 v49, v38
	v_mov_b32_e32 v38, v35
	v_mov_b32_e32 v35, v40
	v_mov_b32_e32 v40, v37
	v_add_u32_e32 v37, 0x90, v140
	s_waitcnt vmcnt(7)
	v_mov_b32_e32 v52, v205
	v_fmamk_f32 v36, v52, 0x3a800000, v149
	v_rsq_f32_e32 v36, v36
	v_mad_i64_i32 v[52:53], s[36:37], v37, s61, v[122:123]
	v_lshl_add_u64 v[52:53], v[52:53], 0, v[124:125]
	v_pk_mul_f32 v[50:51], v[50:51], v[36:37] op_sel_hi:[1,0]
	v_pk_mul_f32 v[42:43], v[42:43], v[36:37] op_sel_hi:[1,0]
	v_pk_mul_f32 v[46:47], v[46:47], v[36:37] op_sel_hi:[1,0]
	v_pk_mul_f32 v[44:45], v[44:45], v[36:37] op_sel_hi:[1,0]
	v_pk_mul_f32 v[48:49], v[48:49], v[36:37] op_sel_hi:[1,0]
	v_pk_mul_f32 v[38:39], v[38:39], v[36:37] op_sel_hi:[1,0]
	v_pk_mul_f32 v[34:35], v[34:35], v[36:37] op_sel_hi:[1,0]
	v_pk_mul_f32 v[36:37], v[40:41], v[36:37] op_sel_hi:[1,0]
	v_mul_f32_e32 v40, 0xbfb8aa3b, v51
	v_mul_f32_e32 v59, 0xbfb8aa3b, v37
	v_mul_f32_e32 v41, 0xbfb8aa3b, v43
	v_mul_f32_e32 v54, 0xbfb8aa3b, v47
	v_mul_f32_e32 v55, 0xbfb8aa3b, v45
	v_mul_f32_e32 v56, 0xbfb8aa3b, v49
	v_mul_f32_e32 v57, 0xbfb8aa3b, v39
	v_mul_f32_e32 v58, 0xbfb8aa3b, v35
	v_exp_f32_e32 v59, v59
	v_exp_f32_e32 v40, v40
	v_exp_f32_e32 v41, v41
	v_exp_f32_e32 v54, v54
	v_exp_f32_e32 v55, v55
	v_exp_f32_e32 v56, v56
	v_exp_f32_e32 v57, v57
	v_exp_f32_e32 v58, v58
	v_add_f32_e32 v59, 1.0, v59
	v_add_f32_e32 v40, 1.0, v40
	v_add_f32_e32 v41, 1.0, v41
	v_add_f32_e32 v54, 1.0, v54
	v_add_f32_e32 v55, 1.0, v55
	v_add_f32_e32 v56, 1.0, v56
	v_add_f32_e32 v57, 1.0, v57
	v_add_f32_e32 v58, 1.0, v58
	v_rcp_f32_e32 v59, v59
	v_rcp_f32_e32 v40, v40
	v_rcp_f32_e32 v41, v41
	v_rcp_f32_e32 v54, v54
	v_rcp_f32_e32 v55, v55
	v_rcp_f32_e32 v56, v56
	v_rcp_f32_e32 v57, v57
	v_rcp_f32_e32 v58, v58
	v_mul_f32_e32 v37, v37, v59
	v_mul_f32_e32 v40, v51, v40
	v_mul_f32_e32 v41, v43, v41
	v_mul_f32_e32 v43, v47, v54
	v_mul_f32_e32 v45, v45, v55
	v_mul_f32_e32 v47, v49, v56
	v_mul_f32_e32 v39, v39, v57
	v_mul_f32_e32 v35, v35, v58
	v_mul_f32_e32 v37, v36, v37
	v_mul_f32_e32 v40, v50, v40
	v_mul_f32_e32 v41, v42, v41
	v_mul_f32_e32 v42, v46, v43
	v_mul_f32_e32 v43, v44, v45
	v_mul_f32_e32 v44, v48, v47
	v_mul_f32_e32 v38, v38, v39
	v_mul_f32_e32 v39, v34, v35
	v_cvt_pk_bf16_f32 v34, v40, v41
	v_cvt_pk_bf16_f32 v35, v42, v43
	v_cvt_pk_bf16_f32 v36, v44, v38
	v_cvt_pk_bf16_f32 v37, v39, v37
	global_store_dwordx4 v[52:53], v[34:37], off
	s_nop 0
	s_nop 0
	v_mov_b32_e32 v34, v30
	v_mov_b32_e32 v30, v32
	v_mov_b32_e32 v32, v18
	v_mov_b32_e32 v18, v20
	v_mov_b32_e32 v35, v26
	v_mov_b32_e32 v26, v31
	v_mov_b32_e32 v31, v28
	v_mov_b32_e32 v28, v33
	v_mov_b32_e32 v33, v22
	v_mov_b32_e32 v22, v19
	v_mov_b32_e32 v19, v24
	v_mov_b32_e32 v24, v21
	v_add_u32_e32 v21, 0xa0, v140
	s_waitcnt vmcnt(7)
; __device__ __forceinline__ unsigned cvt_pk_bf16(float lo, float hi) { unsigned r; asm volatile("v_cvt_pk_bf16_f32 %0, %1, %2" : "=v"(r) : "v"(lo), "v"(hi)); return r; }
; __device__ __forceinline__ float silu_f(float x) { return x * sigmoid_f(x); }
; #define PG8_BAR __builtin_amdgcn_s_barrier()
;     __device__ __forceinline__ void operator()(const f32x4 (&acc)[2][2][4][2], const Unit& u, int wr, int wc, int fr, int fq) const {
;     ...
;             for (int m = 0; m < 4; ++m) {
;                 const int row = row0 + ai * HALF + m * 16;
;                 const float r = __builtin_amdgcn_rsqf(rss[row] * (1.f / 1024.f) + NEPS);
;                 float o[8];
; #pragma unroll
;                 for (int n = 0; n < 2; ++n)
; #pragma unroll
;                     for (int e = 0; e < 4; ++e) o[4 * n + e] = silu_f(acc[ai][0][m][n][e] * r) * (acc[ai][1][m][n][e] * r);
;                 u32x4 w; w.x = cvt_pk_bf16(o[0], o[1]); w.y = cvt_pk_bf16(o[2], o[3]); w.z = cvt_pk_bf16(o[4], o[5]); w.w = cvt_pk_bf16(o[6], o[7]);
;                 *(u32x4*)(O + (size_t)row * 2816 + col0) = w;
; template <class Epi, class Sched, bool ALIGN_EPI = false, bool SP2 = false>
; __device__ __forceinline__ void gemm_phase(PG8_LAS unsigned char* lds, const Gemm g, const Sched& S, const Epi& E) {
;     ...
;         if constexpr (ALIGN_EPI) { if (wr == 1) PG8_BAR; }
	v_mov_b32_e32 v36, v206
	v_fmamk_f32 v20, v36, 0x3a800000, v149
	v_rsq_f32_e32 v20, v20
	v_mad_i64_i32 v[36:37], s[36:37], v21, s61, v[122:123]
	v_lshl_add_u64 v[36:37], v[36:37], 0, v[124:125]
	v_pk_mul_f32 v[34:35], v[34:35], v[20:21] op_sel_hi:[1,0]
	v_pk_mul_f32 v[26:27], v[26:27], v[20:21] op_sel_hi:[1,0]
	v_pk_mul_f32 v[30:31], v[30:31], v[20:21] op_sel_hi:[1,0]
	v_pk_mul_f32 v[28:29], v[28:29], v[20:21] op_sel_hi:[1,0]
	v_pk_mul_f32 v[32:33], v[32:33], v[20:21] op_sel_hi:[1,0]
	v_pk_mul_f32 v[22:23], v[22:23], v[20:21] op_sel_hi:[1,0]
	v_pk_mul_f32 v[18:19], v[18:19], v[20:21] op_sel_hi:[1,0]
	v_pk_mul_f32 v[20:21], v[24:25], v[20:21] op_sel_hi:[1,0]
	v_mul_f32_e32 v24, 0xbfb8aa3b, v35
	v_mul_f32_e32 v43, 0xbfb8aa3b, v21
	v_mul_f32_e32 v25, 0xbfb8aa3b, v27
	v_mul_f32_e32 v38, 0xbfb8aa3b, v31
	v_mul_f32_e32 v39, 0xbfb8aa3b, v29
	v_mul_f32_e32 v40, 0xbfb8aa3b, v33
	v_mul_f32_e32 v41, 0xbfb8aa3b, v23
	v_mul_f32_e32 v42, 0xbfb8aa3b, v19
	v_exp_f32_e32 v43, v43
	v_exp_f32_e32 v24, v24
	v_exp_f32_e32 v25, v25
	v_exp_f32_e32 v38, v38
	v_exp_f32_e32 v39, v39
	v_exp_f32_e32 v40, v40
	v_exp_f32_e32 v41, v41
	v_exp_f32_e32 v42, v42
	v_add_f32_e32 v43, 1.0, v43
	v_add_f32_e32 v24, 1.0, v24
	v_add_f32_e32 v25, 1.0, v25
	v_add_f32_e32 v38, 1.0, v38
	v_add_f32_e32 v39, 1.0, v39
	v_add_f32_e32 v40, 1.0, v40
	v_add_f32_e32 v41, 1.0, v41
	v_add_f32_e32 v42, 1.0, v42
	v_rcp_f32_e32 v43, v43
	v_rcp_f32_e32 v24, v24
	v_rcp_f32_e32 v25, v25
	v_rcp_f32_e32 v38, v38
	v_rcp_f32_e32 v39, v39
	v_rcp_f32_e32 v40, v40
	v_rcp_f32_e32 v41, v41
	v_rcp_f32_e32 v42, v42
	v_mul_f32_e32 v21, v21, v43
	v_mul_f32_e32 v24, v35, v24
	v_mul_f32_e32 v25, v27, v25
	v_mul_f32_e32 v27, v31, v38
	v_mul_f32_e32 v29, v29, v39
	v_mul_f32_e32 v31, v33, v40
	v_mul_f32_e32 v23, v23, v41
	v_mul_f32_e32 v19, v19, v42
	v_mul_f32_e32 v21, v20, v21
	v_mul_f32_e32 v24, v34, v24
	v_mul_f32_e32 v25, v26, v25
	v_mul_f32_e32 v26, v30, v27
	v_mul_f32_e32 v27, v28, v29
	v_mul_f32_e32 v28, v32, v31
	v_mul_f32_e32 v22, v22, v23
	v_mul_f32_e32 v23, v18, v19
	v_cvt_pk_bf16_f32 v18, v24, v25
	v_cvt_pk_bf16_f32 v19, v26, v27
	v_cvt_pk_bf16_f32 v20, v28, v22
	v_cvt_pk_bf16_f32 v21, v23, v21
	global_store_dwordx4 v[36:37], v[18:21], off
	s_nop 0
	s_nop 0
	v_mov_b32_e32 v18, v14
	v_mov_b32_e32 v14, v16
	v_mov_b32_e32 v16, v2
	v_mov_b32_e32 v2, v4
	v_mov_b32_e32 v19, v10
	v_mov_b32_e32 v10, v15
	v_mov_b32_e32 v15, v12
	v_mov_b32_e32 v12, v17
	v_mov_b32_e32 v17, v6
	v_mov_b32_e32 v6, v3
	v_mov_b32_e32 v3, v8
	v_mov_b32_e32 v8, v5
	v_add_u32_e32 v5, 0xb0, v140
	s_waitcnt vmcnt(7)
	v_mov_b32_e32 v20, v207
	v_fmamk_f32 v4, v20, 0x3a800000, v149
	v_rsq_f32_e32 v4, v4
	v_mad_i64_i32 v[20:21], s[36:37], v5, s61, v[122:123]
	v_lshl_add_u64 v[20:21], v[20:21], 0, v[124:125]
	v_pk_mul_f32 v[18:19], v[18:19], v[4:5] op_sel_hi:[1,0]
	v_pk_mul_f32 v[10:11], v[10:11], v[4:5] op_sel_hi:[1,0]
	v_pk_mul_f32 v[14:15], v[14:15], v[4:5] op_sel_hi:[1,0]
	v_pk_mul_f32 v[12:13], v[12:13], v[4:5] op_sel_hi:[1,0]
	v_pk_mul_f32 v[16:17], v[16:17], v[4:5] op_sel_hi:[1,0]
	v_pk_mul_f32 v[6:7], v[6:7], v[4:5] op_sel_hi:[1,0]
	v_pk_mul_f32 v[2:3], v[2:3], v[4:5] op_sel_hi:[1,0]
	v_pk_mul_f32 v[4:5], v[8:9], v[4:5] op_sel_hi:[1,0]
	v_mul_f32_e32 v8, 0xbfb8aa3b, v19
	v_mul_f32_e32 v27, 0xbfb8aa3b, v5
	v_mul_f32_e32 v9, 0xbfb8aa3b, v11
	v_mul_f32_e32 v22, 0xbfb8aa3b, v15
	v_mul_f32_e32 v23, 0xbfb8aa3b, v13
	v_mul_f32_e32 v24, 0xbfb8aa3b, v17
	v_mul_f32_e32 v25, 0xbfb8aa3b, v7
	v_mul_f32_e32 v26, 0xbfb8aa3b, v3
	v_exp_f32_e32 v27, v27
	v_exp_f32_e32 v8, v8
	v_exp_f32_e32 v9, v9
	v_exp_f32_e32 v22, v22
	v_exp_f32_e32 v23, v23
	v_exp_f32_e32 v24, v24
	v_exp_f32_e32 v25, v25
	v_exp_f32_e32 v26, v26
	v_add_f32_e32 v27, 1.0, v27
	v_add_f32_e32 v8, 1.0, v8
	v_add_f32_e32 v9, 1.0, v9
	v_add_f32_e32 v22, 1.0, v22
	v_add_f32_e32 v23, 1.0, v23
	v_add_f32_e32 v24, 1.0, v24
	v_add_f32_e32 v25, 1.0, v25
	v_add_f32_e32 v26, 1.0, v26
	v_rcp_f32_e32 v27, v27
	v_rcp_f32_e32 v8, v8
	v_rcp_f32_e32 v9, v9
	v_rcp_f32_e32 v22, v22
	v_rcp_f32_e32 v23, v23
	v_rcp_f32_e32 v24, v24
	v_rcp_f32_e32 v25, v25
	v_rcp_f32_e32 v26, v26
	v_mul_f32_e32 v5, v5, v27
	v_mul_f32_e32 v8, v19, v8
	v_mul_f32_e32 v9, v11, v9
	v_mul_f32_e32 v11, v15, v22
	v_mul_f32_e32 v13, v13, v23
	v_mul_f32_e32 v15, v17, v24
	v_mul_f32_e32 v7, v7, v25
	v_mul_f32_e32 v3, v3, v26
	v_mul_f32_e32 v5, v4, v5
	v_mul_f32_e32 v8, v18, v8
	v_mul_f32_e32 v9, v10, v9
	v_mul_f32_e32 v10, v14, v11
	v_mul_f32_e32 v11, v12, v13
	v_mul_f32_e32 v12, v16, v15
	v_mul_f32_e32 v6, v6, v7
	v_mul_f32_e32 v7, v2, v3
	v_cvt_pk_bf16_f32 v2, v8, v9
	v_cvt_pk_bf16_f32 v3, v10, v11
	v_cvt_pk_bf16_f32 v4, v12, v6
	v_cvt_pk_bf16_f32 v5, v7, v5
	global_store_dwordx4 v[20:21], v[2:5], off
	s_cbranch_vccnz .LBB0_1485
	s_andn2_b64 vcc, exec, s[20:21]
	s_cbranch_vccnz .LBB0_1484
	s_barrier
	s_branch .LBB0_1484
